# GEMM loops: s_setprio 1 hoisted above the pre-MFMA s_barrier, compiler's redundant lgkmcnt(0) after it and the mid-segment setprio 0/1 flip removed (on top of f8f6f4 fp8 GEMM)
# speedup vs baseline: 1.0111x; 1.0111x over previous
; #define PG8_STAGE(bufoff, gbase, voff) do { _Pragma("unroll") for (int _i = 0; _i < 2; ++_i) \
;         __builtin_amdgcn_global_load_lds((const unsigned*)((const char*)(gbase) + (voff)[_i]), (LAS unsigned*)(lds + (bufoff) + ldsw + _i * 8192), 16, 0, 0); } while (0)
; #define PG8_LDA(dst, b, h) do { _Pragma("unroll") for (int m = 0; m < 4; ++m) _Pragma("unroll") for (int k = 0; k < 2; ++k) dst[m][k] = *(const LAS bf16x8*)(lds + PG8_SA(b, h) + aoff + m * 2048 + k * 1024); } while (0)
; #define PG8_LDB(dst, b, h) do { _Pragma("unroll") for (int n = 0; n < 2; ++n) _Pragma("unroll") for (int k = 0; k < 2; ++k) dst[n][k] = *(const LAS bf16x8*)(lds + PG8_SB(b, h) + boff + n * 2048 + k * 1024); } while (0)
; #define PG8_WAIT_V(n) asm volatile("s_waitcnt vmcnt(" #n ")" ::: "memory")
; #define PG8_WAIT_L(n) asm volatile("s_waitcnt lgkmcnt(" #n ")" ::: "memory")
; #define PG8_BAR __builtin_amdgcn_s_barrier()
; #define PG8_SCHED __builtin_amdgcn_sched_barrier(0)
; template <class Epi, bool FP8 = false>
; __device__ __forceinline__ void gemm_phase(LAS unsigned char* lds, const Gemm g, const StaticOrder& S_, const Epi& E, const int tid) {
;     ...
;         for (int t = 0; t < nt; t += 2) {
;             const bool last = (t == nt - 2);
;             const char* a1 = cA + (size_t)(t + 1) * kstep;
;             const char* a2 = last ? nA : cA + (size_t)(t + 2) * kstep; const char* b2 = last ? nB : cB + (size_t)(t + 2) * kstep;
;             const char* a3 = a2 + kstep; const char* b3 = b2 + kstep;
;             PG8_LDB(B0, 0, 0); PG8_LDB(B1, 0, 1); PG8_SCHED; PG8_LDA(At, 0, 0); PG8_STAGE(PG8_SA(1, 1), a1 + hstepA, voffA);
;             PG8_WAIT_V(8); PG8_WAIT_L(0); PG8_BAR; PG8_MMA(0, 0, At, B0); PG8_MMA(0, 1, At, B1); PG8_BAR; PG8_SCHED;
;             PG8_LDA(At, 0, 1); PG8_STAGE(PG8_SB(0, 0), b2, voffB); PG8_STAGE(PG8_SB(0, 1), b2 + hstepB, voffB); PG8_STAGE(PG8_SA(0, 0), a2, voffA);
;             PG8_WAIT_V(8); PG8_WAIT_L(0); PG8_BAR; PG8_MMA(1, 0, At, B0); PG8_MMA(1, 1, At, B1); PG8_BAR; PG8_SCHED;
.LBB0_233:
	ds_read_b128 v[150:153], v147
	ds_read_b128 v[154:157], v147 offset:1024
	ds_read_b128 v[158:161], v147 offset:2048
	ds_read_b128 v[162:165], v147 offset:3072
	ds_read_b128 v[166:169], v148
	ds_read_b128 v[170:173], v148 offset:1024
	ds_read_b128 v[174:177], v148 offset:2048
	ds_read_b128 v[178:181], v148 offset:3072
	s_add_u32 s44, s30, 0xfff80080
	s_addc_u32 s45, s31, -1
	s_cmp_eq_u32 s70, 28
	s_cselect_b32 s47, s17, s45
	s_cselect_b32 s46, s43, s44
	s_cselect_b32 s45, s15, s69
	s_cselect_b32 s44, s66, s68
	v_lshl_add_u64 v[214:215], s[30:31], 0, v[136:137]
	s_add_i32 m0, s29, 0xc000
	ds_read_b128 v[182:185], v149
	ds_read_b128 v[186:189], v149 offset:1024
	ds_read_b128 v[190:193], v149 offset:2048
	ds_read_b128 v[194:197], v149 offset:3072
	ds_read_b128 v[198:201], v149 offset:4096
	ds_read_b128 v[202:205], v149 offset:5120
	ds_read_b128 v[206:209], v149 offset:6144
	ds_read_b128 v[210:213], v149 offset:7168
	global_load_lds_dwordx4 v[214:215], off
	v_lshl_add_u64 v[214:215], s[30:31], 0, v[138:139]
	s_add_i32 m0, s29, 0xe000
	s_nop 0
	global_load_lds_dwordx4 v[214:215], off
	s_waitcnt vmcnt(8)
	s_waitcnt lgkmcnt(0)
	s_setprio 1
	s_barrier
	v_mfma_f32_16x16x32_bf16 v[124:127], v[150:153], v[182:185], v[124:127]
	v_mfma_f32_16x16x32_bf16 v[120:123], v[158:161], v[182:185], v[120:123]
	v_mfma_f32_16x16x32_bf16 v[108:111], v[150:153], v[190:193], v[108:111]
	v_mfma_f32_16x16x32_bf16 v[104:107], v[158:161], v[190:193], v[104:107]
	v_mfma_f32_16x16x32_bf16 v[92:95], v[150:153], v[198:201], v[92:95]
	v_mfma_f32_16x16x32_bf16 v[88:91], v[158:161], v[198:201], v[88:91]
	v_mfma_f32_16x16x32_bf16 v[76:79], v[150:153], v[206:209], v[76:79]
	v_mfma_f32_16x16x32_bf16 v[72:75], v[158:161], v[206:209], v[72:75]
	v_mfma_f32_16x16x32_bf16 v[124:127], v[154:157], v[186:189], v[124:127]
	v_mfma_f32_16x16x32_bf16 v[120:123], v[162:165], v[186:189], v[120:123]
	v_mfma_f32_16x16x32_bf16 v[108:111], v[154:157], v[194:197], v[108:111]
	v_mfma_f32_16x16x32_bf16 v[104:107], v[162:165], v[194:197], v[104:107]
	v_mfma_f32_16x16x32_bf16 v[92:95], v[154:157], v[202:205], v[92:95]
	v_mfma_f32_16x16x32_bf16 v[88:91], v[162:165], v[202:205], v[88:91]
	v_mfma_f32_16x16x32_bf16 v[76:79], v[154:157], v[210:213], v[76:79]
	v_mfma_f32_16x16x32_bf16 v[72:75], v[162:165], v[210:213], v[72:75]
	v_mfma_f32_16x16x32_bf16 v[116:119], v[166:169], v[182:185], v[116:119]
	v_mfma_f32_16x16x32_bf16 v[112:115], v[174:177], v[182:185], v[112:115]
	v_mfma_f32_16x16x32_bf16 v[100:103], v[166:169], v[190:193], v[100:103]
	v_mfma_f32_16x16x32_bf16 v[96:99], v[174:177], v[190:193], v[96:99]
	v_mfma_f32_16x16x32_bf16 v[84:87], v[166:169], v[198:201], v[84:87]
	v_mfma_f32_16x16x32_bf16 v[80:83], v[174:177], v[198:201], v[80:83]
	v_mfma_f32_16x16x32_bf16 v[68:71], v[166:169], v[206:209], v[68:71]
	v_mfma_f32_16x16x32_bf16 v[64:67], v[174:177], v[206:209], v[64:67]
	v_mfma_f32_16x16x32_bf16 v[116:119], v[170:173], v[186:189], v[116:119]
	v_mfma_f32_16x16x32_bf16 v[112:115], v[178:181], v[186:189], v[112:115]
	v_mfma_f32_16x16x32_bf16 v[100:103], v[170:173], v[194:197], v[100:103]
	v_mfma_f32_16x16x32_bf16 v[96:99], v[178:181], v[194:197], v[96:99]
	v_mfma_f32_16x16x32_bf16 v[84:87], v[170:173], v[202:205], v[84:87]
	v_mfma_f32_16x16x32_bf16 v[80:83], v[178:181], v[202:205], v[80:83]
	v_mfma_f32_16x16x32_bf16 v[68:71], v[170:173], v[210:213], v[68:71]
	v_mfma_f32_16x16x32_bf16 v[64:67], v[178:181], v[210:213], v[64:67]
	s_setprio 0
	s_barrier
	s_add_i32 s71, s61, s51
	v_lshl_add_u64 v[214:215], s[44:45], 0, v[128:129]
	s_mov_b32 m0, s71
	ds_read_b128 v[182:185], v149 offset:16384
	ds_read_b128 v[186:189], v149 offset:17408
	ds_read_b128 v[190:193], v149 offset:18432
	ds_read_b128 v[194:197], v149 offset:19456
	ds_read_b128 v[198:201], v149 offset:20480
	ds_read_b128 v[202:205], v149 offset:21504
	ds_read_b128 v[206:209], v149 offset:22528
	ds_read_b128 v[210:213], v149 offset:23552
	global_load_lds_dwordx4 v[214:215], off
	s_add_i32 m0, s71, 0x2000
	s_add_u32 s72, s44, 0x80000
	v_lshl_add_u64 v[216:217], s[44:45], 0, v[130:131]
	s_addc_u32 s73, s45, 0
	s_add_i32 s71, s62, s51
	global_load_lds_dwordx4 v[216:217], off
	v_lshl_add_u64 v[218:219], s[72:73], 0, v[128:129]
	s_mov_b32 m0, s71
	v_lshl_add_u64 v[220:221], s[46:47], 0, v[132:133]
	global_load_lds_dwordx4 v[218:219], off
	v_lshl_add_u64 v[218:219], s[72:73], 0, v[130:131]
	s_add_i32 m0, s71, 0x2000
	s_nop 0
	global_load_lds_dwordx4 v[218:219], off
	v_lshl_add_u64 v[218:219], s[46:47], 0, v[134:135]
	s_mov_b32 m0, s29
	s_nop 0
	global_load_lds_dwordx4 v[218:219], off
	s_mov_b32 m0, s54
	s_nop 0
	global_load_lds_dwordx4 v[220:221], off
	s_waitcnt vmcnt(8)
	s_waitcnt lgkmcnt(0)
	s_setprio 1
	s_barrier
; #define PG8_STAGE(bufoff, gbase, voff) do { _Pragma("unroll") for (int _i = 0; _i < 2; ++_i) \
;         __builtin_amdgcn_global_load_lds((const unsigned*)((const char*)(gbase) + (voff)[_i]), (LAS unsigned*)(lds + (bufoff) + ldsw + _i * 8192), 16, 0, 0); } while (0)
; #define PG8_LDA(dst, b, h) do { _Pragma("unroll") for (int m = 0; m < 4; ++m) _Pragma("unroll") for (int k = 0; k < 2; ++k) dst[m][k] = *(const LAS bf16x8*)(lds + PG8_SA(b, h) + aoff + m * 2048 + k * 1024); } while (0)
; #define PG8_LDB(dst, b, h) do { _Pragma("unroll") for (int n = 0; n < 2; ++n) _Pragma("unroll") for (int k = 0; k < 2; ++k) dst[n][k] = *(const LAS bf16x8*)(lds + PG8_SB(b, h) + boff + n * 2048 + k * 1024); } while (0)
; #define PG8_WAIT_V(n) asm volatile("s_waitcnt vmcnt(" #n ")" ::: "memory")
; #define PG8_WAIT_L(n) asm volatile("s_waitcnt lgkmcnt(" #n ")" ::: "memory")
; #define PG8_BAR __builtin_amdgcn_s_barrier()
; #define PG8_SCHED __builtin_amdgcn_sched_barrier(0)
; template <class Epi, bool FP8 = false>
; __device__ __forceinline__ void gemm_phase(LAS unsigned char* lds, const Gemm g, const StaticOrder& S_, const Epi& E, const int tid) {
;     ...
;             PG8_WAIT_V(8); PG8_WAIT_L(0); PG8_BAR; PG8_MMA(1, 0, At, B0); PG8_MMA(1, 1, At, B1); PG8_BAR; PG8_SCHED;
;             PG8_LDB(B0, 1, 0); PG8_LDB(B1, 1, 1); PG8_SCHED; PG8_LDA(At, 1, 0); PG8_STAGE(PG8_SA(0, 1), a2 + hstepA, voffA);
;             PG8_WAIT_V(8); PG8_WAIT_L(0); PG8_BAR; PG8_MMA(0, 0, At, B0); PG8_MMA(0, 1, At, B1); PG8_BAR; PG8_SCHED;
;             PG8_LDA(At, 1, 1); PG8_STAGE(PG8_SB(1, 0), b3, voffB); PG8_STAGE(PG8_SB(1, 1), b3 + hstepB, voffB); PG8_STAGE(PG8_SA(1, 0), a3, voffA);
;             PG8_WAIT_V(8); PG8_WAIT_L(0); PG8_BAR; PG8_MMA(1, 0, At, B0); PG8_MMA(1, 1, At, B1); PG8_BAR; PG8_SCHED;
	v_mfma_f32_16x16x32_bf16 v[60:63], v[150:153], v[182:185], v[60:63]
	v_mfma_f32_16x16x32_bf16 v[56:59], v[158:161], v[182:185], v[56:59]
	v_mfma_f32_16x16x32_bf16 v[44:47], v[150:153], v[190:193], v[44:47]
	v_mfma_f32_16x16x32_bf16 v[40:43], v[158:161], v[190:193], v[40:43]
	v_mfma_f32_16x16x32_bf16 v[28:31], v[150:153], v[198:201], v[28:31]
	v_mfma_f32_16x16x32_bf16 v[24:27], v[158:161], v[198:201], v[24:27]
	v_mfma_f32_16x16x32_bf16 v[12:15], v[150:153], v[206:209], v[12:15]
	v_mfma_f32_16x16x32_bf16 v[8:11], v[158:161], v[206:209], v[8:11]
	v_mfma_f32_16x16x32_bf16 v[60:63], v[154:157], v[186:189], v[60:63]
	v_mfma_f32_16x16x32_bf16 v[56:59], v[162:165], v[186:189], v[56:59]
	v_mfma_f32_16x16x32_bf16 v[44:47], v[154:157], v[194:197], v[44:47]
	v_mfma_f32_16x16x32_bf16 v[40:43], v[162:165], v[194:197], v[40:43]
	v_mfma_f32_16x16x32_bf16 v[28:31], v[154:157], v[202:205], v[28:31]
	v_mfma_f32_16x16x32_bf16 v[24:27], v[162:165], v[202:205], v[24:27]
	v_mfma_f32_16x16x32_bf16 v[12:15], v[154:157], v[210:213], v[12:15]
	v_mfma_f32_16x16x32_bf16 v[8:11], v[162:165], v[210:213], v[8:11]
	v_mfma_f32_16x16x32_bf16 v[52:55], v[166:169], v[182:185], v[52:55]
	v_mfma_f32_16x16x32_bf16 v[48:51], v[174:177], v[182:185], v[48:51]
	v_mfma_f32_16x16x32_bf16 v[36:39], v[166:169], v[190:193], v[36:39]
	v_mfma_f32_16x16x32_bf16 v[32:35], v[174:177], v[190:193], v[32:35]
	v_mfma_f32_16x16x32_bf16 v[20:23], v[166:169], v[198:201], v[20:23]
	v_mfma_f32_16x16x32_bf16 v[16:19], v[174:177], v[198:201], v[16:19]
	v_mfma_f32_16x16x32_bf16 v[4:7], v[166:169], v[206:209], v[4:7]
	v_mfma_f32_16x16x32_bf16 v[0:3], v[174:177], v[206:209], v[0:3]
	v_mfma_f32_16x16x32_bf16 v[52:55], v[170:173], v[186:189], v[52:55]
	v_mfma_f32_16x16x32_bf16 v[48:51], v[178:181], v[186:189], v[48:51]
	v_mfma_f32_16x16x32_bf16 v[36:39], v[170:173], v[194:197], v[36:39]
	v_mfma_f32_16x16x32_bf16 v[32:35], v[178:181], v[194:197], v[32:35]
	v_mfma_f32_16x16x32_bf16 v[20:23], v[170:173], v[202:205], v[20:23]
	v_mfma_f32_16x16x32_bf16 v[16:19], v[178:181], v[202:205], v[16:19]
	v_mfma_f32_16x16x32_bf16 v[4:7], v[170:173], v[210:213], v[4:7]
	v_mfma_f32_16x16x32_bf16 v[0:3], v[178:181], v[210:213], v[0:3]
	s_setprio 0
	s_barrier
	s_add_i32 s71, 0, 0x18000
	s_add_i32 s72, 0, 0x1c000
	v_add_u32_e32 v162, s71, v145
	v_add_u32_e32 v178, s72, v145
	ds_read_b128 v[150:153], v162
	ds_read_b128 v[154:157], v162 offset:1024
	ds_read_b128 v[158:161], v162 offset:2048
	ds_read_b128 v[162:165], v162 offset:3072
	ds_read_b128 v[166:169], v178
	ds_read_b128 v[170:173], v178 offset:1024
	ds_read_b128 v[174:177], v178 offset:2048
	ds_read_b128 v[178:181], v178 offset:3072
	s_add_u32 s46, s46, 0x80000
	s_addc_u32 s47, s47, 0
	s_mov_b32 m0, s55
	v_lshl_add_u64 v[222:223], s[46:47], 0, v[134:135]
	ds_read_b128 v[182:185], v149 offset:32768
	ds_read_b128 v[186:189], v149 offset:33792
	ds_read_b128 v[190:193], v149 offset:34816
	ds_read_b128 v[194:197], v149 offset:35840
	ds_read_b128 v[198:201], v149 offset:36864
	ds_read_b128 v[202:205], v149 offset:37888
	ds_read_b128 v[206:209], v149 offset:38912
	ds_read_b128 v[210:213], v149 offset:39936
	global_load_lds_dwordx4 v[222:223], off
	v_lshl_add_u64 v[222:223], s[46:47], 0, v[132:133]
	s_mov_b32 m0, s56
	s_nop 0
	global_load_lds_dwordx4 v[222:223], off
	s_waitcnt vmcnt(8)
	s_waitcnt lgkmcnt(0)
	s_setprio 1
	s_barrier
	v_mfma_f32_16x16x32_bf16 v[124:127], v[150:153], v[182:185], v[124:127]
	v_mfma_f32_16x16x32_bf16 v[120:123], v[158:161], v[182:185], v[120:123]
	v_mfma_f32_16x16x32_bf16 v[108:111], v[150:153], v[190:193], v[108:111]
	v_mfma_f32_16x16x32_bf16 v[104:107], v[158:161], v[190:193], v[104:107]
	v_mfma_f32_16x16x32_bf16 v[92:95], v[150:153], v[198:201], v[92:95]
	v_mfma_f32_16x16x32_bf16 v[88:91], v[158:161], v[198:201], v[88:91]
	v_mfma_f32_16x16x32_bf16 v[76:79], v[150:153], v[206:209], v[76:79]
	v_mfma_f32_16x16x32_bf16 v[72:75], v[158:161], v[206:209], v[72:75]
	v_mfma_f32_16x16x32_bf16 v[124:127], v[154:157], v[186:189], v[124:127]
	v_mfma_f32_16x16x32_bf16 v[120:123], v[162:165], v[186:189], v[120:123]
	v_mfma_f32_16x16x32_bf16 v[108:111], v[154:157], v[194:197], v[108:111]
	v_mfma_f32_16x16x32_bf16 v[104:107], v[162:165], v[194:197], v[104:107]
	v_mfma_f32_16x16x32_bf16 v[92:95], v[154:157], v[202:205], v[92:95]
	v_mfma_f32_16x16x32_bf16 v[88:91], v[162:165], v[202:205], v[88:91]
	v_mfma_f32_16x16x32_bf16 v[76:79], v[154:157], v[210:213], v[76:79]
	v_mfma_f32_16x16x32_bf16 v[72:75], v[162:165], v[210:213], v[72:75]
	v_mfma_f32_16x16x32_bf16 v[116:119], v[166:169], v[182:185], v[116:119]
	v_mfma_f32_16x16x32_bf16 v[112:115], v[174:177], v[182:185], v[112:115]
	v_mfma_f32_16x16x32_bf16 v[100:103], v[166:169], v[190:193], v[100:103]
	v_mfma_f32_16x16x32_bf16 v[96:99], v[174:177], v[190:193], v[96:99]
	v_mfma_f32_16x16x32_bf16 v[84:87], v[166:169], v[198:201], v[84:87]
	v_mfma_f32_16x16x32_bf16 v[80:83], v[174:177], v[198:201], v[80:83]
	v_mfma_f32_16x16x32_bf16 v[68:71], v[166:169], v[206:209], v[68:71]
	v_mfma_f32_16x16x32_bf16 v[64:67], v[174:177], v[206:209], v[64:67]
	v_mfma_f32_16x16x32_bf16 v[116:119], v[170:173], v[186:189], v[116:119]
	v_mfma_f32_16x16x32_bf16 v[112:115], v[178:181], v[186:189], v[112:115]
	v_mfma_f32_16x16x32_bf16 v[100:103], v[170:173], v[194:197], v[100:103]
	v_mfma_f32_16x16x32_bf16 v[96:99], v[178:181], v[194:197], v[96:99]
	v_mfma_f32_16x16x32_bf16 v[84:87], v[170:173], v[202:205], v[84:87]
	v_mfma_f32_16x16x32_bf16 v[80:83], v[178:181], v[202:205], v[80:83]
	v_mfma_f32_16x16x32_bf16 v[68:71], v[170:173], v[210:213], v[68:71]
	v_mfma_f32_16x16x32_bf16 v[64:67], v[178:181], v[210:213], v[64:67]
	s_setprio 0
	s_barrier
; #define PG8_STAGE(bufoff, gbase, voff) do { _Pragma("unroll") for (int _i = 0; _i < 2; ++_i) \
;         __builtin_amdgcn_global_load_lds((const unsigned*)((const char*)(gbase) + (voff)[_i]), (LAS unsigned*)(lds + (bufoff) + ldsw + _i * 8192), 16, 0, 0); } while (0)
; #define PG8_LDA(dst, b, h) do { _Pragma("unroll") for (int m = 0; m < 4; ++m) _Pragma("unroll") for (int k = 0; k < 2; ++k) dst[m][k] = *(const LAS bf16x8*)(lds + PG8_SA(b, h) + aoff + m * 2048 + k * 1024); } while (0)
; #define PG8_WAIT_V(n) asm volatile("s_waitcnt vmcnt(" #n ")" ::: "memory")
; #define PG8_WAIT_L(n) asm volatile("s_waitcnt lgkmcnt(" #n ")" ::: "memory")
; #define PG8_BAR __builtin_amdgcn_s_barrier()
; #define PG8_SCHED __builtin_amdgcn_sched_barrier(0)
; template <class Epi, bool FP8 = false>
; __device__ __forceinline__ void gemm_phase(LAS unsigned char* lds, const Gemm g, const StaticOrder& S_, const Epi& E, const int tid) {
;     ...
;             PG8_LDA(At, 1, 1); PG8_STAGE(PG8_SB(1, 0), b3, voffB); PG8_STAGE(PG8_SB(1, 1), b3 + hstepB, voffB); PG8_STAGE(PG8_SA(1, 0), a3, voffA);
;             PG8_WAIT_V(8); PG8_WAIT_L(0); PG8_BAR; PG8_MMA(1, 0, At, B0); PG8_MMA(1, 1, At, B1); PG8_BAR; PG8_SCHED;
;         }
;         if (wr == 0) PG8_BAR;
	s_add_i32 s46, s71, s51
	v_lshl_add_u64 v[214:215], v[214:215], 0, s[10:11]
	s_mov_b32 m0, s46
	ds_read_b128 v[182:185], v149 offset:49152
	ds_read_b128 v[186:189], v149 offset:50176
	ds_read_b128 v[190:193], v149 offset:51200
	ds_read_b128 v[194:197], v149 offset:52224
	ds_read_b128 v[198:201], v149 offset:53248
	ds_read_b128 v[202:205], v149 offset:54272
	ds_read_b128 v[206:209], v149 offset:55296
	ds_read_b128 v[210:213], v149 offset:56320
	global_load_lds_dwordx4 v[214:215], off
	s_add_i32 m0, s46, 0x2000
	s_add_u32 s44, s44, 0x80080
	v_lshl_add_u64 v[214:215], v[216:217], 0, s[10:11]
	s_addc_u32 s45, s45, 0
	s_add_i32 s46, s72, s51
	global_load_lds_dwordx4 v[214:215], off
	v_lshl_add_u64 v[214:215], s[44:45], 0, v[128:129]
	s_mov_b32 m0, s46
	s_nop 0
	global_load_lds_dwordx4 v[214:215], off
	v_lshl_add_u64 v[214:215], s[44:45], 0, v[130:131]
	s_add_i32 m0, s46, 0x2000
	s_nop 0
	global_load_lds_dwordx4 v[214:215], off
	v_lshl_add_u64 v[214:215], v[218:219], 0, s[10:11]
	s_mov_b32 m0, s58
	s_nop 0
	global_load_lds_dwordx4 v[214:215], off
	v_lshl_add_u64 v[214:215], v[220:221], 0, s[10:11]
	s_mov_b32 m0, s59
	s_nop 0
	global_load_lds_dwordx4 v[214:215], off
	s_waitcnt vmcnt(8)
	s_waitcnt lgkmcnt(0)
	s_setprio 1
	s_barrier
	v_mfma_f32_16x16x32_bf16 v[60:63], v[150:153], v[182:185], v[60:63]
	v_mfma_f32_16x16x32_bf16 v[56:59], v[158:161], v[182:185], v[56:59]
	v_mfma_f32_16x16x32_bf16 v[44:47], v[150:153], v[190:193], v[44:47]
	v_mfma_f32_16x16x32_bf16 v[40:43], v[158:161], v[190:193], v[40:43]
	v_mfma_f32_16x16x32_bf16 v[28:31], v[150:153], v[198:201], v[28:31]
	v_mfma_f32_16x16x32_bf16 v[24:27], v[158:161], v[198:201], v[24:27]
	v_mfma_f32_16x16x32_bf16 v[12:15], v[150:153], v[206:209], v[12:15]
	v_mfma_f32_16x16x32_bf16 v[8:11], v[158:161], v[206:209], v[8:11]
	v_mfma_f32_16x16x32_bf16 v[60:63], v[154:157], v[186:189], v[60:63]
	v_mfma_f32_16x16x32_bf16 v[56:59], v[162:165], v[186:189], v[56:59]
	v_mfma_f32_16x16x32_bf16 v[44:47], v[154:157], v[194:197], v[44:47]
	v_mfma_f32_16x16x32_bf16 v[40:43], v[162:165], v[194:197], v[40:43]
	v_mfma_f32_16x16x32_bf16 v[28:31], v[154:157], v[202:205], v[28:31]
	v_mfma_f32_16x16x32_bf16 v[24:27], v[162:165], v[202:205], v[24:27]
	v_mfma_f32_16x16x32_bf16 v[12:15], v[154:157], v[210:213], v[12:15]
	v_mfma_f32_16x16x32_bf16 v[8:11], v[162:165], v[210:213], v[8:11]
	v_mfma_f32_16x16x32_bf16 v[52:55], v[166:169], v[182:185], v[52:55]
	v_mfma_f32_16x16x32_bf16 v[48:51], v[174:177], v[182:185], v[48:51]
	v_mfma_f32_16x16x32_bf16 v[36:39], v[166:169], v[190:193], v[36:39]
	v_mfma_f32_16x16x32_bf16 v[32:35], v[174:177], v[190:193], v[32:35]
	v_mfma_f32_16x16x32_bf16 v[20:23], v[166:169], v[198:201], v[20:23]
	v_mfma_f32_16x16x32_bf16 v[16:19], v[174:177], v[198:201], v[16:19]
	v_mfma_f32_16x16x32_bf16 v[4:7], v[166:169], v[206:209], v[4:7]
	v_mfma_f32_16x16x32_bf16 v[0:3], v[174:177], v[206:209], v[0:3]
	v_mfma_f32_16x16x32_bf16 v[52:55], v[170:173], v[186:189], v[52:55]
	v_mfma_f32_16x16x32_bf16 v[48:51], v[178:181], v[186:189], v[48:51]
	v_mfma_f32_16x16x32_bf16 v[36:39], v[170:173], v[194:197], v[36:39]
	v_mfma_f32_16x16x32_bf16 v[32:35], v[178:181], v[194:197], v[32:35]
	v_mfma_f32_16x16x32_bf16 v[20:23], v[170:173], v[202:205], v[20:23]
	v_mfma_f32_16x16x32_bf16 v[16:19], v[178:181], v[202:205], v[16:19]
	v_mfma_f32_16x16x32_bf16 v[4:7], v[170:173], v[210:213], v[4:7]
	v_mfma_f32_16x16x32_bf16 v[0:3], v[178:181], v[210:213], v[0:3]
	s_setprio 0
	s_barrier
	s_add_i32 s70, s70, 2
	s_add_u32 s30, s30, 0x100
	s_addc_u32 s31, s31, 0
	s_add_u32 s68, s68, 0x100
	s_addc_u32 s69, s69, 0
	s_cmp_gt_u32 s70, 29
	s_cbranch_scc0 .LBB0_233
	s_and_b64 vcc, exec, s[12:13]
	s_cbranch_vccz .LBB0_236
	s_barrier

; #define PG8_STAGE(bufoff, gbase, voff) do { _Pragma("unroll") for (int _i = 0; _i < 2; ++_i) \
;         __builtin_amdgcn_global_load_lds((const unsigned*)((const char*)(gbase) + (voff)[_i]), (LAS unsigned*)(lds + (bufoff) + ldsw + _i * 8192), 16, 0, 0); } while (0)
; #define PG8_LDA(dst, b, h) do { _Pragma("unroll") for (int m = 0; m < 4; ++m) _Pragma("unroll") for (int k = 0; k < 2; ++k) dst[m][k] = *(const LAS bf16x8*)(lds + PG8_SA(b, h) + aoff + m * 2048 + k * 1024); } while (0)
; #define PG8_LDB(dst, b, h) do { _Pragma("unroll") for (int n = 0; n < 2; ++n) _Pragma("unroll") for (int k = 0; k < 2; ++k) dst[n][k] = *(const LAS bf16x8*)(lds + PG8_SB(b, h) + boff + n * 2048 + k * 1024); } while (0)
; #define PG8_WAIT_V(n) asm volatile("s_waitcnt vmcnt(" #n ")" ::: "memory")
; #define PG8_WAIT_L(n) asm volatile("s_waitcnt lgkmcnt(" #n ")" ::: "memory")
; #define PG8_BAR __builtin_amdgcn_s_barrier()
; #define PG8_SCHED __builtin_amdgcn_sched_barrier(0)
; template <class Epi, bool FP8 = false>
; __device__ __forceinline__ void gemm_phase(LAS unsigned char* lds, const Gemm g, const StaticOrder& S_, const Epi& E, const int tid) {
;     ...
;         for (int t = 0; t < nt; t += 2) {
;             const bool last = (t == nt - 2);
;             const char* a1 = cA + (size_t)(t + 1) * kstep;
;             const char* a2 = last ? nA : cA + (size_t)(t + 2) * kstep; const char* b2 = last ? nB : cB + (size_t)(t + 2) * kstep;
;             const char* a3 = a2 + kstep; const char* b3 = b2 + kstep;
;             PG8_LDB(B0, 0, 0); PG8_LDB(B1, 0, 1); PG8_SCHED; PG8_LDA(At, 0, 0); PG8_STAGE(PG8_SA(1, 1), a1 + hstepA, voffA);
;             PG8_WAIT_V(8); PG8_WAIT_L(0); PG8_BAR; PG8_MMA(0, 0, At, B0); PG8_MMA(0, 1, At, B1); PG8_BAR; PG8_SCHED;
;             PG8_LDA(At, 0, 1); PG8_STAGE(PG8_SB(0, 0), b2, voffB); PG8_STAGE(PG8_SB(0, 1), b2 + hstepB, voffB); PG8_STAGE(PG8_SA(0, 0), a2, voffA);
;             PG8_WAIT_V(8); PG8_WAIT_L(0); PG8_BAR; PG8_MMA(1, 0, At, B0); PG8_MMA(1, 1, At, B1); PG8_BAR; PG8_SCHED;
.LBB0_319:
	ds_read_b128 v[150:153], v146
	ds_read_b128 v[154:157], v146 offset:1024
	ds_read_b128 v[158:161], v146 offset:2048
	ds_read_b128 v[162:165], v146 offset:3072
	ds_read_b128 v[166:169], v147
	ds_read_b128 v[170:173], v147 offset:1024
	ds_read_b128 v[174:177], v147 offset:2048
	ds_read_b128 v[178:181], v147 offset:3072
	s_add_u32 s50, s48, 0x100
	s_addc_u32 s51, s49, 0
	s_cmpk_eq_i32 s77, 0x54
	s_cselect_b32 s55, s7, s51
	s_cselect_b32 s54, s6, s50
	s_cselect_b32 s53, s45, s76
	s_cselect_b32 s52, s44, s75
	v_lshl_add_u64 v[140:141], s[48:49], 0, v[132:133]
	s_add_i32 m0, s60, 0xc000
	ds_read_b128 v[182:185], v148
	ds_read_b128 v[186:189], v148 offset:1024
	ds_read_b128 v[190:193], v148 offset:2048
	ds_read_b128 v[194:197], v148 offset:3072
	ds_read_b128 v[198:201], v148 offset:4096
	ds_read_b128 v[202:205], v148 offset:5120
	ds_read_b128 v[206:209], v148 offset:6144
	ds_read_b128 v[210:213], v148 offset:7168
	global_load_lds_dwordx4 v[140:141], off
	v_lshl_add_u64 v[140:141], s[48:49], 0, v[134:135]
	s_add_i32 m0, s60, 0xe000
	s_nop 0
	global_load_lds_dwordx4 v[140:141], off
	s_waitcnt vmcnt(8)
	s_waitcnt lgkmcnt(0)
	s_setprio 1
	s_barrier
	v_mfma_f32_16x16x32_bf16 v[124:127], v[150:153], v[182:185], v[124:127]
	v_mfma_f32_16x16x32_bf16 v[120:123], v[158:161], v[182:185], v[120:123]
	v_mfma_f32_16x16x32_bf16 v[112:115], v[150:153], v[190:193], v[112:115]
	v_mfma_f32_16x16x32_bf16 v[104:107], v[158:161], v[190:193], v[104:107]
	v_mfma_f32_16x16x32_bf16 v[96:99], v[150:153], v[198:201], v[96:99]
	v_mfma_f32_16x16x32_bf16 v[88:91], v[158:161], v[198:201], v[88:91]
	v_mfma_f32_16x16x32_bf16 v[80:83], v[150:153], v[206:209], v[80:83]
	v_mfma_f32_16x16x32_bf16 v[72:75], v[158:161], v[206:209], v[72:75]
	v_mfma_f32_16x16x32_bf16 v[124:127], v[154:157], v[186:189], v[124:127]
	v_mfma_f32_16x16x32_bf16 v[120:123], v[162:165], v[186:189], v[120:123]
	v_mfma_f32_16x16x32_bf16 v[112:115], v[154:157], v[194:197], v[112:115]
	v_mfma_f32_16x16x32_bf16 v[104:107], v[162:165], v[194:197], v[104:107]
	v_mfma_f32_16x16x32_bf16 v[96:99], v[154:157], v[202:205], v[96:99]
	v_mfma_f32_16x16x32_bf16 v[88:91], v[162:165], v[202:205], v[88:91]
	v_mfma_f32_16x16x32_bf16 v[80:83], v[154:157], v[210:213], v[80:83]
	v_mfma_f32_16x16x32_bf16 v[72:75], v[162:165], v[210:213], v[72:75]
	v_mfma_f32_16x16x32_bf16 v[116:119], v[166:169], v[182:185], v[116:119]
	v_mfma_f32_16x16x32_bf16 v[108:111], v[174:177], v[182:185], v[108:111]
	v_mfma_f32_16x16x32_bf16 v[100:103], v[166:169], v[190:193], v[100:103]
	v_mfma_f32_16x16x32_bf16 v[92:95], v[174:177], v[190:193], v[92:95]
	v_mfma_f32_16x16x32_bf16 v[84:87], v[166:169], v[198:201], v[84:87]
	v_mfma_f32_16x16x32_bf16 v[76:79], v[174:177], v[198:201], v[76:79]
	v_mfma_f32_16x16x32_bf16 v[68:71], v[166:169], v[206:209], v[68:71]
	v_mfma_f32_16x16x32_bf16 v[64:67], v[174:177], v[206:209], v[64:67]
	v_mfma_f32_16x16x32_bf16 v[116:119], v[170:173], v[186:189], v[116:119]
	v_mfma_f32_16x16x32_bf16 v[108:111], v[178:181], v[186:189], v[108:111]
	v_mfma_f32_16x16x32_bf16 v[100:103], v[170:173], v[194:197], v[100:103]
	v_mfma_f32_16x16x32_bf16 v[92:95], v[178:181], v[194:197], v[92:95]
	v_mfma_f32_16x16x32_bf16 v[84:87], v[170:173], v[202:205], v[84:87]
	v_mfma_f32_16x16x32_bf16 v[76:79], v[178:181], v[202:205], v[76:79]
	v_mfma_f32_16x16x32_bf16 v[68:71], v[170:173], v[210:213], v[68:71]
	v_mfma_f32_16x16x32_bf16 v[64:67], v[178:181], v[210:213], v[64:67]
	s_setprio 0
	s_barrier
	s_add_i32 s48, s71, s59
	v_lshl_add_u64 v[140:141], s[52:53], 0, v[128:129]
	s_mov_b32 m0, s48
	ds_read_b128 v[182:185], v148 offset:16384
	ds_read_b128 v[186:189], v148 offset:17408
	ds_read_b128 v[190:193], v148 offset:18432
	ds_read_b128 v[194:197], v148 offset:19456
	ds_read_b128 v[198:201], v148 offset:20480
	ds_read_b128 v[202:205], v148 offset:21504
	ds_read_b128 v[206:209], v148 offset:22528
	ds_read_b128 v[210:213], v148 offset:23552
	global_load_lds_dwordx4 v[140:141], off
	s_add_i32 m0, s48, 0x2000
	s_add_u32 s48, s52, 0x160000
	v_lshl_add_u64 v[214:215], s[52:53], 0, v[130:131]
	s_addc_u32 s49, s53, 0
	s_add_i32 s78, s72, s59
	global_load_lds_dwordx4 v[214:215], off
	v_lshl_add_u64 v[216:217], s[48:49], 0, v[128:129]
	s_mov_b32 m0, s78
	v_lshl_add_u64 v[218:219], s[54:55], 0, v[130:131]
	global_load_lds_dwordx4 v[216:217], off
	v_lshl_add_u64 v[216:217], s[48:49], 0, v[130:131]
	s_add_i32 m0, s78, 0x2000
	s_nop 0
	global_load_lds_dwordx4 v[216:217], off
	v_lshl_add_u64 v[216:217], s[54:55], 0, v[128:129]
	s_mov_b32 m0, s60
	s_nop 0
	global_load_lds_dwordx4 v[216:217], off
	s_mov_b32 m0, s61
	s_nop 0
	global_load_lds_dwordx4 v[218:219], off
	s_waitcnt vmcnt(8)
	s_waitcnt lgkmcnt(0)
	s_setprio 1
	s_barrier
; #define PG8_STAGE(bufoff, gbase, voff) do { _Pragma("unroll") for (int _i = 0; _i < 2; ++_i) \
;         __builtin_amdgcn_global_load_lds((const unsigned*)((const char*)(gbase) + (voff)[_i]), (LAS unsigned*)(lds + (bufoff) + ldsw + _i * 8192), 16, 0, 0); } while (0)
; #define PG8_LDA(dst, b, h) do { _Pragma("unroll") for (int m = 0; m < 4; ++m) _Pragma("unroll") for (int k = 0; k < 2; ++k) dst[m][k] = *(const LAS bf16x8*)(lds + PG8_SA(b, h) + aoff + m * 2048 + k * 1024); } while (0)
; #define PG8_LDB(dst, b, h) do { _Pragma("unroll") for (int n = 0; n < 2; ++n) _Pragma("unroll") for (int k = 0; k < 2; ++k) dst[n][k] = *(const LAS bf16x8*)(lds + PG8_SB(b, h) + boff + n * 2048 + k * 1024); } while (0)
; #define PG8_WAIT_V(n) asm volatile("s_waitcnt vmcnt(" #n ")" ::: "memory")
; #define PG8_WAIT_L(n) asm volatile("s_waitcnt lgkmcnt(" #n ")" ::: "memory")
; #define PG8_BAR __builtin_amdgcn_s_barrier()
; #define PG8_SCHED __builtin_amdgcn_sched_barrier(0)
; template <class Epi, bool FP8 = false>
; __device__ __forceinline__ void gemm_phase(LAS unsigned char* lds, const Gemm g, const StaticOrder& S_, const Epi& E, const int tid) {
;     ...
;             PG8_WAIT_V(8); PG8_WAIT_L(0); PG8_BAR; PG8_MMA(1, 0, At, B0); PG8_MMA(1, 1, At, B1); PG8_BAR; PG8_SCHED;
;             PG8_LDB(B0, 1, 0); PG8_LDB(B1, 1, 1); PG8_SCHED; PG8_LDA(At, 1, 0); PG8_STAGE(PG8_SA(0, 1), a2 + hstepA, voffA);
;             PG8_WAIT_V(8); PG8_WAIT_L(0); PG8_BAR; PG8_MMA(0, 0, At, B0); PG8_MMA(0, 1, At, B1); PG8_BAR; PG8_SCHED;
;             PG8_LDA(At, 1, 1); PG8_STAGE(PG8_SB(1, 0), b3, voffB); PG8_STAGE(PG8_SB(1, 1), b3 + hstepB, voffB); PG8_STAGE(PG8_SA(1, 0), a3, voffA);
;             PG8_WAIT_V(8); PG8_WAIT_L(0); PG8_BAR; PG8_MMA(1, 0, At, B0); PG8_MMA(1, 1, At, B1); PG8_BAR; PG8_SCHED;
	v_mfma_f32_16x16x32_bf16 v[60:63], v[150:153], v[182:185], v[60:63]
	v_mfma_f32_16x16x32_bf16 v[56:59], v[158:161], v[182:185], v[56:59]
	v_mfma_f32_16x16x32_bf16 v[48:51], v[150:153], v[190:193], v[48:51]
	v_mfma_f32_16x16x32_bf16 v[40:43], v[158:161], v[190:193], v[40:43]
	v_mfma_f32_16x16x32_bf16 v[32:35], v[150:153], v[198:201], v[32:35]
	v_mfma_f32_16x16x32_bf16 v[24:27], v[158:161], v[198:201], v[24:27]
	v_mfma_f32_16x16x32_bf16 v[16:19], v[150:153], v[206:209], v[16:19]
	v_mfma_f32_16x16x32_bf16 v[8:11], v[158:161], v[206:209], v[8:11]
	v_mfma_f32_16x16x32_bf16 v[60:63], v[154:157], v[186:189], v[60:63]
	v_mfma_f32_16x16x32_bf16 v[56:59], v[162:165], v[186:189], v[56:59]
	v_mfma_f32_16x16x32_bf16 v[48:51], v[154:157], v[194:197], v[48:51]
	v_mfma_f32_16x16x32_bf16 v[40:43], v[162:165], v[194:197], v[40:43]
	v_mfma_f32_16x16x32_bf16 v[32:35], v[154:157], v[202:205], v[32:35]
	v_mfma_f32_16x16x32_bf16 v[24:27], v[162:165], v[202:205], v[24:27]
	v_mfma_f32_16x16x32_bf16 v[16:19], v[154:157], v[210:213], v[16:19]
	v_mfma_f32_16x16x32_bf16 v[8:11], v[162:165], v[210:213], v[8:11]
	v_mfma_f32_16x16x32_bf16 v[52:55], v[166:169], v[182:185], v[52:55]
	v_mfma_f32_16x16x32_bf16 v[44:47], v[174:177], v[182:185], v[44:47]
	v_mfma_f32_16x16x32_bf16 v[36:39], v[166:169], v[190:193], v[36:39]
	v_mfma_f32_16x16x32_bf16 v[28:31], v[174:177], v[190:193], v[28:31]
	v_mfma_f32_16x16x32_bf16 v[20:23], v[166:169], v[198:201], v[20:23]
	v_mfma_f32_16x16x32_bf16 v[12:15], v[174:177], v[198:201], v[12:15]
	v_mfma_f32_16x16x32_bf16 v[4:7], v[166:169], v[206:209], v[4:7]
	v_mfma_f32_16x16x32_bf16 v[0:3], v[174:177], v[206:209], v[0:3]
	v_mfma_f32_16x16x32_bf16 v[52:55], v[170:173], v[186:189], v[52:55]
	v_mfma_f32_16x16x32_bf16 v[44:47], v[178:181], v[186:189], v[44:47]
	v_mfma_f32_16x16x32_bf16 v[36:39], v[170:173], v[194:197], v[36:39]
	v_mfma_f32_16x16x32_bf16 v[28:31], v[178:181], v[194:197], v[28:31]
	v_mfma_f32_16x16x32_bf16 v[20:23], v[170:173], v[202:205], v[20:23]
	v_mfma_f32_16x16x32_bf16 v[12:15], v[178:181], v[202:205], v[12:15]
	v_mfma_f32_16x16x32_bf16 v[4:7], v[170:173], v[210:213], v[4:7]
	v_mfma_f32_16x16x32_bf16 v[0:3], v[178:181], v[210:213], v[0:3]
	s_setprio 0
	s_barrier
	s_add_i32 s78, 0, 0x18000
	v_add_u32_e32 v149, s78, v144
	s_add_i32 s79, 0, 0x1c000
	ds_read_b128 v[150:153], v149
	ds_read_b128 v[154:157], v149 offset:1024
	ds_read_b128 v[158:161], v149 offset:2048
	ds_read_b128 v[162:165], v149 offset:3072
	v_add_u32_e32 v149, s79, v144
	ds_read_b128 v[166:169], v149
	ds_read_b128 v[170:173], v149 offset:1024
	ds_read_b128 v[174:177], v149 offset:2048
	ds_read_b128 v[178:181], v149 offset:3072
	s_add_u32 s48, s54, 0x160000
	s_addc_u32 s49, s55, 0
	s_mov_b32 m0, s62
	v_lshl_add_u64 v[220:221], s[48:49], 0, v[128:129]
	ds_read_b128 v[182:185], v148 offset:32768
	ds_read_b128 v[186:189], v148 offset:33792
	ds_read_b128 v[190:193], v148 offset:34816
	ds_read_b128 v[194:197], v148 offset:35840
	ds_read_b128 v[198:201], v148 offset:36864
	ds_read_b128 v[202:205], v148 offset:37888
	ds_read_b128 v[206:209], v148 offset:38912
	ds_read_b128 v[210:213], v148 offset:39936
	global_load_lds_dwordx4 v[220:221], off
	v_lshl_add_u64 v[220:221], s[48:49], 0, v[130:131]
	s_mov_b32 m0, s63
	s_nop 0
	global_load_lds_dwordx4 v[220:221], off
	s_waitcnt vmcnt(8)
	s_waitcnt lgkmcnt(0)
	s_setprio 1
	s_barrier
	v_mfma_f32_16x16x32_bf16 v[124:127], v[150:153], v[182:185], v[124:127]
	v_mfma_f32_16x16x32_bf16 v[120:123], v[158:161], v[182:185], v[120:123]
	v_mfma_f32_16x16x32_bf16 v[112:115], v[150:153], v[190:193], v[112:115]
	v_mfma_f32_16x16x32_bf16 v[104:107], v[158:161], v[190:193], v[104:107]
	v_mfma_f32_16x16x32_bf16 v[96:99], v[150:153], v[198:201], v[96:99]
	v_mfma_f32_16x16x32_bf16 v[88:91], v[158:161], v[198:201], v[88:91]
	v_mfma_f32_16x16x32_bf16 v[80:83], v[150:153], v[206:209], v[80:83]
	v_mfma_f32_16x16x32_bf16 v[72:75], v[158:161], v[206:209], v[72:75]
	v_mfma_f32_16x16x32_bf16 v[124:127], v[154:157], v[186:189], v[124:127]
	v_mfma_f32_16x16x32_bf16 v[120:123], v[162:165], v[186:189], v[120:123]
	v_mfma_f32_16x16x32_bf16 v[112:115], v[154:157], v[194:197], v[112:115]
	v_mfma_f32_16x16x32_bf16 v[104:107], v[162:165], v[194:197], v[104:107]
	v_mfma_f32_16x16x32_bf16 v[96:99], v[154:157], v[202:205], v[96:99]
	v_mfma_f32_16x16x32_bf16 v[88:91], v[162:165], v[202:205], v[88:91]
	v_mfma_f32_16x16x32_bf16 v[80:83], v[154:157], v[210:213], v[80:83]
	v_mfma_f32_16x16x32_bf16 v[72:75], v[162:165], v[210:213], v[72:75]
	v_mfma_f32_16x16x32_bf16 v[116:119], v[166:169], v[182:185], v[116:119]
	v_mfma_f32_16x16x32_bf16 v[108:111], v[174:177], v[182:185], v[108:111]
	v_mfma_f32_16x16x32_bf16 v[100:103], v[166:169], v[190:193], v[100:103]
	v_mfma_f32_16x16x32_bf16 v[92:95], v[174:177], v[190:193], v[92:95]
	v_mfma_f32_16x16x32_bf16 v[84:87], v[166:169], v[198:201], v[84:87]
	v_mfma_f32_16x16x32_bf16 v[76:79], v[174:177], v[198:201], v[76:79]
	v_mfma_f32_16x16x32_bf16 v[68:71], v[166:169], v[206:209], v[68:71]
	v_mfma_f32_16x16x32_bf16 v[64:67], v[174:177], v[206:209], v[64:67]
	v_mfma_f32_16x16x32_bf16 v[116:119], v[170:173], v[186:189], v[116:119]
	v_mfma_f32_16x16x32_bf16 v[108:111], v[178:181], v[186:189], v[108:111]
	v_mfma_f32_16x16x32_bf16 v[100:103], v[170:173], v[194:197], v[100:103]
	v_mfma_f32_16x16x32_bf16 v[92:95], v[178:181], v[194:197], v[92:95]
	v_mfma_f32_16x16x32_bf16 v[84:87], v[170:173], v[202:205], v[84:87]
	v_mfma_f32_16x16x32_bf16 v[76:79], v[178:181], v[202:205], v[76:79]
	v_mfma_f32_16x16x32_bf16 v[68:71], v[170:173], v[210:213], v[68:71]
	v_mfma_f32_16x16x32_bf16 v[64:67], v[178:181], v[210:213], v[64:67]
	s_setprio 0
	s_barrier
; #define PG8_STAGE(bufoff, gbase, voff) do { _Pragma("unroll") for (int _i = 0; _i < 2; ++_i) \
;         __builtin_amdgcn_global_load_lds((const unsigned*)((const char*)(gbase) + (voff)[_i]), (LAS unsigned*)(lds + (bufoff) + ldsw + _i * 8192), 16, 0, 0); } while (0)
; #define PG8_LDA(dst, b, h) do { _Pragma("unroll") for (int m = 0; m < 4; ++m) _Pragma("unroll") for (int k = 0; k < 2; ++k) dst[m][k] = *(const LAS bf16x8*)(lds + PG8_SA(b, h) + aoff + m * 2048 + k * 1024); } while (0)
; #define PG8_WAIT_V(n) asm volatile("s_waitcnt vmcnt(" #n ")" ::: "memory")
; #define PG8_WAIT_L(n) asm volatile("s_waitcnt lgkmcnt(" #n ")" ::: "memory")
; #define PG8_BAR __builtin_amdgcn_s_barrier()
; #define PG8_SCHED __builtin_amdgcn_sched_barrier(0)
; template <class Epi, bool FP8 = false>
; __device__ __forceinline__ void gemm_phase(LAS unsigned char* lds, const Gemm g, const StaticOrder& S_, const Epi& E, const int tid) {
;     ...
;             PG8_LDA(At, 1, 1); PG8_STAGE(PG8_SB(1, 0), b3, voffB); PG8_STAGE(PG8_SB(1, 1), b3 + hstepB, voffB); PG8_STAGE(PG8_SA(1, 0), a3, voffA);
;             PG8_WAIT_V(8); PG8_WAIT_L(0); PG8_BAR; PG8_MMA(1, 0, At, B0); PG8_MMA(1, 1, At, B1); PG8_BAR; PG8_SCHED;
;         }
;         if (wr == 0) PG8_BAR;
	s_add_i32 s48, s78, s59
	v_lshl_add_u64 v[140:141], v[140:141], 0, s[14:15]
	s_mov_b32 m0, s48
	ds_read_b128 v[182:185], v148 offset:49152
	ds_read_b128 v[186:189], v148 offset:50176
	ds_read_b128 v[190:193], v148 offset:51200
	ds_read_b128 v[194:197], v148 offset:52224
	ds_read_b128 v[198:201], v148 offset:53248
	ds_read_b128 v[202:205], v148 offset:54272
	ds_read_b128 v[206:209], v148 offset:55296
	ds_read_b128 v[210:213], v148 offset:56320
	global_load_lds_dwordx4 v[140:141], off
	s_add_i32 m0, s48, 0x2000
	s_add_u32 s48, s52, 0x160080
	v_lshl_add_u64 v[140:141], v[214:215], 0, s[14:15]
	s_addc_u32 s49, s53, 0
	s_add_i32 s52, s79, s59
	global_load_lds_dwordx4 v[140:141], off
	v_lshl_add_u64 v[140:141], s[48:49], 0, v[128:129]
	s_mov_b32 m0, s52
	s_nop 0
	global_load_lds_dwordx4 v[140:141], off
	v_lshl_add_u64 v[140:141], s[48:49], 0, v[130:131]
	s_add_i32 m0, s52, 0x2000
	s_nop 0
	global_load_lds_dwordx4 v[140:141], off
	v_lshl_add_u64 v[140:141], v[216:217], 0, s[14:15]
	s_mov_b32 m0, s68
	s_nop 0
	global_load_lds_dwordx4 v[140:141], off
	v_lshl_add_u64 v[140:141], v[218:219], 0, s[14:15]
	s_mov_b32 m0, s69
	s_nop 0
	global_load_lds_dwordx4 v[140:141], off
	s_waitcnt vmcnt(8)
	s_waitcnt lgkmcnt(0)
	s_setprio 1
	s_barrier
	v_mfma_f32_16x16x32_bf16 v[60:63], v[150:153], v[182:185], v[60:63]
	v_mfma_f32_16x16x32_bf16 v[56:59], v[158:161], v[182:185], v[56:59]
	v_mfma_f32_16x16x32_bf16 v[48:51], v[150:153], v[190:193], v[48:51]
	v_mfma_f32_16x16x32_bf16 v[40:43], v[158:161], v[190:193], v[40:43]
	v_mfma_f32_16x16x32_bf16 v[32:35], v[150:153], v[198:201], v[32:35]
	v_mfma_f32_16x16x32_bf16 v[24:27], v[158:161], v[198:201], v[24:27]
	v_mfma_f32_16x16x32_bf16 v[16:19], v[150:153], v[206:209], v[16:19]
	v_mfma_f32_16x16x32_bf16 v[8:11], v[158:161], v[206:209], v[8:11]
	v_mfma_f32_16x16x32_bf16 v[60:63], v[154:157], v[186:189], v[60:63]
	v_mfma_f32_16x16x32_bf16 v[56:59], v[162:165], v[186:189], v[56:59]
	v_mfma_f32_16x16x32_bf16 v[48:51], v[154:157], v[194:197], v[48:51]
	v_mfma_f32_16x16x32_bf16 v[40:43], v[162:165], v[194:197], v[40:43]
	v_mfma_f32_16x16x32_bf16 v[32:35], v[154:157], v[202:205], v[32:35]
	v_mfma_f32_16x16x32_bf16 v[24:27], v[162:165], v[202:205], v[24:27]
	v_mfma_f32_16x16x32_bf16 v[16:19], v[154:157], v[210:213], v[16:19]
	v_mfma_f32_16x16x32_bf16 v[8:11], v[162:165], v[210:213], v[8:11]
	v_mfma_f32_16x16x32_bf16 v[52:55], v[166:169], v[182:185], v[52:55]
	v_mfma_f32_16x16x32_bf16 v[44:47], v[174:177], v[182:185], v[44:47]
	v_mfma_f32_16x16x32_bf16 v[36:39], v[166:169], v[190:193], v[36:39]
	v_mfma_f32_16x16x32_bf16 v[28:31], v[174:177], v[190:193], v[28:31]
	v_mfma_f32_16x16x32_bf16 v[20:23], v[166:169], v[198:201], v[20:23]
	v_mfma_f32_16x16x32_bf16 v[12:15], v[174:177], v[198:201], v[12:15]
	v_mfma_f32_16x16x32_bf16 v[4:7], v[166:169], v[206:209], v[4:7]
	v_mfma_f32_16x16x32_bf16 v[0:3], v[174:177], v[206:209], v[0:3]
	v_mfma_f32_16x16x32_bf16 v[52:55], v[170:173], v[186:189], v[52:55]
	v_mfma_f32_16x16x32_bf16 v[44:47], v[178:181], v[186:189], v[44:47]
	v_mfma_f32_16x16x32_bf16 v[36:39], v[170:173], v[194:197], v[36:39]
	v_mfma_f32_16x16x32_bf16 v[28:31], v[178:181], v[194:197], v[28:31]
	v_mfma_f32_16x16x32_bf16 v[20:23], v[170:173], v[202:205], v[20:23]
	v_mfma_f32_16x16x32_bf16 v[12:15], v[178:181], v[202:205], v[12:15]
	v_mfma_f32_16x16x32_bf16 v[4:7], v[170:173], v[210:213], v[4:7]
	v_mfma_f32_16x16x32_bf16 v[0:3], v[178:181], v[210:213], v[0:3]
	s_setprio 0
	s_barrier
	s_add_i32 s77, s77, 2
	s_add_u32 s75, s75, 0x100
	s_addc_u32 s76, s76, 0
	s_cmpk_gt_u32 s77, 0x55
	s_mov_b64 s[48:49], s[50:51]
	s_cbranch_scc0 .LBB0_319
	s_and_b64 vcc, exec, s[16:17]
	s_cbranch_vccz .LBB0_322
	s_barrier

; #define PG8_STAGE(bufoff, gbase, voff) do { _Pragma("unroll") for (int _i = 0; _i < 2; ++_i) \
;         __builtin_amdgcn_global_load_lds((const unsigned*)((const char*)(gbase) + (voff)[_i]), (LAS unsigned*)(lds + (bufoff) + ldsw + _i * 8192), 16, 0, 0); } while (0)
; #define PG8_LDA(dst, b, h) do { _Pragma("unroll") for (int m = 0; m < 4; ++m) _Pragma("unroll") for (int k = 0; k < 2; ++k) dst[m][k] = *(const LAS bf16x8*)(lds + PG8_SA(b, h) + aoff + m * 2048 + k * 1024); } while (0)
; #define PG8_LDB(dst, b, h) do { _Pragma("unroll") for (int n = 0; n < 2; ++n) _Pragma("unroll") for (int k = 0; k < 2; ++k) dst[n][k] = *(const LAS bf16x8*)(lds + PG8_SB(b, h) + boff + n * 2048 + k * 1024); } while (0)
; #define PG8_WAIT_V(n) asm volatile("s_waitcnt vmcnt(" #n ")" ::: "memory")
; #define PG8_WAIT_L(n) asm volatile("s_waitcnt lgkmcnt(" #n ")" ::: "memory")
; #define PG8_BAR __builtin_amdgcn_s_barrier()
; #define PG8_SCHED __builtin_amdgcn_sched_barrier(0)
; template <class Epi, bool FP8 = false>
; __device__ __forceinline__ void gemm_phase(LAS unsigned char* lds, const Gemm g, const StaticOrder& S_, const Epi& E, const int tid) {
;     ...
;         for (int t = 0; t < nt; t += 2) {
;             const bool last = (t == nt - 2);
;             const char* a1 = cA + (size_t)(t + 1) * kstep;
;             const char* a2 = last ? nA : cA + (size_t)(t + 2) * kstep; const char* b2 = last ? nB : cB + (size_t)(t + 2) * kstep;
;             const char* a3 = a2 + kstep; const char* b3 = b2 + kstep;
;             PG8_LDB(B0, 0, 0); PG8_LDB(B1, 0, 1); PG8_SCHED; PG8_LDA(At, 0, 0); PG8_STAGE(PG8_SA(1, 1), a1 + hstepA, voffA);
;             PG8_WAIT_V(8); PG8_WAIT_L(0); PG8_BAR; PG8_MMA(0, 0, At, B0); PG8_MMA(0, 1, At, B1); PG8_BAR; PG8_SCHED;
;             PG8_LDA(At, 0, 1); PG8_STAGE(PG8_SB(0, 0), b2, voffB); PG8_STAGE(PG8_SB(0, 1), b2 + hstepB, voffB); PG8_STAGE(PG8_SA(0, 0), a2, voffA);
;             PG8_WAIT_V(8); PG8_WAIT_L(0); PG8_BAR; PG8_MMA(1, 0, At, B0); PG8_MMA(1, 1, At, B1); PG8_BAR; PG8_SCHED;
.LBB0_457:
	ds_read_b128 v[128:131], v190
	ds_read_b128 v[132:135], v190 offset:1024
	ds_read_b128 v[136:139], v190 offset:2048
	ds_read_b128 v[140:143], v190 offset:3072
	ds_read_b128 v[182:185], v192
	ds_read_b128 v[194:197], v192 offset:1024
	ds_read_b128 v[198:201], v192 offset:2048
	ds_read_b128 v[202:205], v192 offset:3072
	s_add_u32 s56, s54, 0xfff80080
	s_addc_u32 s57, s55, -1
	s_cmp_eq_u32 s61, 28
	s_cselect_b32 s59, s7, s57
	s_cselect_b32 s58, s42, s56
	s_cselect_b32 s57, s27, s60
	s_cselect_b32 s56, s43, s49
	v_lshl_add_u64 v[186:187], s[54:55], 0, v[174:175]
	s_add_i32 m0, s71, 0xc000
	ds_read_b128 v[206:209], v191
	ds_read_b128 v[210:213], v191 offset:1024
	ds_read_b128 v[214:217], v191 offset:2048
	ds_read_b128 v[218:221], v191 offset:3072
	ds_read_b128 v[222:225], v191 offset:4096
	ds_read_b128 v[226:229], v191 offset:5120
	ds_read_b128 v[230:233], v191 offset:6144
	ds_read_b128 v[234:237], v191 offset:7168
	global_load_lds_dwordx4 v[186:187], off
	v_lshl_add_u64 v[186:187], s[54:55], 0, v[176:177]
	s_add_i32 m0, s71, 0xe000
	s_nop 0
	global_load_lds_dwordx4 v[186:187], off
	s_waitcnt vmcnt(8)
	s_waitcnt lgkmcnt(0)
	s_setprio 1
	s_barrier
	v_mfma_f32_16x16x32_bf16 v[124:127], v[128:131], v[206:209], v[124:127]
	v_mfma_f32_16x16x32_bf16 v[120:123], v[136:139], v[206:209], v[120:123]
	v_mfma_f32_16x16x32_bf16 v[108:111], v[128:131], v[214:217], v[108:111]
	v_mfma_f32_16x16x32_bf16 v[104:107], v[136:139], v[214:217], v[104:107]
	v_mfma_f32_16x16x32_bf16 v[92:95], v[128:131], v[222:225], v[92:95]
	v_mfma_f32_16x16x32_bf16 v[88:91], v[136:139], v[222:225], v[88:91]
	v_mfma_f32_16x16x32_bf16 v[76:79], v[128:131], v[230:233], v[76:79]
	v_mfma_f32_16x16x32_bf16 v[72:75], v[136:139], v[230:233], v[72:75]
	v_mfma_f32_16x16x32_bf16 v[124:127], v[132:135], v[210:213], v[124:127]
	v_mfma_f32_16x16x32_bf16 v[120:123], v[140:143], v[210:213], v[120:123]
	v_mfma_f32_16x16x32_bf16 v[108:111], v[132:135], v[218:221], v[108:111]
	v_mfma_f32_16x16x32_bf16 v[104:107], v[140:143], v[218:221], v[104:107]
	v_mfma_f32_16x16x32_bf16 v[92:95], v[132:135], v[226:229], v[92:95]
	v_mfma_f32_16x16x32_bf16 v[88:91], v[140:143], v[226:229], v[88:91]
	v_mfma_f32_16x16x32_bf16 v[76:79], v[132:135], v[234:237], v[76:79]
	v_mfma_f32_16x16x32_bf16 v[72:75], v[140:143], v[234:237], v[72:75]
	v_mfma_f32_16x16x32_bf16 v[116:119], v[182:185], v[206:209], v[116:119]
	v_mfma_f32_16x16x32_bf16 v[112:115], v[198:201], v[206:209], v[112:115]
	v_mfma_f32_16x16x32_bf16 v[100:103], v[182:185], v[214:217], v[100:103]
	v_mfma_f32_16x16x32_bf16 v[96:99], v[198:201], v[214:217], v[96:99]
	v_mfma_f32_16x16x32_bf16 v[84:87], v[182:185], v[222:225], v[84:87]
	v_mfma_f32_16x16x32_bf16 v[80:83], v[198:201], v[222:225], v[80:83]
	v_mfma_f32_16x16x32_bf16 v[68:71], v[182:185], v[230:233], v[68:71]
	v_mfma_f32_16x16x32_bf16 v[64:67], v[198:201], v[230:233], v[64:67]
	v_mfma_f32_16x16x32_bf16 v[116:119], v[194:197], v[210:213], v[116:119]
	v_mfma_f32_16x16x32_bf16 v[112:115], v[202:205], v[210:213], v[112:115]
	v_mfma_f32_16x16x32_bf16 v[100:103], v[194:197], v[218:221], v[100:103]
	v_mfma_f32_16x16x32_bf16 v[96:99], v[202:205], v[218:221], v[96:99]
	v_mfma_f32_16x16x32_bf16 v[84:87], v[194:197], v[226:229], v[84:87]
	v_mfma_f32_16x16x32_bf16 v[80:83], v[202:205], v[226:229], v[80:83]
	v_mfma_f32_16x16x32_bf16 v[68:71], v[194:197], v[234:237], v[68:71]
	v_mfma_f32_16x16x32_bf16 v[64:67], v[202:205], v[234:237], v[64:67]
	s_setprio 0
	s_barrier
	s_add_i32 s62, s85, s70
	v_lshl_add_u64 v[186:187], s[56:57], 0, v[146:147]
	s_mov_b32 m0, s62
	ds_read_b128 v[206:209], v191 offset:16384
	ds_read_b128 v[210:213], v191 offset:17408
	ds_read_b128 v[214:217], v191 offset:18432
	ds_read_b128 v[218:221], v191 offset:19456
	ds_read_b128 v[222:225], v191 offset:20480
	ds_read_b128 v[226:229], v191 offset:21504
	ds_read_b128 v[230:233], v191 offset:22528
	ds_read_b128 v[234:237], v191 offset:23552
	global_load_lds_dwordx4 v[186:187], off
	s_add_i32 m0, s62, 0x2000
	s_add_u32 s62, s56, 0x80000
	v_lshl_add_u64 v[238:239], s[56:57], 0, v[150:151]
	s_addc_u32 s63, s57, 0
	s_add_i32 s66, s86, s70
	global_load_lds_dwordx4 v[238:239], off
	v_lshl_add_u64 v[240:241], s[62:63], 0, v[146:147]
	s_mov_b32 m0, s66
	v_lshl_add_u64 v[242:243], s[58:59], 0, v[148:149]
	global_load_lds_dwordx4 v[240:241], off
	v_lshl_add_u64 v[240:241], s[62:63], 0, v[150:151]
	s_add_i32 m0, s66, 0x2000
	s_nop 0
	global_load_lds_dwordx4 v[240:241], off
	v_lshl_add_u64 v[240:241], s[58:59], 0, v[144:145]
	s_mov_b32 m0, s71
	s_nop 0
	global_load_lds_dwordx4 v[240:241], off
	s_mov_b32 m0, s72
	s_nop 0
	global_load_lds_dwordx4 v[242:243], off
	s_waitcnt vmcnt(8)
	s_waitcnt lgkmcnt(0)
	s_setprio 1
	s_barrier
; #define PG8_STAGE(bufoff, gbase, voff) do { _Pragma("unroll") for (int _i = 0; _i < 2; ++_i) \
;         __builtin_amdgcn_global_load_lds((const unsigned*)((const char*)(gbase) + (voff)[_i]), (LAS unsigned*)(lds + (bufoff) + ldsw + _i * 8192), 16, 0, 0); } while (0)
; #define PG8_LDA(dst, b, h) do { _Pragma("unroll") for (int m = 0; m < 4; ++m) _Pragma("unroll") for (int k = 0; k < 2; ++k) dst[m][k] = *(const LAS bf16x8*)(lds + PG8_SA(b, h) + aoff + m * 2048 + k * 1024); } while (0)
; #define PG8_LDB(dst, b, h) do { _Pragma("unroll") for (int n = 0; n < 2; ++n) _Pragma("unroll") for (int k = 0; k < 2; ++k) dst[n][k] = *(const LAS bf16x8*)(lds + PG8_SB(b, h) + boff + n * 2048 + k * 1024); } while (0)
; #define PG8_WAIT_V(n) asm volatile("s_waitcnt vmcnt(" #n ")" ::: "memory")
; #define PG8_WAIT_L(n) asm volatile("s_waitcnt lgkmcnt(" #n ")" ::: "memory")
; #define PG8_BAR __builtin_amdgcn_s_barrier()
; #define PG8_SCHED __builtin_amdgcn_sched_barrier(0)
; template <class Epi, bool FP8 = false>
; __device__ __forceinline__ void gemm_phase(LAS unsigned char* lds, const Gemm g, const StaticOrder& S_, const Epi& E, const int tid) {
;     ...
;             PG8_WAIT_V(8); PG8_WAIT_L(0); PG8_BAR; PG8_MMA(1, 0, At, B0); PG8_MMA(1, 1, At, B1); PG8_BAR; PG8_SCHED;
;             PG8_LDB(B0, 1, 0); PG8_LDB(B1, 1, 1); PG8_SCHED; PG8_LDA(At, 1, 0); PG8_STAGE(PG8_SA(0, 1), a2 + hstepA, voffA);
;             PG8_WAIT_V(8); PG8_WAIT_L(0); PG8_BAR; PG8_MMA(0, 0, At, B0); PG8_MMA(0, 1, At, B1); PG8_BAR; PG8_SCHED;
;             PG8_LDA(At, 1, 1); PG8_STAGE(PG8_SB(1, 0), b3, voffB); PG8_STAGE(PG8_SB(1, 1), b3 + hstepB, voffB); PG8_STAGE(PG8_SA(1, 0), a3, voffA);
;             PG8_WAIT_V(8); PG8_WAIT_L(0); PG8_BAR; PG8_MMA(1, 0, At, B0); PG8_MMA(1, 1, At, B1); PG8_BAR; PG8_SCHED;
	v_mfma_f32_16x16x32_bf16 v[60:63], v[128:131], v[206:209], v[60:63]
	v_mfma_f32_16x16x32_bf16 v[56:59], v[136:139], v[206:209], v[56:59]
	v_mfma_f32_16x16x32_bf16 v[44:47], v[128:131], v[214:217], v[44:47]
	v_mfma_f32_16x16x32_bf16 v[40:43], v[136:139], v[214:217], v[40:43]
	v_mfma_f32_16x16x32_bf16 v[28:31], v[128:131], v[222:225], v[28:31]
	v_mfma_f32_16x16x32_bf16 v[24:27], v[136:139], v[222:225], v[24:27]
	v_mfma_f32_16x16x32_bf16 v[12:15], v[128:131], v[230:233], v[12:15]
	v_mfma_f32_16x16x32_bf16 v[8:11], v[136:139], v[230:233], v[8:11]
	v_mfma_f32_16x16x32_bf16 v[60:63], v[132:135], v[210:213], v[60:63]
	v_mfma_f32_16x16x32_bf16 v[56:59], v[140:143], v[210:213], v[56:59]
	v_mfma_f32_16x16x32_bf16 v[44:47], v[132:135], v[218:221], v[44:47]
	v_mfma_f32_16x16x32_bf16 v[40:43], v[140:143], v[218:221], v[40:43]
	v_mfma_f32_16x16x32_bf16 v[28:31], v[132:135], v[226:229], v[28:31]
	v_mfma_f32_16x16x32_bf16 v[24:27], v[140:143], v[226:229], v[24:27]
	v_mfma_f32_16x16x32_bf16 v[12:15], v[132:135], v[234:237], v[12:15]
	v_mfma_f32_16x16x32_bf16 v[8:11], v[140:143], v[234:237], v[8:11]
	v_mfma_f32_16x16x32_bf16 v[52:55], v[182:185], v[206:209], v[52:55]
	v_mfma_f32_16x16x32_bf16 v[48:51], v[198:201], v[206:209], v[48:51]
	v_mfma_f32_16x16x32_bf16 v[36:39], v[182:185], v[214:217], v[36:39]
	v_mfma_f32_16x16x32_bf16 v[32:35], v[198:201], v[214:217], v[32:35]
	v_mfma_f32_16x16x32_bf16 v[20:23], v[182:185], v[222:225], v[20:23]
	v_mfma_f32_16x16x32_bf16 v[16:19], v[198:201], v[222:225], v[16:19]
	v_mfma_f32_16x16x32_bf16 v[4:7], v[182:185], v[230:233], v[4:7]
	v_mfma_f32_16x16x32_bf16 v[0:3], v[198:201], v[230:233], v[0:3]
	v_mfma_f32_16x16x32_bf16 v[52:55], v[194:197], v[210:213], v[52:55]
	v_mfma_f32_16x16x32_bf16 v[48:51], v[202:205], v[210:213], v[48:51]
	v_mfma_f32_16x16x32_bf16 v[36:39], v[194:197], v[218:221], v[36:39]
	v_mfma_f32_16x16x32_bf16 v[32:35], v[202:205], v[218:221], v[32:35]
	v_mfma_f32_16x16x32_bf16 v[20:23], v[194:197], v[226:229], v[20:23]
	v_mfma_f32_16x16x32_bf16 v[16:19], v[202:205], v[226:229], v[16:19]
	v_mfma_f32_16x16x32_bf16 v[4:7], v[194:197], v[234:237], v[4:7]
	v_mfma_f32_16x16x32_bf16 v[0:3], v[202:205], v[234:237], v[0:3]
	s_setprio 0
	s_barrier
	s_add_i32 s62, 0, 0x18000
	s_add_i32 s63, 0, 0x1c000
	v_add_u32_e32 v140, s62, v163
	v_add_u32_e32 v152, s63, v163
	ds_read_b128 v[128:131], v140
	ds_read_b128 v[132:135], v140 offset:1024
	ds_read_b128 v[136:139], v140 offset:2048
	ds_read_b128 v[140:143], v140 offset:3072
	ds_read_b128 v[182:185], v152
	ds_read_b128 v[194:197], v152 offset:1024
	ds_read_b128 v[198:201], v152 offset:2048
	ds_read_b128 v[202:205], v152 offset:3072
	s_add_u32 s58, s58, 0x80000
	s_addc_u32 s59, s59, 0
	s_mov_b32 m0, s73
	v_lshl_add_u64 v[244:245], s[58:59], 0, v[144:145]
	ds_read_b128 v[206:209], v191 offset:32768
	ds_read_b128 v[210:213], v191 offset:33792
	ds_read_b128 v[214:217], v191 offset:34816
	ds_read_b128 v[218:221], v191 offset:35840
	ds_read_b128 v[222:225], v191 offset:36864
	ds_read_b128 v[226:229], v191 offset:37888
	ds_read_b128 v[230:233], v191 offset:38912
	ds_read_b128 v[234:237], v191 offset:39936
	global_load_lds_dwordx4 v[244:245], off
	v_lshl_add_u64 v[244:245], s[58:59], 0, v[148:149]
	s_mov_b32 m0, s74
	s_nop 0
	global_load_lds_dwordx4 v[244:245], off
	s_waitcnt vmcnt(8)
	s_waitcnt lgkmcnt(0)
	s_setprio 1
	s_barrier
	v_mfma_f32_16x16x32_bf16 v[124:127], v[128:131], v[206:209], v[124:127]
	v_mfma_f32_16x16x32_bf16 v[120:123], v[136:139], v[206:209], v[120:123]
	v_mfma_f32_16x16x32_bf16 v[108:111], v[128:131], v[214:217], v[108:111]
	v_mfma_f32_16x16x32_bf16 v[104:107], v[136:139], v[214:217], v[104:107]
	v_mfma_f32_16x16x32_bf16 v[92:95], v[128:131], v[222:225], v[92:95]
	v_mfma_f32_16x16x32_bf16 v[88:91], v[136:139], v[222:225], v[88:91]
	v_mfma_f32_16x16x32_bf16 v[76:79], v[128:131], v[230:233], v[76:79]
	v_mfma_f32_16x16x32_bf16 v[72:75], v[136:139], v[230:233], v[72:75]
	v_mfma_f32_16x16x32_bf16 v[124:127], v[132:135], v[210:213], v[124:127]
	v_mfma_f32_16x16x32_bf16 v[120:123], v[140:143], v[210:213], v[120:123]
	v_mfma_f32_16x16x32_bf16 v[108:111], v[132:135], v[218:221], v[108:111]
	v_mfma_f32_16x16x32_bf16 v[104:107], v[140:143], v[218:221], v[104:107]
	v_mfma_f32_16x16x32_bf16 v[92:95], v[132:135], v[226:229], v[92:95]
	v_mfma_f32_16x16x32_bf16 v[88:91], v[140:143], v[226:229], v[88:91]
	v_mfma_f32_16x16x32_bf16 v[76:79], v[132:135], v[234:237], v[76:79]
	v_mfma_f32_16x16x32_bf16 v[72:75], v[140:143], v[234:237], v[72:75]
	v_mfma_f32_16x16x32_bf16 v[116:119], v[182:185], v[206:209], v[116:119]
	v_mfma_f32_16x16x32_bf16 v[112:115], v[198:201], v[206:209], v[112:115]
	v_mfma_f32_16x16x32_bf16 v[100:103], v[182:185], v[214:217], v[100:103]
	v_mfma_f32_16x16x32_bf16 v[96:99], v[198:201], v[214:217], v[96:99]
	v_mfma_f32_16x16x32_bf16 v[84:87], v[182:185], v[222:225], v[84:87]
	v_mfma_f32_16x16x32_bf16 v[80:83], v[198:201], v[222:225], v[80:83]
	v_mfma_f32_16x16x32_bf16 v[68:71], v[182:185], v[230:233], v[68:71]
	v_mfma_f32_16x16x32_bf16 v[64:67], v[198:201], v[230:233], v[64:67]
	v_mfma_f32_16x16x32_bf16 v[116:119], v[194:197], v[210:213], v[116:119]
	v_mfma_f32_16x16x32_bf16 v[112:115], v[202:205], v[210:213], v[112:115]
	v_mfma_f32_16x16x32_bf16 v[100:103], v[194:197], v[218:221], v[100:103]
	v_mfma_f32_16x16x32_bf16 v[96:99], v[202:205], v[218:221], v[96:99]
	v_mfma_f32_16x16x32_bf16 v[84:87], v[194:197], v[226:229], v[84:87]
	v_mfma_f32_16x16x32_bf16 v[80:83], v[202:205], v[226:229], v[80:83]
	v_mfma_f32_16x16x32_bf16 v[68:71], v[194:197], v[234:237], v[68:71]
	v_mfma_f32_16x16x32_bf16 v[64:67], v[202:205], v[234:237], v[64:67]
	s_setprio 0
	s_barrier
; #define PG8_STAGE(bufoff, gbase, voff) do { _Pragma("unroll") for (int _i = 0; _i < 2; ++_i) \
;         __builtin_amdgcn_global_load_lds((const unsigned*)((const char*)(gbase) + (voff)[_i]), (LAS unsigned*)(lds + (bufoff) + ldsw + _i * 8192), 16, 0, 0); } while (0)
; #define PG8_LDA(dst, b, h) do { _Pragma("unroll") for (int m = 0; m < 4; ++m) _Pragma("unroll") for (int k = 0; k < 2; ++k) dst[m][k] = *(const LAS bf16x8*)(lds + PG8_SA(b, h) + aoff + m * 2048 + k * 1024); } while (0)
; #define PG8_WAIT_V(n) asm volatile("s_waitcnt vmcnt(" #n ")" ::: "memory")
; #define PG8_WAIT_L(n) asm volatile("s_waitcnt lgkmcnt(" #n ")" ::: "memory")
; #define PG8_BAR __builtin_amdgcn_s_barrier()
; #define PG8_SCHED __builtin_amdgcn_sched_barrier(0)
; template <class Epi, bool FP8 = false>
; __device__ __forceinline__ void gemm_phase(LAS unsigned char* lds, const Gemm g, const StaticOrder& S_, const Epi& E, const int tid) {
;     ...
;             PG8_LDA(At, 1, 1); PG8_STAGE(PG8_SB(1, 0), b3, voffB); PG8_STAGE(PG8_SB(1, 1), b3 + hstepB, voffB); PG8_STAGE(PG8_SA(1, 0), a3, voffA);
;             PG8_WAIT_V(8); PG8_WAIT_L(0); PG8_BAR; PG8_MMA(1, 0, At, B0); PG8_MMA(1, 1, At, B1); PG8_BAR; PG8_SCHED;
;         }
;         if (wr == 0) PG8_BAR;
	s_add_i32 s58, s62, s70
	v_lshl_add_u64 v[186:187], v[186:187], 0, s[14:15]
	s_mov_b32 m0, s58
	ds_read_b128 v[206:209], v191 offset:49152
	ds_read_b128 v[210:213], v191 offset:50176
	ds_read_b128 v[214:217], v191 offset:51200
	ds_read_b128 v[218:221], v191 offset:52224
	ds_read_b128 v[222:225], v191 offset:53248
	ds_read_b128 v[226:229], v191 offset:54272
	ds_read_b128 v[230:233], v191 offset:55296
	ds_read_b128 v[234:237], v191 offset:56320
	global_load_lds_dwordx4 v[186:187], off
	s_add_i32 m0, s58, 0x2000
	s_add_u32 s56, s56, 0x80080
	v_lshl_add_u64 v[186:187], v[238:239], 0, s[14:15]
	s_addc_u32 s57, s57, 0
	s_add_i32 s58, s63, s70
	global_load_lds_dwordx4 v[186:187], off
	v_lshl_add_u64 v[186:187], s[56:57], 0, v[146:147]
	s_mov_b32 m0, s58
	s_nop 0
	global_load_lds_dwordx4 v[186:187], off
	v_lshl_add_u64 v[186:187], s[56:57], 0, v[150:151]
	s_add_i32 m0, s58, 0x2000
	s_nop 0
	global_load_lds_dwordx4 v[186:187], off
	v_lshl_add_u64 v[186:187], v[240:241], 0, s[14:15]
	s_mov_b32 m0, s79
	s_nop 0
	global_load_lds_dwordx4 v[186:187], off
	v_lshl_add_u64 v[186:187], v[242:243], 0, s[14:15]
	s_mov_b32 m0, s80
	s_nop 0
	global_load_lds_dwordx4 v[186:187], off
	s_waitcnt vmcnt(8)
	s_waitcnt lgkmcnt(0)
	s_setprio 1
	s_barrier
	v_mfma_f32_16x16x32_bf16 v[60:63], v[128:131], v[206:209], v[60:63]
	v_mfma_f32_16x16x32_bf16 v[56:59], v[136:139], v[206:209], v[56:59]
	v_mfma_f32_16x16x32_bf16 v[44:47], v[128:131], v[214:217], v[44:47]
	v_mfma_f32_16x16x32_bf16 v[40:43], v[136:139], v[214:217], v[40:43]
	v_mfma_f32_16x16x32_bf16 v[28:31], v[128:131], v[222:225], v[28:31]
	v_mfma_f32_16x16x32_bf16 v[24:27], v[136:139], v[222:225], v[24:27]
	v_mfma_f32_16x16x32_bf16 v[12:15], v[128:131], v[230:233], v[12:15]
	v_mfma_f32_16x16x32_bf16 v[8:11], v[136:139], v[230:233], v[8:11]
	v_mfma_f32_16x16x32_bf16 v[60:63], v[132:135], v[210:213], v[60:63]
	v_mfma_f32_16x16x32_bf16 v[56:59], v[140:143], v[210:213], v[56:59]
	v_mfma_f32_16x16x32_bf16 v[44:47], v[132:135], v[218:221], v[44:47]
	v_mfma_f32_16x16x32_bf16 v[40:43], v[140:143], v[218:221], v[40:43]
	v_mfma_f32_16x16x32_bf16 v[28:31], v[132:135], v[226:229], v[28:31]
	v_mfma_f32_16x16x32_bf16 v[24:27], v[140:143], v[226:229], v[24:27]
	v_mfma_f32_16x16x32_bf16 v[12:15], v[132:135], v[234:237], v[12:15]
	v_mfma_f32_16x16x32_bf16 v[8:11], v[140:143], v[234:237], v[8:11]
	v_mfma_f32_16x16x32_bf16 v[52:55], v[182:185], v[206:209], v[52:55]
	v_mfma_f32_16x16x32_bf16 v[48:51], v[198:201], v[206:209], v[48:51]
	v_mfma_f32_16x16x32_bf16 v[36:39], v[182:185], v[214:217], v[36:39]
	v_mfma_f32_16x16x32_bf16 v[32:35], v[198:201], v[214:217], v[32:35]
	v_mfma_f32_16x16x32_bf16 v[20:23], v[182:185], v[222:225], v[20:23]
	v_mfma_f32_16x16x32_bf16 v[16:19], v[198:201], v[222:225], v[16:19]
	v_mfma_f32_16x16x32_bf16 v[4:7], v[182:185], v[230:233], v[4:7]
	v_mfma_f32_16x16x32_bf16 v[0:3], v[198:201], v[230:233], v[0:3]
	v_mfma_f32_16x16x32_bf16 v[52:55], v[194:197], v[210:213], v[52:55]
	v_mfma_f32_16x16x32_bf16 v[48:51], v[202:205], v[210:213], v[48:51]
	v_mfma_f32_16x16x32_bf16 v[36:39], v[194:197], v[218:221], v[36:39]
	v_mfma_f32_16x16x32_bf16 v[32:35], v[202:205], v[218:221], v[32:35]
	v_mfma_f32_16x16x32_bf16 v[20:23], v[194:197], v[226:229], v[20:23]
	v_mfma_f32_16x16x32_bf16 v[16:19], v[202:205], v[226:229], v[16:19]
	v_mfma_f32_16x16x32_bf16 v[4:7], v[194:197], v[234:237], v[4:7]
	v_mfma_f32_16x16x32_bf16 v[0:3], v[202:205], v[234:237], v[0:3]
	s_setprio 0
	s_barrier
	s_add_i32 s61, s61, 2
	s_add_u32 s54, s54, 0x100
	s_addc_u32 s55, s55, 0
	s_add_u32 s49, s49, 0x100
	s_addc_u32 s60, s60, 0
	s_cmp_gt_u32 s61, 29
	s_cbranch_scc0 .LBB0_457
	s_and_b64 vcc, exec, s[16:17]
	s_cbranch_vccz .LBB0_460
	s_barrier

; #define PG8_STAGE(bufoff, gbase, voff) do { _Pragma("unroll") for (int _i = 0; _i < 2; ++_i) \
;         __builtin_amdgcn_global_load_lds((const unsigned*)((const char*)(gbase) + (voff)[_i]), (LAS unsigned*)(lds + (bufoff) + ldsw + _i * 8192), 16, 0, 0); } while (0)
; #define PG8_LDA(dst, b, h) do { _Pragma("unroll") for (int m = 0; m < 4; ++m) _Pragma("unroll") for (int k = 0; k < 2; ++k) dst[m][k] = *(const LAS bf16x8*)(lds + PG8_SA(b, h) + aoff + m * 2048 + k * 1024); } while (0)
; #define PG8_LDB(dst, b, h) do { _Pragma("unroll") for (int n = 0; n < 2; ++n) _Pragma("unroll") for (int k = 0; k < 2; ++k) dst[n][k] = *(const LAS bf16x8*)(lds + PG8_SB(b, h) + boff + n * 2048 + k * 1024); } while (0)
; #define PG8_WAIT_V(n) asm volatile("s_waitcnt vmcnt(" #n ")" ::: "memory")
; #define PG8_WAIT_L(n) asm volatile("s_waitcnt lgkmcnt(" #n ")" ::: "memory")
; #define PG8_BAR __builtin_amdgcn_s_barrier()
; #define PG8_SCHED __builtin_amdgcn_sched_barrier(0)
; template <class Epi, bool FP8 = false>
; __device__ __forceinline__ void gemm_phase(LAS unsigned char* lds, const Gemm g, const StaticOrder& S_, const Epi& E, const int tid) {
;     ...
;         for (int t = 0; t < nt; t += 2) {
;             const bool last = (t == nt - 2);
;             const char* a1 = cA + (size_t)(t + 1) * kstep;
;             const char* a2 = last ? nA : cA + (size_t)(t + 2) * kstep; const char* b2 = last ? nB : cB + (size_t)(t + 2) * kstep;
;             const char* a3 = a2 + kstep; const char* b3 = b2 + kstep;
;             PG8_LDB(B0, 0, 0); PG8_LDB(B1, 0, 1); PG8_SCHED; PG8_LDA(At, 0, 0); PG8_STAGE(PG8_SA(1, 1), a1 + hstepA, voffA);
;             PG8_WAIT_V(8); PG8_WAIT_L(0); PG8_BAR; PG8_MMA(0, 0, At, B0); PG8_MMA(0, 1, At, B1); PG8_BAR; PG8_SCHED;
;             PG8_LDA(At, 0, 1); PG8_STAGE(PG8_SB(0, 0), b2, voffB); PG8_STAGE(PG8_SB(0, 1), b2 + hstepB, voffB); PG8_STAGE(PG8_SA(0, 0), a2, voffA);
;             PG8_WAIT_V(8); PG8_WAIT_L(0); PG8_BAR; PG8_MMA(1, 0, At, B0); PG8_MMA(1, 1, At, B1); PG8_BAR; PG8_SCHED;
;             PG8_LDB(B0, 1, 0); PG8_LDB(B1, 1, 1); PG8_SCHED; PG8_LDA(At, 1, 0); PG8_STAGE(PG8_SA(0, 1), a2 + hstepA, voffA);
;             PG8_WAIT_V(8); PG8_WAIT_L(0); PG8_BAR; PG8_MMA(0, 0, At, B0); PG8_MMA(0, 1, At, B1); PG8_BAR; PG8_SCHED;
.LBB0_596:
	ds_read_b128 v[156:159], v197 offset:1024
	ds_read_b128 v[152:155], v197
	ds_read_b128 v[148:151], v197 offset:3072
	ds_read_b128 v[144:147], v197 offset:2048
	ds_read_b128 v[140:143], v198 offset:1024
	ds_read_b128 v[136:139], v198
	ds_read_b128 v[132:135], v198 offset:3072
	ds_read_b128 v[128:131], v198 offset:2048
	s_add_u32 s54, s52, 0xfffc0080
	s_addc_u32 s55, s53, -1
	s_cmp_eq_u32 s85, 12
	s_cselect_b32 s57, s27, s55
	s_cselect_b32 s56, s42, s54
	s_cselect_b32 s55, s25, s84
	s_cselect_b32 s54, s43, s66
	v_lshl_add_u64 v[224:225], s[52:53], 0, v[178:179]
	s_add_i32 m0, s63, 0xc000
	ds_read_b128 v[186:189], v199
	ds_read_b128 v[190:193], v199 offset:1024
	ds_read_b128 v[200:203], v199 offset:2048
	ds_read_b128 v[204:207], v199 offset:3072
	ds_read_b128 v[208:211], v199 offset:4096
	ds_read_b128 v[212:215], v199 offset:5120
	ds_read_b128 v[216:219], v199 offset:6144
	ds_read_b128 v[220:223], v199 offset:7168
	global_load_lds_dwordx4 v[224:225], off
	v_lshl_add_u64 v[224:225], s[52:53], 0, v[180:181]
	s_add_i32 m0, s63, 0xe000
	s_nop 0
	global_load_lds_dwordx4 v[224:225], off
	s_waitcnt vmcnt(8)
	s_waitcnt lgkmcnt(0)
	s_setprio 1
	s_barrier
	v_mfma_f32_16x16x128_f8f6f4 v[124:127], v[152:159], v[186:193], v[124:127]
	v_mfma_f32_16x16x128_f8f6f4 v[120:123], v[144:151], v[186:193], v[120:123]
	v_mfma_f32_16x16x128_f8f6f4 v[112:115], v[152:159], v[200:207], v[112:115]
	v_mfma_f32_16x16x128_f8f6f4 v[104:107], v[144:151], v[200:207], v[104:107]
	v_mfma_f32_16x16x128_f8f6f4 v[96:99], v[152:159], v[208:215], v[96:99]
	v_mfma_f32_16x16x128_f8f6f4 v[88:91], v[144:151], v[208:215], v[88:91]
	v_mfma_f32_16x16x128_f8f6f4 v[84:87], v[152:159], v[216:223], v[84:87]
	v_mfma_f32_16x16x128_f8f6f4 v[72:75], v[144:151], v[216:223], v[72:75]
	v_mfma_f32_16x16x128_f8f6f4 v[116:119], v[136:143], v[186:193], v[116:119]
	v_mfma_f32_16x16x128_f8f6f4 v[108:111], v[128:135], v[186:193], v[108:111]
	v_mfma_f32_16x16x128_f8f6f4 v[100:103], v[136:143], v[200:207], v[100:103]
	v_mfma_f32_16x16x128_f8f6f4 v[92:95], v[128:135], v[200:207], v[92:95]
	v_mfma_f32_16x16x128_f8f6f4 v[80:83], v[136:143], v[208:215], v[80:83]
	v_mfma_f32_16x16x128_f8f6f4 v[76:79], v[128:135], v[208:215], v[76:79]
	v_mfma_f32_16x16x128_f8f6f4 v[68:71], v[136:143], v[216:223], v[68:71]
	v_mfma_f32_16x16x128_f8f6f4 v[64:67], v[128:135], v[216:223], v[64:67]
	s_setprio 0
	s_barrier
	s_add_i32 s86, s74, s60
	v_lshl_add_u64 v[186:187], s[54:55], 0, v[160:161]
	s_mov_b32 m0, s86
	ds_read_b128 v[200:203], v199 offset:16384
	ds_read_b128 v[204:207], v199 offset:17408
	ds_read_b128 v[208:211], v199 offset:18432
	ds_read_b128 v[212:215], v199 offset:19456
	ds_read_b128 v[216:219], v199 offset:20480
	ds_read_b128 v[220:223], v199 offset:21504
	ds_read_b128 v[224:227], v199 offset:22528
	ds_read_b128 v[228:231], v199 offset:23552
	global_load_lds_dwordx4 v[186:187], off
	s_add_i32 m0, s86, 0x2000
	s_add_u32 s86, s54, 0x40000
	v_lshl_add_u64 v[188:189], s[54:55], 0, v[162:163]
	s_addc_u32 s87, s55, 0
	s_add_i32 s88, s75, s60
	global_load_lds_dwordx4 v[188:189], off
	v_lshl_add_u64 v[190:191], s[86:87], 0, v[160:161]
	s_mov_b32 m0, s88
	v_lshl_add_u64 v[192:193], s[56:57], 0, v[164:165]
	global_load_lds_dwordx4 v[190:191], off
	v_lshl_add_u64 v[190:191], s[86:87], 0, v[162:163]
	s_add_i32 m0, s88, 0x2000
	s_nop 0
	global_load_lds_dwordx4 v[190:191], off
	v_lshl_add_u64 v[190:191], s[56:57], 0, v[166:167]
	s_mov_b32 m0, s63
	s_nop 0
	global_load_lds_dwordx4 v[190:191], off
	s_mov_b32 m0, s68
	s_nop 0
	global_load_lds_dwordx4 v[192:193], off
	s_waitcnt vmcnt(8)
	s_waitcnt lgkmcnt(0)
	s_setprio 1
	s_barrier
	v_mfma_f32_16x16x128_f8f6f4 v[60:63], v[152:159], v[200:207], v[60:63]
	v_mfma_f32_16x16x128_f8f6f4 v[56:59], v[144:151], v[200:207], v[56:59]
	v_mfma_f32_16x16x128_f8f6f4 v[48:51], v[152:159], v[208:215], v[48:51]
	v_mfma_f32_16x16x128_f8f6f4 v[40:43], v[144:151], v[208:215], v[40:43]
	v_mfma_f32_16x16x128_f8f6f4 v[32:35], v[152:159], v[216:223], v[32:35]
	v_mfma_f32_16x16x128_f8f6f4 v[24:27], v[144:151], v[216:223], v[24:27]
	v_mfma_f32_16x16x128_f8f6f4 v[16:19], v[152:159], v[224:231], v[16:19]
	v_mfma_f32_16x16x128_f8f6f4 v[8:11], v[144:151], v[224:231], v[8:11]
	v_mfma_f32_16x16x128_f8f6f4 v[52:55], v[136:143], v[200:207], v[52:55]
	v_mfma_f32_16x16x128_f8f6f4 v[44:47], v[128:135], v[200:207], v[44:47]
	v_mfma_f32_16x16x128_f8f6f4 v[36:39], v[136:143], v[208:215], v[36:39]
	v_mfma_f32_16x16x128_f8f6f4 v[28:31], v[128:135], v[208:215], v[28:31]
	v_mfma_f32_16x16x128_f8f6f4 v[20:23], v[136:143], v[216:223], v[20:23]
	v_mfma_f32_16x16x128_f8f6f4 v[12:15], v[128:135], v[216:223], v[12:15]
	v_mfma_f32_16x16x128_f8f6f4 v[4:7], v[136:143], v[224:231], v[4:7]
	v_mfma_f32_16x16x128_f8f6f4 v[0:3], v[128:135], v[224:231], v[0:3]
	s_setprio 0
	s_barrier
; #define PG8_STAGE(bufoff, gbase, voff) do { _Pragma("unroll") for (int _i = 0; _i < 2; ++_i) \
;         __builtin_amdgcn_global_load_lds((const unsigned*)((const char*)(gbase) + (voff)[_i]), (LAS unsigned*)(lds + (bufoff) + ldsw + _i * 8192), 16, 0, 0); } while (0)
; #define PG8_LDA(dst, b, h) do { _Pragma("unroll") for (int m = 0; m < 4; ++m) _Pragma("unroll") for (int k = 0; k < 2; ++k) dst[m][k] = *(const LAS bf16x8*)(lds + PG8_SA(b, h) + aoff + m * 2048 + k * 1024); } while (0)
; #define PG8_LDB(dst, b, h) do { _Pragma("unroll") for (int n = 0; n < 2; ++n) _Pragma("unroll") for (int k = 0; k < 2; ++k) dst[n][k] = *(const LAS bf16x8*)(lds + PG8_SB(b, h) + boff + n * 2048 + k * 1024); } while (0)
; #define PG8_WAIT_V(n) asm volatile("s_waitcnt vmcnt(" #n ")" ::: "memory")
; #define PG8_WAIT_L(n) asm volatile("s_waitcnt lgkmcnt(" #n ")" ::: "memory")
; #define PG8_BAR __builtin_amdgcn_s_barrier()
; #define PG8_SCHED __builtin_amdgcn_sched_barrier(0)
; template <class Epi, bool FP8 = false>
; __device__ __forceinline__ void gemm_phase(LAS unsigned char* lds, const Gemm g, const StaticOrder& S_, const Epi& E, const int tid) {
;     ...
;             PG8_LDB(B0, 1, 0); PG8_LDB(B1, 1, 1); PG8_SCHED; PG8_LDA(At, 1, 0); PG8_STAGE(PG8_SA(0, 1), a2 + hstepA, voffA);
;             PG8_WAIT_V(8); PG8_WAIT_L(0); PG8_BAR; PG8_MMA(0, 0, At, B0); PG8_MMA(0, 1, At, B1); PG8_BAR; PG8_SCHED;
;             PG8_LDA(At, 1, 1); PG8_STAGE(PG8_SB(1, 0), b3, voffB); PG8_STAGE(PG8_SB(1, 1), b3 + hstepB, voffB); PG8_STAGE(PG8_SA(1, 0), a3, voffA);
;             PG8_WAIT_V(8); PG8_WAIT_L(0); PG8_BAR; PG8_MMA(1, 0, At, B0); PG8_MMA(1, 1, At, B1); PG8_BAR; PG8_SCHED;
;         }
;         if (wr == 0) PG8_BAR;
	s_add_i32 s86, 0, 0x18000
	v_add_u32_e32 v128, s86, v195
	s_add_i32 s87, 0, 0x1c000
	ds_read_b128 v[156:159], v128 offset:1024
	ds_read_b128 v[152:155], v128
	ds_read_b128 v[148:151], v128 offset:3072
	ds_read_b128 v[144:147], v128 offset:2048
	v_add_u32_e32 v128, s87, v195
	ds_read_b128 v[140:143], v128 offset:1024
	ds_read_b128 v[136:139], v128
	ds_read_b128 v[132:135], v128 offset:3072
	ds_read_b128 v[128:131], v128 offset:2048
	s_add_u32 s56, s56, 0x40000
	s_addc_u32 s57, s57, 0
	s_mov_b32 m0, s69
	v_lshl_add_u64 v[232:233], s[56:57], 0, v[166:167]
	ds_read_b128 v[200:203], v199 offset:32768
	ds_read_b128 v[204:207], v199 offset:33792
	ds_read_b128 v[208:211], v199 offset:34816
	ds_read_b128 v[212:215], v199 offset:35840
	ds_read_b128 v[216:219], v199 offset:36864
	ds_read_b128 v[220:223], v199 offset:37888
	ds_read_b128 v[224:227], v199 offset:38912
	ds_read_b128 v[228:231], v199 offset:39936
	global_load_lds_dwordx4 v[232:233], off
	v_lshl_add_u64 v[232:233], s[56:57], 0, v[164:165]
	s_mov_b32 m0, s70
	s_nop 0
	global_load_lds_dwordx4 v[232:233], off
	s_waitcnt vmcnt(8)
	s_waitcnt lgkmcnt(0)
	s_setprio 1
	s_barrier
	v_mfma_f32_16x16x128_f8f6f4 v[124:127], v[152:159], v[200:207], v[124:127]
	v_mfma_f32_16x16x128_f8f6f4 v[120:123], v[144:151], v[200:207], v[120:123]
	v_mfma_f32_16x16x128_f8f6f4 v[112:115], v[152:159], v[208:215], v[112:115]
	v_mfma_f32_16x16x128_f8f6f4 v[104:107], v[144:151], v[208:215], v[104:107]
	v_mfma_f32_16x16x128_f8f6f4 v[96:99], v[152:159], v[216:223], v[96:99]
	v_mfma_f32_16x16x128_f8f6f4 v[88:91], v[144:151], v[216:223], v[88:91]
	v_mfma_f32_16x16x128_f8f6f4 v[84:87], v[152:159], v[224:231], v[84:87]
	v_mfma_f32_16x16x128_f8f6f4 v[72:75], v[144:151], v[224:231], v[72:75]
	v_mfma_f32_16x16x128_f8f6f4 v[116:119], v[136:143], v[200:207], v[116:119]
	v_mfma_f32_16x16x128_f8f6f4 v[108:111], v[128:135], v[200:207], v[108:111]
	v_mfma_f32_16x16x128_f8f6f4 v[100:103], v[136:143], v[208:215], v[100:103]
	v_mfma_f32_16x16x128_f8f6f4 v[92:95], v[128:135], v[208:215], v[92:95]
	v_mfma_f32_16x16x128_f8f6f4 v[80:83], v[136:143], v[216:223], v[80:83]
	v_mfma_f32_16x16x128_f8f6f4 v[76:79], v[128:135], v[216:223], v[76:79]
	v_mfma_f32_16x16x128_f8f6f4 v[68:71], v[136:143], v[224:231], v[68:71]
	v_mfma_f32_16x16x128_f8f6f4 v[64:67], v[128:135], v[224:231], v[64:67]
	s_setprio 0
	s_barrier
	s_add_i32 s56, s86, s60
	v_lshl_add_u64 v[186:187], v[186:187], 0, s[10:11]
	s_mov_b32 m0, s56
	ds_read_b128 v[200:203], v199 offset:49152
	ds_read_b128 v[204:207], v199 offset:50176
	ds_read_b128 v[208:211], v199 offset:51200
	ds_read_b128 v[212:215], v199 offset:52224
	ds_read_b128 v[216:219], v199 offset:53248
	ds_read_b128 v[220:223], v199 offset:54272
	ds_read_b128 v[224:227], v199 offset:55296
	ds_read_b128 v[228:231], v199 offset:56320
	global_load_lds_dwordx4 v[186:187], off
	s_add_i32 m0, s56, 0x2000
	s_add_u32 s54, s54, 0x40080
	v_lshl_add_u64 v[186:187], v[188:189], 0, s[10:11]
	s_addc_u32 s55, s55, 0
	s_add_i32 s56, s87, s60
	global_load_lds_dwordx4 v[186:187], off
	v_lshl_add_u64 v[186:187], s[54:55], 0, v[160:161]
	s_mov_b32 m0, s56
	s_nop 0
	global_load_lds_dwordx4 v[186:187], off
	v_lshl_add_u64 v[186:187], s[54:55], 0, v[162:163]
	s_add_i32 m0, s56, 0x2000
	s_nop 0
	global_load_lds_dwordx4 v[186:187], off
	v_lshl_add_u64 v[186:187], v[190:191], 0, s[10:11]
	s_mov_b32 m0, s72
	s_nop 0
	global_load_lds_dwordx4 v[186:187], off
	v_lshl_add_u64 v[186:187], v[192:193], 0, s[10:11]
	s_mov_b32 m0, s73
	s_nop 0
	global_load_lds_dwordx4 v[186:187], off
	s_waitcnt vmcnt(8)
	s_waitcnt lgkmcnt(0)
	s_setprio 1
	s_barrier
	v_mfma_f32_16x16x128_f8f6f4 v[60:63], v[152:159], v[200:207], v[60:63]
	v_mfma_f32_16x16x128_f8f6f4 v[56:59], v[144:151], v[200:207], v[56:59]
	v_mfma_f32_16x16x128_f8f6f4 v[48:51], v[152:159], v[208:215], v[48:51]
	v_mfma_f32_16x16x128_f8f6f4 v[40:43], v[144:151], v[208:215], v[40:43]
	v_mfma_f32_16x16x128_f8f6f4 v[32:35], v[152:159], v[216:223], v[32:35]
	v_mfma_f32_16x16x128_f8f6f4 v[24:27], v[144:151], v[216:223], v[24:27]
	v_mfma_f32_16x16x128_f8f6f4 v[16:19], v[152:159], v[224:231], v[16:19]
	v_mfma_f32_16x16x128_f8f6f4 v[8:11], v[144:151], v[224:231], v[8:11]
	v_mfma_f32_16x16x128_f8f6f4 v[52:55], v[136:143], v[200:207], v[52:55]
	v_mfma_f32_16x16x128_f8f6f4 v[44:47], v[128:135], v[200:207], v[44:47]
	v_mfma_f32_16x16x128_f8f6f4 v[36:39], v[136:143], v[208:215], v[36:39]
	v_mfma_f32_16x16x128_f8f6f4 v[28:31], v[128:135], v[208:215], v[28:31]
	v_mfma_f32_16x16x128_f8f6f4 v[20:23], v[136:143], v[216:223], v[20:23]
	v_mfma_f32_16x16x128_f8f6f4 v[12:15], v[128:135], v[216:223], v[12:15]
	v_mfma_f32_16x16x128_f8f6f4 v[4:7], v[136:143], v[224:231], v[4:7]
	v_mfma_f32_16x16x128_f8f6f4 v[0:3], v[128:135], v[224:231], v[0:3]
	s_setprio 0
	s_barrier
	s_add_i32 s85, s85, 2
	s_add_u32 s52, s52, 0x100
	s_addc_u32 s53, s53, 0
	s_add_u32 s66, s66, 0x100
	s_addc_u32 s84, s84, 0
	s_cmp_gt_u32 s85, 13
	s_cbranch_scc0 .LBB0_596
	s_and_b64 vcc, exec, s[12:13]
	s_cbranch_vccz .LBB0_599
	s_barrier

; #define PG8_STAGE(bufoff, gbase, voff) do { _Pragma("unroll") for (int _i = 0; _i < 2; ++_i) \
;         __builtin_amdgcn_global_load_lds((const unsigned*)((const char*)(gbase) + (voff)[_i]), (LAS unsigned*)(lds + (bufoff) + ldsw + _i * 8192), 16, 0, 0); } while (0)
; #define PG8_LDA(dst, b, h) do { _Pragma("unroll") for (int m = 0; m < 4; ++m) _Pragma("unroll") for (int k = 0; k < 2; ++k) dst[m][k] = *(const LAS bf16x8*)(lds + PG8_SA(b, h) + aoff + m * 2048 + k * 1024); } while (0)
; #define PG8_LDB(dst, b, h) do { _Pragma("unroll") for (int n = 0; n < 2; ++n) _Pragma("unroll") for (int k = 0; k < 2; ++k) dst[n][k] = *(const LAS bf16x8*)(lds + PG8_SB(b, h) + boff + n * 2048 + k * 1024); } while (0)
; #define PG8_WAIT_V(n) asm volatile("s_waitcnt vmcnt(" #n ")" ::: "memory")
; #define PG8_WAIT_L(n) asm volatile("s_waitcnt lgkmcnt(" #n ")" ::: "memory")
; #define PG8_BAR __builtin_amdgcn_s_barrier()
; #define PG8_SCHED __builtin_amdgcn_sched_barrier(0)
; template <class Epi, bool FP8 = false>
; __device__ __forceinline__ void gemm_phase(LAS unsigned char* lds, const Gemm g, const StaticOrder& S_, const Epi& E, const int tid) {
;     ...
;         for (int t = 0; t < nt; t += 2) {
;             const bool last = (t == nt - 2);
;             const char* a1 = cA + (size_t)(t + 1) * kstep;
;             const char* a2 = last ? nA : cA + (size_t)(t + 2) * kstep; const char* b2 = last ? nB : cB + (size_t)(t + 2) * kstep;
;             const char* a3 = a2 + kstep; const char* b3 = b2 + kstep;
;             PG8_LDB(B0, 0, 0); PG8_LDB(B1, 0, 1); PG8_SCHED; PG8_LDA(At, 0, 0); PG8_STAGE(PG8_SA(1, 1), a1 + hstepA, voffA);
;             PG8_WAIT_V(8); PG8_WAIT_L(0); PG8_BAR; PG8_MMA(0, 0, At, B0); PG8_MMA(0, 1, At, B1); PG8_BAR; PG8_SCHED;
;             PG8_LDA(At, 0, 1); PG8_STAGE(PG8_SB(0, 0), b2, voffB); PG8_STAGE(PG8_SB(0, 1), b2 + hstepB, voffB); PG8_STAGE(PG8_SA(0, 0), a2, voffA);
;             PG8_WAIT_V(8); PG8_WAIT_L(0); PG8_BAR; PG8_MMA(1, 0, At, B0); PG8_MMA(1, 1, At, B1); PG8_BAR; PG8_SCHED;
.LBB0_1095:
	ds_read_b128 v[144:147], v174
	ds_read_b128 v[178:181], v174 offset:1024
	ds_read_b128 v[182:185], v174 offset:2048
	ds_read_b128 v[186:189], v174 offset:3072
	ds_read_b128 v[190:193], v175
	ds_read_b128 v[194:197], v175 offset:1024
	ds_read_b128 v[198:201], v175 offset:2048
	ds_read_b128 v[202:205], v175 offset:3072
	s_add_u32 s8, s26, 0x100
	s_addc_u32 s9, s27, 0
	s_cmp_eq_u32 s69, 12
	s_cselect_b32 s49, s23, s9
	s_cselect_b32 s48, s22, s8
	s_cselect_b32 s47, s21, s68
	s_cselect_b32 s46, s66, s67
	v_lshl_add_u64 v[238:239], s[26:27], 0, v[136:137]
	s_add_i32 m0, s54, 0xc000
	ds_read_b128 v[206:209], v176
	ds_read_b128 v[210:213], v176 offset:1024
	ds_read_b128 v[214:217], v176 offset:2048
	ds_read_b128 v[218:221], v176 offset:3072
	ds_read_b128 v[222:225], v176 offset:4096
	ds_read_b128 v[226:229], v176 offset:5120
	ds_read_b128 v[230:233], v176 offset:6144
	ds_read_b128 v[234:237], v176 offset:7168
	global_load_lds_dwordx4 v[238:239], off
	v_lshl_add_u64 v[238:239], s[26:27], 0, v[138:139]
	s_add_i32 m0, s54, 0xe000
	s_nop 0
	global_load_lds_dwordx4 v[238:239], off
	s_waitcnt vmcnt(8)
	s_waitcnt lgkmcnt(0)
	s_setprio 1
	s_barrier
	v_mfma_f32_16x16x32_bf16 v[124:127], v[144:147], v[206:209], v[124:127]
	v_mfma_f32_16x16x32_bf16 v[120:123], v[182:185], v[206:209], v[120:123]
	v_mfma_f32_16x16x32_bf16 v[108:111], v[144:147], v[214:217], v[108:111]
	v_mfma_f32_16x16x32_bf16 v[104:107], v[182:185], v[214:217], v[104:107]
	v_mfma_f32_16x16x32_bf16 v[92:95], v[144:147], v[222:225], v[92:95]
	v_mfma_f32_16x16x32_bf16 v[88:91], v[182:185], v[222:225], v[88:91]
	v_mfma_f32_16x16x32_bf16 v[76:79], v[144:147], v[230:233], v[76:79]
	v_mfma_f32_16x16x32_bf16 v[72:75], v[182:185], v[230:233], v[72:75]
	v_mfma_f32_16x16x32_bf16 v[124:127], v[178:181], v[210:213], v[124:127]
	v_mfma_f32_16x16x32_bf16 v[120:123], v[186:189], v[210:213], v[120:123]
	v_mfma_f32_16x16x32_bf16 v[108:111], v[178:181], v[218:221], v[108:111]
	v_mfma_f32_16x16x32_bf16 v[104:107], v[186:189], v[218:221], v[104:107]
	v_mfma_f32_16x16x32_bf16 v[92:95], v[178:181], v[226:229], v[92:95]
	v_mfma_f32_16x16x32_bf16 v[88:91], v[186:189], v[226:229], v[88:91]
	v_mfma_f32_16x16x32_bf16 v[76:79], v[178:181], v[234:237], v[76:79]
	v_mfma_f32_16x16x32_bf16 v[72:75], v[186:189], v[234:237], v[72:75]
	v_mfma_f32_16x16x32_bf16 v[116:119], v[190:193], v[206:209], v[116:119]
	v_mfma_f32_16x16x32_bf16 v[112:115], v[198:201], v[206:209], v[112:115]
	v_mfma_f32_16x16x32_bf16 v[100:103], v[190:193], v[214:217], v[100:103]
	v_mfma_f32_16x16x32_bf16 v[96:99], v[198:201], v[214:217], v[96:99]
	v_mfma_f32_16x16x32_bf16 v[84:87], v[190:193], v[222:225], v[84:87]
	v_mfma_f32_16x16x32_bf16 v[80:83], v[198:201], v[222:225], v[80:83]
	v_mfma_f32_16x16x32_bf16 v[68:71], v[190:193], v[230:233], v[68:71]
	v_mfma_f32_16x16x32_bf16 v[64:67], v[198:201], v[230:233], v[64:67]
	v_mfma_f32_16x16x32_bf16 v[116:119], v[194:197], v[210:213], v[116:119]
	v_mfma_f32_16x16x32_bf16 v[112:115], v[202:205], v[210:213], v[112:115]
	v_mfma_f32_16x16x32_bf16 v[100:103], v[194:197], v[218:221], v[100:103]
	v_mfma_f32_16x16x32_bf16 v[96:99], v[202:205], v[218:221], v[96:99]
	v_mfma_f32_16x16x32_bf16 v[84:87], v[194:197], v[226:229], v[84:87]
	v_mfma_f32_16x16x32_bf16 v[80:83], v[202:205], v[226:229], v[80:83]
	v_mfma_f32_16x16x32_bf16 v[68:71], v[194:197], v[234:237], v[68:71]
	v_mfma_f32_16x16x32_bf16 v[64:67], v[202:205], v[234:237], v[64:67]
	s_setprio 0
	s_barrier
	s_add_i32 s26, s61, s53
	v_lshl_add_u64 v[238:239], s[46:47], 0, v[132:133]
	s_mov_b32 m0, s26
	ds_read_b128 v[206:209], v176 offset:16384
	ds_read_b128 v[210:213], v176 offset:17408
	ds_read_b128 v[214:217], v176 offset:18432
	ds_read_b128 v[218:221], v176 offset:19456
	ds_read_b128 v[222:225], v176 offset:20480
	ds_read_b128 v[226:229], v176 offset:21504
	ds_read_b128 v[230:233], v176 offset:22528
	ds_read_b128 v[234:237], v176 offset:23552
	global_load_lds_dwordx4 v[238:239], off
	s_add_i32 m0, s26, 0x2000
	s_add_u32 s26, s46, 0x40000
	v_lshl_add_u64 v[240:241], s[46:47], 0, v[134:135]
	s_addc_u32 s27, s47, 0
	s_add_i32 s70, s62, s53
	global_load_lds_dwordx4 v[240:241], off
	v_lshl_add_u64 v[242:243], s[26:27], 0, v[132:133]
	s_mov_b32 m0, s70
	v_lshl_add_u64 v[244:245], s[48:49], 0, v[130:131]
	global_load_lds_dwordx4 v[242:243], off
	v_lshl_add_u64 v[242:243], s[26:27], 0, v[134:135]
	s_add_i32 m0, s70, 0x2000
	s_nop 0
	global_load_lds_dwordx4 v[242:243], off
	v_lshl_add_u64 v[242:243], s[48:49], 0, v[128:129]
	s_mov_b32 m0, s54
	s_nop 0
	global_load_lds_dwordx4 v[242:243], off
	s_mov_b32 m0, s55
	s_nop 0
	global_load_lds_dwordx4 v[244:245], off
	s_waitcnt vmcnt(8)
	s_waitcnt lgkmcnt(0)
	s_setprio 1
	s_barrier
; #define PG8_STAGE(bufoff, gbase, voff) do { _Pragma("unroll") for (int _i = 0; _i < 2; ++_i) \
;         __builtin_amdgcn_global_load_lds((const unsigned*)((const char*)(gbase) + (voff)[_i]), (LAS unsigned*)(lds + (bufoff) + ldsw + _i * 8192), 16, 0, 0); } while (0)
; #define PG8_LDA(dst, b, h) do { _Pragma("unroll") for (int m = 0; m < 4; ++m) _Pragma("unroll") for (int k = 0; k < 2; ++k) dst[m][k] = *(const LAS bf16x8*)(lds + PG8_SA(b, h) + aoff + m * 2048 + k * 1024); } while (0)
; #define PG8_LDB(dst, b, h) do { _Pragma("unroll") for (int n = 0; n < 2; ++n) _Pragma("unroll") for (int k = 0; k < 2; ++k) dst[n][k] = *(const LAS bf16x8*)(lds + PG8_SB(b, h) + boff + n * 2048 + k * 1024); } while (0)
; #define PG8_WAIT_V(n) asm volatile("s_waitcnt vmcnt(" #n ")" ::: "memory")
; #define PG8_WAIT_L(n) asm volatile("s_waitcnt lgkmcnt(" #n ")" ::: "memory")
; #define PG8_BAR __builtin_amdgcn_s_barrier()
; #define PG8_SCHED __builtin_amdgcn_sched_barrier(0)
; template <class Epi, bool FP8 = false>
; __device__ __forceinline__ void gemm_phase(LAS unsigned char* lds, const Gemm g, const StaticOrder& S_, const Epi& E, const int tid) {
;     ...
;             PG8_WAIT_V(8); PG8_WAIT_L(0); PG8_BAR; PG8_MMA(1, 0, At, B0); PG8_MMA(1, 1, At, B1); PG8_BAR; PG8_SCHED;
;             PG8_LDB(B0, 1, 0); PG8_LDB(B1, 1, 1); PG8_SCHED; PG8_LDA(At, 1, 0); PG8_STAGE(PG8_SA(0, 1), a2 + hstepA, voffA);
;             PG8_WAIT_V(8); PG8_WAIT_L(0); PG8_BAR; PG8_MMA(0, 0, At, B0); PG8_MMA(0, 1, At, B1); PG8_BAR; PG8_SCHED;
;             PG8_LDA(At, 1, 1); PG8_STAGE(PG8_SB(1, 0), b3, voffB); PG8_STAGE(PG8_SB(1, 1), b3 + hstepB, voffB); PG8_STAGE(PG8_SA(1, 0), a3, voffA);
;             PG8_WAIT_V(8); PG8_WAIT_L(0); PG8_BAR; PG8_MMA(1, 0, At, B0); PG8_MMA(1, 1, At, B1); PG8_BAR; PG8_SCHED;
	v_mfma_f32_16x16x32_bf16 v[60:63], v[144:147], v[206:209], v[60:63]
	v_mfma_f32_16x16x32_bf16 v[56:59], v[182:185], v[206:209], v[56:59]
	v_mfma_f32_16x16x32_bf16 v[44:47], v[144:147], v[214:217], v[44:47]
	v_mfma_f32_16x16x32_bf16 v[40:43], v[182:185], v[214:217], v[40:43]
	v_mfma_f32_16x16x32_bf16 v[28:31], v[144:147], v[222:225], v[28:31]
	v_mfma_f32_16x16x32_bf16 v[24:27], v[182:185], v[222:225], v[24:27]
	v_mfma_f32_16x16x32_bf16 v[12:15], v[144:147], v[230:233], v[12:15]
	v_mfma_f32_16x16x32_bf16 v[8:11], v[182:185], v[230:233], v[8:11]
	v_mfma_f32_16x16x32_bf16 v[60:63], v[178:181], v[210:213], v[60:63]
	v_mfma_f32_16x16x32_bf16 v[56:59], v[186:189], v[210:213], v[56:59]
	v_mfma_f32_16x16x32_bf16 v[44:47], v[178:181], v[218:221], v[44:47]
	v_mfma_f32_16x16x32_bf16 v[40:43], v[186:189], v[218:221], v[40:43]
	v_mfma_f32_16x16x32_bf16 v[28:31], v[178:181], v[226:229], v[28:31]
	v_mfma_f32_16x16x32_bf16 v[24:27], v[186:189], v[226:229], v[24:27]
	v_mfma_f32_16x16x32_bf16 v[12:15], v[178:181], v[234:237], v[12:15]
	v_mfma_f32_16x16x32_bf16 v[8:11], v[186:189], v[234:237], v[8:11]
	v_mfma_f32_16x16x32_bf16 v[52:55], v[190:193], v[206:209], v[52:55]
	v_mfma_f32_16x16x32_bf16 v[48:51], v[198:201], v[206:209], v[48:51]
	v_mfma_f32_16x16x32_bf16 v[36:39], v[190:193], v[214:217], v[36:39]
	v_mfma_f32_16x16x32_bf16 v[32:35], v[198:201], v[214:217], v[32:35]
	v_mfma_f32_16x16x32_bf16 v[20:23], v[190:193], v[222:225], v[20:23]
	v_mfma_f32_16x16x32_bf16 v[16:19], v[198:201], v[222:225], v[16:19]
	v_mfma_f32_16x16x32_bf16 v[4:7], v[190:193], v[230:233], v[4:7]
	v_mfma_f32_16x16x32_bf16 v[0:3], v[198:201], v[230:233], v[0:3]
	v_mfma_f32_16x16x32_bf16 v[52:55], v[194:197], v[210:213], v[52:55]
	v_mfma_f32_16x16x32_bf16 v[48:51], v[202:205], v[210:213], v[48:51]
	v_mfma_f32_16x16x32_bf16 v[36:39], v[194:197], v[218:221], v[36:39]
	v_mfma_f32_16x16x32_bf16 v[32:35], v[202:205], v[218:221], v[32:35]
	v_mfma_f32_16x16x32_bf16 v[20:23], v[194:197], v[226:229], v[20:23]
	v_mfma_f32_16x16x32_bf16 v[16:19], v[202:205], v[226:229], v[16:19]
	v_mfma_f32_16x16x32_bf16 v[4:7], v[194:197], v[234:237], v[4:7]
	v_mfma_f32_16x16x32_bf16 v[0:3], v[202:205], v[234:237], v[0:3]
	s_setprio 0
	s_barrier
	s_add_i32 s70, 0, 0x18000
	v_add_u32_e32 v177, s70, v172
	s_add_i32 s71, 0, 0x1c000
	ds_read_b128 v[144:147], v177
	ds_read_b128 v[178:181], v177 offset:1024
	ds_read_b128 v[182:185], v177 offset:2048
	ds_read_b128 v[186:189], v177 offset:3072
	v_add_u32_e32 v177, s71, v172
	ds_read_b128 v[190:193], v177
	ds_read_b128 v[194:197], v177 offset:1024
	ds_read_b128 v[198:201], v177 offset:2048
	ds_read_b128 v[202:205], v177 offset:3072
	s_add_u32 s26, s48, 0x60000
	s_addc_u32 s27, s49, 0
	s_mov_b32 m0, s56
	v_lshl_add_u64 v[246:247], s[26:27], 0, v[128:129]
	ds_read_b128 v[206:209], v176 offset:32768
	ds_read_b128 v[210:213], v176 offset:33792
	ds_read_b128 v[214:217], v176 offset:34816
	ds_read_b128 v[218:221], v176 offset:35840
	ds_read_b128 v[222:225], v176 offset:36864
	ds_read_b128 v[226:229], v176 offset:37888
	ds_read_b128 v[230:233], v176 offset:38912
	ds_read_b128 v[234:237], v176 offset:39936
	global_load_lds_dwordx4 v[246:247], off
	v_lshl_add_u64 v[246:247], s[26:27], 0, v[130:131]
	s_mov_b32 m0, s57
	s_nop 0
	global_load_lds_dwordx4 v[246:247], off
	s_waitcnt vmcnt(8)
	s_waitcnt lgkmcnt(0)
	s_setprio 1
	s_barrier
	v_mfma_f32_16x16x32_bf16 v[124:127], v[144:147], v[206:209], v[124:127]
	v_mfma_f32_16x16x32_bf16 v[120:123], v[182:185], v[206:209], v[120:123]
	v_mfma_f32_16x16x32_bf16 v[108:111], v[144:147], v[214:217], v[108:111]
	v_mfma_f32_16x16x32_bf16 v[104:107], v[182:185], v[214:217], v[104:107]
	v_mfma_f32_16x16x32_bf16 v[92:95], v[144:147], v[222:225], v[92:95]
	v_mfma_f32_16x16x32_bf16 v[88:91], v[182:185], v[222:225], v[88:91]
	v_mfma_f32_16x16x32_bf16 v[76:79], v[144:147], v[230:233], v[76:79]
	v_mfma_f32_16x16x32_bf16 v[72:75], v[182:185], v[230:233], v[72:75]
	v_mfma_f32_16x16x32_bf16 v[124:127], v[178:181], v[210:213], v[124:127]
	v_mfma_f32_16x16x32_bf16 v[120:123], v[186:189], v[210:213], v[120:123]
	v_mfma_f32_16x16x32_bf16 v[108:111], v[178:181], v[218:221], v[108:111]
	v_mfma_f32_16x16x32_bf16 v[104:107], v[186:189], v[218:221], v[104:107]
	v_mfma_f32_16x16x32_bf16 v[92:95], v[178:181], v[226:229], v[92:95]
	v_mfma_f32_16x16x32_bf16 v[88:91], v[186:189], v[226:229], v[88:91]
	v_mfma_f32_16x16x32_bf16 v[76:79], v[178:181], v[234:237], v[76:79]
	v_mfma_f32_16x16x32_bf16 v[72:75], v[186:189], v[234:237], v[72:75]
	v_mfma_f32_16x16x32_bf16 v[116:119], v[190:193], v[206:209], v[116:119]
	v_mfma_f32_16x16x32_bf16 v[112:115], v[198:201], v[206:209], v[112:115]
	v_mfma_f32_16x16x32_bf16 v[100:103], v[190:193], v[214:217], v[100:103]
	v_mfma_f32_16x16x32_bf16 v[96:99], v[198:201], v[214:217], v[96:99]
	v_mfma_f32_16x16x32_bf16 v[84:87], v[190:193], v[222:225], v[84:87]
	v_mfma_f32_16x16x32_bf16 v[80:83], v[198:201], v[222:225], v[80:83]
	v_mfma_f32_16x16x32_bf16 v[68:71], v[190:193], v[230:233], v[68:71]
	v_mfma_f32_16x16x32_bf16 v[64:67], v[198:201], v[230:233], v[64:67]
	v_mfma_f32_16x16x32_bf16 v[116:119], v[194:197], v[210:213], v[116:119]
	v_mfma_f32_16x16x32_bf16 v[112:115], v[202:205], v[210:213], v[112:115]
	v_mfma_f32_16x16x32_bf16 v[100:103], v[194:197], v[218:221], v[100:103]
	v_mfma_f32_16x16x32_bf16 v[96:99], v[202:205], v[218:221], v[96:99]
	v_mfma_f32_16x16x32_bf16 v[84:87], v[194:197], v[226:229], v[84:87]
	v_mfma_f32_16x16x32_bf16 v[80:83], v[202:205], v[226:229], v[80:83]
	v_mfma_f32_16x16x32_bf16 v[68:71], v[194:197], v[234:237], v[68:71]
	v_mfma_f32_16x16x32_bf16 v[64:67], v[202:205], v[234:237], v[64:67]
	s_setprio 0
	s_barrier
; #define PG8_STAGE(bufoff, gbase, voff) do { _Pragma("unroll") for (int _i = 0; _i < 2; ++_i) \
;         __builtin_amdgcn_global_load_lds((const unsigned*)((const char*)(gbase) + (voff)[_i]), (LAS unsigned*)(lds + (bufoff) + ldsw + _i * 8192), 16, 0, 0); } while (0)
; #define PG8_LDA(dst, b, h) do { _Pragma("unroll") for (int m = 0; m < 4; ++m) _Pragma("unroll") for (int k = 0; k < 2; ++k) dst[m][k] = *(const LAS bf16x8*)(lds + PG8_SA(b, h) + aoff + m * 2048 + k * 1024); } while (0)
; #define PG8_WAIT_V(n) asm volatile("s_waitcnt vmcnt(" #n ")" ::: "memory")
; #define PG8_WAIT_L(n) asm volatile("s_waitcnt lgkmcnt(" #n ")" ::: "memory")
; #define PG8_BAR __builtin_amdgcn_s_barrier()
; #define PG8_SCHED __builtin_amdgcn_sched_barrier(0)
; template <class Epi, bool FP8 = false>
; __device__ __forceinline__ void gemm_phase(LAS unsigned char* lds, const Gemm g, const StaticOrder& S_, const Epi& E, const int tid) {
;     ...
;             PG8_LDA(At, 1, 1); PG8_STAGE(PG8_SB(1, 0), b3, voffB); PG8_STAGE(PG8_SB(1, 1), b3 + hstepB, voffB); PG8_STAGE(PG8_SA(1, 0), a3, voffA);
;             PG8_WAIT_V(8); PG8_WAIT_L(0); PG8_BAR; PG8_MMA(1, 0, At, B0); PG8_MMA(1, 1, At, B1); PG8_BAR; PG8_SCHED;
;         }
;         if (wr == 0) PG8_BAR;
	s_add_i32 s26, s70, s53
	v_lshl_add_u64 v[238:239], v[238:239], 0, s[16:17]
	s_mov_b32 m0, s26
	ds_read_b128 v[206:209], v176 offset:49152
	ds_read_b128 v[210:213], v176 offset:50176
	ds_read_b128 v[214:217], v176 offset:51200
	ds_read_b128 v[218:221], v176 offset:52224
	ds_read_b128 v[222:225], v176 offset:53248
	ds_read_b128 v[226:229], v176 offset:54272
	ds_read_b128 v[230:233], v176 offset:55296
	ds_read_b128 v[234:237], v176 offset:56320
	global_load_lds_dwordx4 v[238:239], off
	s_add_i32 m0, s26, 0x2000
	s_add_u32 s26, s46, 0x40080
	v_lshl_add_u64 v[238:239], v[240:241], 0, s[16:17]
	s_addc_u32 s27, s47, 0
	s_add_i32 s46, s71, s53
	global_load_lds_dwordx4 v[238:239], off
	v_lshl_add_u64 v[238:239], s[26:27], 0, v[132:133]
	s_mov_b32 m0, s46
	s_nop 0
	global_load_lds_dwordx4 v[238:239], off
	v_lshl_add_u64 v[238:239], s[26:27], 0, v[134:135]
	s_add_i32 m0, s46, 0x2000
	s_nop 0
	global_load_lds_dwordx4 v[238:239], off
	v_lshl_add_u64 v[238:239], v[242:243], 0, s[16:17]
	s_mov_b32 m0, s59
	s_nop 0
	global_load_lds_dwordx4 v[238:239], off
	v_lshl_add_u64 v[238:239], v[244:245], 0, s[16:17]
	s_mov_b32 m0, s60
	s_nop 0
	global_load_lds_dwordx4 v[238:239], off
	s_waitcnt vmcnt(8)
	s_waitcnt lgkmcnt(0)
	s_setprio 1
	s_barrier
	v_mfma_f32_16x16x32_bf16 v[60:63], v[144:147], v[206:209], v[60:63]
	v_mfma_f32_16x16x32_bf16 v[56:59], v[182:185], v[206:209], v[56:59]
	v_mfma_f32_16x16x32_bf16 v[44:47], v[144:147], v[214:217], v[44:47]
	v_mfma_f32_16x16x32_bf16 v[40:43], v[182:185], v[214:217], v[40:43]
	v_mfma_f32_16x16x32_bf16 v[28:31], v[144:147], v[222:225], v[28:31]
	v_mfma_f32_16x16x32_bf16 v[24:27], v[182:185], v[222:225], v[24:27]
	v_mfma_f32_16x16x32_bf16 v[12:15], v[144:147], v[230:233], v[12:15]
	v_mfma_f32_16x16x32_bf16 v[8:11], v[182:185], v[230:233], v[8:11]
	v_mfma_f32_16x16x32_bf16 v[60:63], v[178:181], v[210:213], v[60:63]
	v_mfma_f32_16x16x32_bf16 v[56:59], v[186:189], v[210:213], v[56:59]
	v_mfma_f32_16x16x32_bf16 v[44:47], v[178:181], v[218:221], v[44:47]
	v_mfma_f32_16x16x32_bf16 v[40:43], v[186:189], v[218:221], v[40:43]
	v_mfma_f32_16x16x32_bf16 v[28:31], v[178:181], v[226:229], v[28:31]
	v_mfma_f32_16x16x32_bf16 v[24:27], v[186:189], v[226:229], v[24:27]
	v_mfma_f32_16x16x32_bf16 v[12:15], v[178:181], v[234:237], v[12:15]
	v_mfma_f32_16x16x32_bf16 v[8:11], v[186:189], v[234:237], v[8:11]
	v_mfma_f32_16x16x32_bf16 v[52:55], v[190:193], v[206:209], v[52:55]
	v_mfma_f32_16x16x32_bf16 v[48:51], v[198:201], v[206:209], v[48:51]
	v_mfma_f32_16x16x32_bf16 v[36:39], v[190:193], v[214:217], v[36:39]
	v_mfma_f32_16x16x32_bf16 v[32:35], v[198:201], v[214:217], v[32:35]
	v_mfma_f32_16x16x32_bf16 v[20:23], v[190:193], v[222:225], v[20:23]
	v_mfma_f32_16x16x32_bf16 v[16:19], v[198:201], v[222:225], v[16:19]
	v_mfma_f32_16x16x32_bf16 v[4:7], v[190:193], v[230:233], v[4:7]
	v_mfma_f32_16x16x32_bf16 v[0:3], v[198:201], v[230:233], v[0:3]
	v_mfma_f32_16x16x32_bf16 v[52:55], v[194:197], v[210:213], v[52:55]
	v_mfma_f32_16x16x32_bf16 v[48:51], v[202:205], v[210:213], v[48:51]
	v_mfma_f32_16x16x32_bf16 v[36:39], v[194:197], v[218:221], v[36:39]
	v_mfma_f32_16x16x32_bf16 v[32:35], v[202:205], v[218:221], v[32:35]
	v_mfma_f32_16x16x32_bf16 v[20:23], v[194:197], v[226:229], v[20:23]
	v_mfma_f32_16x16x32_bf16 v[16:19], v[202:205], v[226:229], v[16:19]
	v_mfma_f32_16x16x32_bf16 v[4:7], v[194:197], v[234:237], v[4:7]
	v_mfma_f32_16x16x32_bf16 v[0:3], v[202:205], v[234:237], v[0:3]
	s_setprio 0
	s_barrier
	s_add_i32 s69, s69, 2
	s_add_u32 s67, s67, 0x100
	s_addc_u32 s68, s68, 0
	s_cmp_gt_u32 s69, 13
	s_mov_b64 s[26:27], s[8:9]
	s_cbranch_scc0 .LBB0_1095
	s_and_b64 vcc, exec, s[18:19]
	s_cbranch_vccz .LBB0_1098
	s_barrier

; #define PG8_STAGE(bufoff, gbase, voff) do { _Pragma("unroll") for (int _i = 0; _i < 2; ++_i) \
;         __builtin_amdgcn_global_load_lds((const unsigned*)((const char*)(gbase) + (voff)[_i]), (LAS unsigned*)(lds + (bufoff) + ldsw + _i * 8192), 16, 0, 0); } while (0)
; #define PG8_LDA(dst, b, h) do { _Pragma("unroll") for (int m = 0; m < 4; ++m) _Pragma("unroll") for (int k = 0; k < 2; ++k) dst[m][k] = *(const LAS bf16x8*)(lds + PG8_SA(b, h) + aoff + m * 2048 + k * 1024); } while (0)
; #define PG8_LDB(dst, b, h) do { _Pragma("unroll") for (int n = 0; n < 2; ++n) _Pragma("unroll") for (int k = 0; k < 2; ++k) dst[n][k] = *(const LAS bf16x8*)(lds + PG8_SB(b, h) + boff + n * 2048 + k * 1024); } while (0)
; #define PG8_WAIT_V(n) asm volatile("s_waitcnt vmcnt(" #n ")" ::: "memory")
; #define PG8_WAIT_L(n) asm volatile("s_waitcnt lgkmcnt(" #n ")" ::: "memory")
; #define PG8_BAR __builtin_amdgcn_s_barrier()
; #define PG8_SCHED __builtin_amdgcn_sched_barrier(0)
; template <class Epi, bool FP8 = false>
; __device__ __forceinline__ void gemm_phase(LAS unsigned char* lds, const Gemm g, const StaticOrder& S_, const Epi& E, const int tid) {
;     ...
;         for (int t = 0; t < nt; t += 2) {
;             const bool last = (t == nt - 2);
;             const char* a1 = cA + (size_t)(t + 1) * kstep;
;             const char* a2 = last ? nA : cA + (size_t)(t + 2) * kstep; const char* b2 = last ? nB : cB + (size_t)(t + 2) * kstep;
;             const char* a3 = a2 + kstep; const char* b3 = b2 + kstep;
;             PG8_LDB(B0, 0, 0); PG8_LDB(B1, 0, 1); PG8_SCHED; PG8_LDA(At, 0, 0); PG8_STAGE(PG8_SA(1, 1), a1 + hstepA, voffA);
;             PG8_WAIT_V(8); PG8_WAIT_L(0); PG8_BAR; PG8_MMA(0, 0, At, B0); PG8_MMA(0, 1, At, B1); PG8_BAR; PG8_SCHED;
;             PG8_LDA(At, 0, 1); PG8_STAGE(PG8_SB(0, 0), b2, voffB); PG8_STAGE(PG8_SB(0, 1), b2 + hstepB, voffB); PG8_STAGE(PG8_SA(0, 0), a2, voffA);
;             PG8_WAIT_V(8); PG8_WAIT_L(0); PG8_BAR; PG8_MMA(1, 0, At, B0); PG8_MMA(1, 1, At, B1); PG8_BAR; PG8_SCHED;
.LBB0_1121:
	ds_read_b128 v[144:147], v148
	ds_read_b128 v[152:155], v148 offset:1024
	ds_read_b128 v[160:163], v148 offset:2048
	ds_read_b128 v[164:167], v148 offset:3072
	ds_read_b128 v[168:171], v149
	ds_read_b128 v[172:175], v149 offset:1024
	ds_read_b128 v[176:179], v149 offset:2048
	ds_read_b128 v[180:183], v149 offset:3072
	s_add_u32 s8, s26, 0x100
	s_addc_u32 s9, s27, 0
	s_cmp_eq_u32 s69, 4
	s_cselect_b32 s49, s23, s9
	s_cselect_b32 s48, s22, s8
	s_cselect_b32 s47, s21, s68
	s_cselect_b32 s46, s66, s67
	v_lshl_add_u64 v[216:217], s[26:27], 0, v[136:137]
	s_add_i32 m0, s54, 0xc000
	ds_read_b128 v[184:187], v150
	ds_read_b128 v[188:191], v150 offset:1024
	ds_read_b128 v[192:195], v150 offset:2048
	ds_read_b128 v[196:199], v150 offset:3072
	ds_read_b128 v[200:203], v150 offset:4096
	ds_read_b128 v[204:207], v150 offset:5120
	ds_read_b128 v[208:211], v150 offset:6144
	ds_read_b128 v[212:215], v150 offset:7168
	global_load_lds_dwordx4 v[216:217], off
	v_lshl_add_u64 v[216:217], s[26:27], 0, v[138:139]
	s_add_i32 m0, s54, 0xe000
	s_nop 0
	global_load_lds_dwordx4 v[216:217], off
	s_waitcnt vmcnt(8)
	s_waitcnt lgkmcnt(0)
	s_setprio 1
	s_barrier
	v_mfma_f32_16x16x32_bf16 v[124:127], v[144:147], v[184:187], v[124:127]
	v_mfma_f32_16x16x32_bf16 v[120:123], v[160:163], v[184:187], v[120:123]
	v_mfma_f32_16x16x32_bf16 v[108:111], v[144:147], v[192:195], v[108:111]
	v_mfma_f32_16x16x32_bf16 v[104:107], v[160:163], v[192:195], v[104:107]
	v_mfma_f32_16x16x32_bf16 v[92:95], v[144:147], v[200:203], v[92:95]
	v_mfma_f32_16x16x32_bf16 v[88:91], v[160:163], v[200:203], v[88:91]
	v_mfma_f32_16x16x32_bf16 v[76:79], v[144:147], v[208:211], v[76:79]
	v_mfma_f32_16x16x32_bf16 v[72:75], v[160:163], v[208:211], v[72:75]
	v_mfma_f32_16x16x32_bf16 v[124:127], v[152:155], v[188:191], v[124:127]
	v_mfma_f32_16x16x32_bf16 v[120:123], v[164:167], v[188:191], v[120:123]
	v_mfma_f32_16x16x32_bf16 v[108:111], v[152:155], v[196:199], v[108:111]
	v_mfma_f32_16x16x32_bf16 v[104:107], v[164:167], v[196:199], v[104:107]
	v_mfma_f32_16x16x32_bf16 v[92:95], v[152:155], v[204:207], v[92:95]
	v_mfma_f32_16x16x32_bf16 v[88:91], v[164:167], v[204:207], v[88:91]
	v_mfma_f32_16x16x32_bf16 v[76:79], v[152:155], v[212:215], v[76:79]
	v_mfma_f32_16x16x32_bf16 v[72:75], v[164:167], v[212:215], v[72:75]
	v_mfma_f32_16x16x32_bf16 v[116:119], v[168:171], v[184:187], v[116:119]
	v_mfma_f32_16x16x32_bf16 v[112:115], v[176:179], v[184:187], v[112:115]
	v_mfma_f32_16x16x32_bf16 v[100:103], v[168:171], v[192:195], v[100:103]
	v_mfma_f32_16x16x32_bf16 v[96:99], v[176:179], v[192:195], v[96:99]
	v_mfma_f32_16x16x32_bf16 v[84:87], v[168:171], v[200:203], v[84:87]
	v_mfma_f32_16x16x32_bf16 v[80:83], v[176:179], v[200:203], v[80:83]
	v_mfma_f32_16x16x32_bf16 v[68:71], v[168:171], v[208:211], v[68:71]
	v_mfma_f32_16x16x32_bf16 v[64:67], v[176:179], v[208:211], v[64:67]
	v_mfma_f32_16x16x32_bf16 v[116:119], v[172:175], v[188:191], v[116:119]
	v_mfma_f32_16x16x32_bf16 v[112:115], v[180:183], v[188:191], v[112:115]
	v_mfma_f32_16x16x32_bf16 v[100:103], v[172:175], v[196:199], v[100:103]
	v_mfma_f32_16x16x32_bf16 v[96:99], v[180:183], v[196:199], v[96:99]
	v_mfma_f32_16x16x32_bf16 v[84:87], v[172:175], v[204:207], v[84:87]
	v_mfma_f32_16x16x32_bf16 v[80:83], v[180:183], v[204:207], v[80:83]
	v_mfma_f32_16x16x32_bf16 v[68:71], v[172:175], v[212:215], v[68:71]
	v_mfma_f32_16x16x32_bf16 v[64:67], v[180:183], v[212:215], v[64:67]
	s_setprio 0
	s_barrier
	s_add_i32 s26, s61, s53
	v_lshl_add_u64 v[216:217], s[46:47], 0, v[132:133]
	s_mov_b32 m0, s26
	ds_read_b128 v[184:187], v150 offset:16384
	ds_read_b128 v[188:191], v150 offset:17408
	ds_read_b128 v[192:195], v150 offset:18432
	ds_read_b128 v[196:199], v150 offset:19456
	ds_read_b128 v[200:203], v150 offset:20480
	ds_read_b128 v[204:207], v150 offset:21504
	ds_read_b128 v[208:211], v150 offset:22528
	ds_read_b128 v[212:215], v150 offset:23552
	global_load_lds_dwordx4 v[216:217], off
	s_add_i32 m0, s26, 0x2000
	s_add_u32 s26, s46, 0x20000
	v_lshl_add_u64 v[218:219], s[46:47], 0, v[134:135]
	s_addc_u32 s27, s47, 0
	s_add_i32 s70, s62, s53
	global_load_lds_dwordx4 v[218:219], off
	v_lshl_add_u64 v[220:221], s[26:27], 0, v[132:133]
	s_mov_b32 m0, s70
	v_lshl_add_u64 v[222:223], s[48:49], 0, v[130:131]
	global_load_lds_dwordx4 v[220:221], off
	v_lshl_add_u64 v[220:221], s[26:27], 0, v[134:135]
	s_add_i32 m0, s70, 0x2000
	s_nop 0
	global_load_lds_dwordx4 v[220:221], off
	v_lshl_add_u64 v[220:221], s[48:49], 0, v[128:129]
	s_mov_b32 m0, s54
	s_nop 0
	global_load_lds_dwordx4 v[220:221], off
	s_mov_b32 m0, s55
	s_nop 0
	global_load_lds_dwordx4 v[222:223], off
	s_waitcnt vmcnt(8)
	s_waitcnt lgkmcnt(0)
	s_setprio 1
	s_barrier
; #define PG8_STAGE(bufoff, gbase, voff) do { _Pragma("unroll") for (int _i = 0; _i < 2; ++_i) \
;         __builtin_amdgcn_global_load_lds((const unsigned*)((const char*)(gbase) + (voff)[_i]), (LAS unsigned*)(lds + (bufoff) + ldsw + _i * 8192), 16, 0, 0); } while (0)
; #define PG8_LDA(dst, b, h) do { _Pragma("unroll") for (int m = 0; m < 4; ++m) _Pragma("unroll") for (int k = 0; k < 2; ++k) dst[m][k] = *(const LAS bf16x8*)(lds + PG8_SA(b, h) + aoff + m * 2048 + k * 1024); } while (0)
; #define PG8_LDB(dst, b, h) do { _Pragma("unroll") for (int n = 0; n < 2; ++n) _Pragma("unroll") for (int k = 0; k < 2; ++k) dst[n][k] = *(const LAS bf16x8*)(lds + PG8_SB(b, h) + boff + n * 2048 + k * 1024); } while (0)
; #define PG8_WAIT_V(n) asm volatile("s_waitcnt vmcnt(" #n ")" ::: "memory")
; #define PG8_WAIT_L(n) asm volatile("s_waitcnt lgkmcnt(" #n ")" ::: "memory")
; #define PG8_BAR __builtin_amdgcn_s_barrier()
; #define PG8_SCHED __builtin_amdgcn_sched_barrier(0)
; template <class Epi, bool FP8 = false>
; __device__ __forceinline__ void gemm_phase(LAS unsigned char* lds, const Gemm g, const StaticOrder& S_, const Epi& E, const int tid) {
;     ...
;             PG8_WAIT_V(8); PG8_WAIT_L(0); PG8_BAR; PG8_MMA(1, 0, At, B0); PG8_MMA(1, 1, At, B1); PG8_BAR; PG8_SCHED;
;             PG8_LDB(B0, 1, 0); PG8_LDB(B1, 1, 1); PG8_SCHED; PG8_LDA(At, 1, 0); PG8_STAGE(PG8_SA(0, 1), a2 + hstepA, voffA);
;             PG8_WAIT_V(8); PG8_WAIT_L(0); PG8_BAR; PG8_MMA(0, 0, At, B0); PG8_MMA(0, 1, At, B1); PG8_BAR; PG8_SCHED;
;             PG8_LDA(At, 1, 1); PG8_STAGE(PG8_SB(1, 0), b3, voffB); PG8_STAGE(PG8_SB(1, 1), b3 + hstepB, voffB); PG8_STAGE(PG8_SA(1, 0), a3, voffA);
;             PG8_WAIT_V(8); PG8_WAIT_L(0); PG8_BAR; PG8_MMA(1, 0, At, B0); PG8_MMA(1, 1, At, B1); PG8_BAR; PG8_SCHED;
	v_mfma_f32_16x16x32_bf16 v[60:63], v[144:147], v[184:187], v[60:63]
	v_mfma_f32_16x16x32_bf16 v[56:59], v[160:163], v[184:187], v[56:59]
	v_mfma_f32_16x16x32_bf16 v[44:47], v[144:147], v[192:195], v[44:47]
	v_mfma_f32_16x16x32_bf16 v[40:43], v[160:163], v[192:195], v[40:43]
	v_mfma_f32_16x16x32_bf16 v[28:31], v[144:147], v[200:203], v[28:31]
	v_mfma_f32_16x16x32_bf16 v[24:27], v[160:163], v[200:203], v[24:27]
	v_mfma_f32_16x16x32_bf16 v[12:15], v[144:147], v[208:211], v[12:15]
	v_mfma_f32_16x16x32_bf16 v[8:11], v[160:163], v[208:211], v[8:11]
	v_mfma_f32_16x16x32_bf16 v[60:63], v[152:155], v[188:191], v[60:63]
	v_mfma_f32_16x16x32_bf16 v[56:59], v[164:167], v[188:191], v[56:59]
	v_mfma_f32_16x16x32_bf16 v[44:47], v[152:155], v[196:199], v[44:47]
	v_mfma_f32_16x16x32_bf16 v[40:43], v[164:167], v[196:199], v[40:43]
	v_mfma_f32_16x16x32_bf16 v[28:31], v[152:155], v[204:207], v[28:31]
	v_mfma_f32_16x16x32_bf16 v[24:27], v[164:167], v[204:207], v[24:27]
	v_mfma_f32_16x16x32_bf16 v[12:15], v[152:155], v[212:215], v[12:15]
	v_mfma_f32_16x16x32_bf16 v[8:11], v[164:167], v[212:215], v[8:11]
	v_mfma_f32_16x16x32_bf16 v[52:55], v[168:171], v[184:187], v[52:55]
	v_mfma_f32_16x16x32_bf16 v[48:51], v[176:179], v[184:187], v[48:51]
	v_mfma_f32_16x16x32_bf16 v[36:39], v[168:171], v[192:195], v[36:39]
	v_mfma_f32_16x16x32_bf16 v[32:35], v[176:179], v[192:195], v[32:35]
	v_mfma_f32_16x16x32_bf16 v[20:23], v[168:171], v[200:203], v[20:23]
	v_mfma_f32_16x16x32_bf16 v[16:19], v[176:179], v[200:203], v[16:19]
	v_mfma_f32_16x16x32_bf16 v[4:7], v[168:171], v[208:211], v[4:7]
	v_mfma_f32_16x16x32_bf16 v[0:3], v[176:179], v[208:211], v[0:3]
	v_mfma_f32_16x16x32_bf16 v[52:55], v[172:175], v[188:191], v[52:55]
	v_mfma_f32_16x16x32_bf16 v[48:51], v[180:183], v[188:191], v[48:51]
	v_mfma_f32_16x16x32_bf16 v[36:39], v[172:175], v[196:199], v[36:39]
	v_mfma_f32_16x16x32_bf16 v[32:35], v[180:183], v[196:199], v[32:35]
	v_mfma_f32_16x16x32_bf16 v[20:23], v[172:175], v[204:207], v[20:23]
	v_mfma_f32_16x16x32_bf16 v[16:19], v[180:183], v[204:207], v[16:19]
	v_mfma_f32_16x16x32_bf16 v[4:7], v[172:175], v[212:215], v[4:7]
	v_mfma_f32_16x16x32_bf16 v[0:3], v[180:183], v[212:215], v[0:3]
	s_setprio 0
	s_barrier
	s_add_i32 s70, 0, 0x18000
	v_add_u32_e32 v151, s70, v157
	s_add_i32 s71, 0, 0x1c000
	ds_read_b128 v[144:147], v151
	ds_read_b128 v[152:155], v151 offset:1024
	ds_read_b128 v[160:163], v151 offset:2048
	ds_read_b128 v[164:167], v151 offset:3072
	v_add_u32_e32 v151, s71, v157
	ds_read_b128 v[168:171], v151
	ds_read_b128 v[172:175], v151 offset:1024
	ds_read_b128 v[176:179], v151 offset:2048
	ds_read_b128 v[180:183], v151 offset:3072
	s_add_u32 s26, s48, 0x60000
	s_addc_u32 s27, s49, 0
	s_mov_b32 m0, s56
	v_lshl_add_u64 v[224:225], s[26:27], 0, v[128:129]
	ds_read_b128 v[184:187], v150 offset:32768
	ds_read_b128 v[188:191], v150 offset:33792
	ds_read_b128 v[192:195], v150 offset:34816
	ds_read_b128 v[196:199], v150 offset:35840
	ds_read_b128 v[200:203], v150 offset:36864
	ds_read_b128 v[204:207], v150 offset:37888
	ds_read_b128 v[208:211], v150 offset:38912
	ds_read_b128 v[212:215], v150 offset:39936
	global_load_lds_dwordx4 v[224:225], off
	v_lshl_add_u64 v[224:225], s[26:27], 0, v[130:131]
	s_mov_b32 m0, s57
	s_nop 0
	global_load_lds_dwordx4 v[224:225], off
	s_waitcnt vmcnt(8)
	s_waitcnt lgkmcnt(0)
	s_setprio 1
	s_barrier
	v_mfma_f32_16x16x32_bf16 v[124:127], v[144:147], v[184:187], v[124:127]
	v_mfma_f32_16x16x32_bf16 v[120:123], v[160:163], v[184:187], v[120:123]
	v_mfma_f32_16x16x32_bf16 v[108:111], v[144:147], v[192:195], v[108:111]
	v_mfma_f32_16x16x32_bf16 v[104:107], v[160:163], v[192:195], v[104:107]
	v_mfma_f32_16x16x32_bf16 v[92:95], v[144:147], v[200:203], v[92:95]
	v_mfma_f32_16x16x32_bf16 v[88:91], v[160:163], v[200:203], v[88:91]
	v_mfma_f32_16x16x32_bf16 v[76:79], v[144:147], v[208:211], v[76:79]
	v_mfma_f32_16x16x32_bf16 v[72:75], v[160:163], v[208:211], v[72:75]
	v_mfma_f32_16x16x32_bf16 v[124:127], v[152:155], v[188:191], v[124:127]
	v_mfma_f32_16x16x32_bf16 v[120:123], v[164:167], v[188:191], v[120:123]
	v_mfma_f32_16x16x32_bf16 v[108:111], v[152:155], v[196:199], v[108:111]
	v_mfma_f32_16x16x32_bf16 v[104:107], v[164:167], v[196:199], v[104:107]
	v_mfma_f32_16x16x32_bf16 v[92:95], v[152:155], v[204:207], v[92:95]
	v_mfma_f32_16x16x32_bf16 v[88:91], v[164:167], v[204:207], v[88:91]
	v_mfma_f32_16x16x32_bf16 v[76:79], v[152:155], v[212:215], v[76:79]
	v_mfma_f32_16x16x32_bf16 v[72:75], v[164:167], v[212:215], v[72:75]
	v_mfma_f32_16x16x32_bf16 v[116:119], v[168:171], v[184:187], v[116:119]
	v_mfma_f32_16x16x32_bf16 v[112:115], v[176:179], v[184:187], v[112:115]
	v_mfma_f32_16x16x32_bf16 v[100:103], v[168:171], v[192:195], v[100:103]
	v_mfma_f32_16x16x32_bf16 v[96:99], v[176:179], v[192:195], v[96:99]
	v_mfma_f32_16x16x32_bf16 v[84:87], v[168:171], v[200:203], v[84:87]
	v_mfma_f32_16x16x32_bf16 v[80:83], v[176:179], v[200:203], v[80:83]
	v_mfma_f32_16x16x32_bf16 v[68:71], v[168:171], v[208:211], v[68:71]
	v_mfma_f32_16x16x32_bf16 v[64:67], v[176:179], v[208:211], v[64:67]
	v_mfma_f32_16x16x32_bf16 v[116:119], v[172:175], v[188:191], v[116:119]
	v_mfma_f32_16x16x32_bf16 v[112:115], v[180:183], v[188:191], v[112:115]
	v_mfma_f32_16x16x32_bf16 v[100:103], v[172:175], v[196:199], v[100:103]
	v_mfma_f32_16x16x32_bf16 v[96:99], v[180:183], v[196:199], v[96:99]
	v_mfma_f32_16x16x32_bf16 v[84:87], v[172:175], v[204:207], v[84:87]
	v_mfma_f32_16x16x32_bf16 v[80:83], v[180:183], v[204:207], v[80:83]
	v_mfma_f32_16x16x32_bf16 v[68:71], v[172:175], v[212:215], v[68:71]
	v_mfma_f32_16x16x32_bf16 v[64:67], v[180:183], v[212:215], v[64:67]
	s_setprio 0
	s_barrier
; #define PG8_STAGE(bufoff, gbase, voff) do { _Pragma("unroll") for (int _i = 0; _i < 2; ++_i) \
;         __builtin_amdgcn_global_load_lds((const unsigned*)((const char*)(gbase) + (voff)[_i]), (LAS unsigned*)(lds + (bufoff) + ldsw + _i * 8192), 16, 0, 0); } while (0)
; #define PG8_LDA(dst, b, h) do { _Pragma("unroll") for (int m = 0; m < 4; ++m) _Pragma("unroll") for (int k = 0; k < 2; ++k) dst[m][k] = *(const LAS bf16x8*)(lds + PG8_SA(b, h) + aoff + m * 2048 + k * 1024); } while (0)
; #define PG8_WAIT_V(n) asm volatile("s_waitcnt vmcnt(" #n ")" ::: "memory")
; #define PG8_WAIT_L(n) asm volatile("s_waitcnt lgkmcnt(" #n ")" ::: "memory")
; #define PG8_BAR __builtin_amdgcn_s_barrier()
; #define PG8_SCHED __builtin_amdgcn_sched_barrier(0)
; template <class Epi, bool FP8 = false>
; __device__ __forceinline__ void gemm_phase(LAS unsigned char* lds, const Gemm g, const StaticOrder& S_, const Epi& E, const int tid) {
;     ...
;             PG8_LDA(At, 1, 1); PG8_STAGE(PG8_SB(1, 0), b3, voffB); PG8_STAGE(PG8_SB(1, 1), b3 + hstepB, voffB); PG8_STAGE(PG8_SA(1, 0), a3, voffA);
;             PG8_WAIT_V(8); PG8_WAIT_L(0); PG8_BAR; PG8_MMA(1, 0, At, B0); PG8_MMA(1, 1, At, B1); PG8_BAR; PG8_SCHED;
;         }
;         if (wr == 0) PG8_BAR;
	s_add_i32 s26, s70, s53
	v_lshl_add_u64 v[216:217], v[216:217], 0, s[16:17]
	s_mov_b32 m0, s26
	ds_read_b128 v[184:187], v150 offset:49152
	ds_read_b128 v[188:191], v150 offset:50176
	ds_read_b128 v[192:195], v150 offset:51200
	ds_read_b128 v[196:199], v150 offset:52224
	ds_read_b128 v[200:203], v150 offset:53248
	ds_read_b128 v[204:207], v150 offset:54272
	ds_read_b128 v[208:211], v150 offset:55296
	ds_read_b128 v[212:215], v150 offset:56320
	global_load_lds_dwordx4 v[216:217], off
	s_add_i32 m0, s26, 0x2000
	s_add_u32 s26, s46, 0x20080
	v_lshl_add_u64 v[216:217], v[218:219], 0, s[16:17]
	s_addc_u32 s27, s47, 0
	s_add_i32 s46, s71, s53
	global_load_lds_dwordx4 v[216:217], off
	v_lshl_add_u64 v[216:217], s[26:27], 0, v[132:133]
	s_mov_b32 m0, s46
	s_nop 0
	global_load_lds_dwordx4 v[216:217], off
	v_lshl_add_u64 v[216:217], s[26:27], 0, v[134:135]
	s_add_i32 m0, s46, 0x2000
	s_nop 0
	global_load_lds_dwordx4 v[216:217], off
	v_lshl_add_u64 v[216:217], v[220:221], 0, s[16:17]
	s_mov_b32 m0, s59
	s_nop 0
	global_load_lds_dwordx4 v[216:217], off
	v_lshl_add_u64 v[216:217], v[222:223], 0, s[16:17]
	s_mov_b32 m0, s60
	s_nop 0
	global_load_lds_dwordx4 v[216:217], off
	s_waitcnt vmcnt(8)
	s_waitcnt lgkmcnt(0)
	s_setprio 1
	s_barrier
	v_mfma_f32_16x16x32_bf16 v[60:63], v[144:147], v[184:187], v[60:63]
	v_mfma_f32_16x16x32_bf16 v[56:59], v[160:163], v[184:187], v[56:59]
	v_mfma_f32_16x16x32_bf16 v[44:47], v[144:147], v[192:195], v[44:47]
	v_mfma_f32_16x16x32_bf16 v[40:43], v[160:163], v[192:195], v[40:43]
	v_mfma_f32_16x16x32_bf16 v[28:31], v[144:147], v[200:203], v[28:31]
	v_mfma_f32_16x16x32_bf16 v[24:27], v[160:163], v[200:203], v[24:27]
	v_mfma_f32_16x16x32_bf16 v[12:15], v[144:147], v[208:211], v[12:15]
	v_mfma_f32_16x16x32_bf16 v[8:11], v[160:163], v[208:211], v[8:11]
	v_mfma_f32_16x16x32_bf16 v[60:63], v[152:155], v[188:191], v[60:63]
	v_mfma_f32_16x16x32_bf16 v[56:59], v[164:167], v[188:191], v[56:59]
	v_mfma_f32_16x16x32_bf16 v[44:47], v[152:155], v[196:199], v[44:47]
	v_mfma_f32_16x16x32_bf16 v[40:43], v[164:167], v[196:199], v[40:43]
	v_mfma_f32_16x16x32_bf16 v[28:31], v[152:155], v[204:207], v[28:31]
	v_mfma_f32_16x16x32_bf16 v[24:27], v[164:167], v[204:207], v[24:27]
	v_mfma_f32_16x16x32_bf16 v[12:15], v[152:155], v[212:215], v[12:15]
	v_mfma_f32_16x16x32_bf16 v[8:11], v[164:167], v[212:215], v[8:11]
	v_mfma_f32_16x16x32_bf16 v[52:55], v[168:171], v[184:187], v[52:55]
	v_mfma_f32_16x16x32_bf16 v[48:51], v[176:179], v[184:187], v[48:51]
	v_mfma_f32_16x16x32_bf16 v[36:39], v[168:171], v[192:195], v[36:39]
	v_mfma_f32_16x16x32_bf16 v[32:35], v[176:179], v[192:195], v[32:35]
	v_mfma_f32_16x16x32_bf16 v[20:23], v[168:171], v[200:203], v[20:23]
	v_mfma_f32_16x16x32_bf16 v[16:19], v[176:179], v[200:203], v[16:19]
	v_mfma_f32_16x16x32_bf16 v[4:7], v[168:171], v[208:211], v[4:7]
	v_mfma_f32_16x16x32_bf16 v[0:3], v[176:179], v[208:211], v[0:3]
	v_mfma_f32_16x16x32_bf16 v[52:55], v[172:175], v[188:191], v[52:55]
	v_mfma_f32_16x16x32_bf16 v[48:51], v[180:183], v[188:191], v[48:51]
	v_mfma_f32_16x16x32_bf16 v[36:39], v[172:175], v[196:199], v[36:39]
	v_mfma_f32_16x16x32_bf16 v[32:35], v[180:183], v[196:199], v[32:35]
	v_mfma_f32_16x16x32_bf16 v[20:23], v[172:175], v[204:207], v[20:23]
	v_mfma_f32_16x16x32_bf16 v[16:19], v[180:183], v[204:207], v[16:19]
	v_mfma_f32_16x16x32_bf16 v[4:7], v[172:175], v[212:215], v[4:7]
	v_mfma_f32_16x16x32_bf16 v[0:3], v[180:183], v[212:215], v[0:3]
	s_setprio 0
	s_barrier
	s_add_i32 s69, s69, 2
	s_add_u32 s67, s67, 0x100
	s_addc_u32 s68, s68, 0
	s_cmp_gt_u32 s69, 5
	s_mov_b64 s[26:27], s[8:9]
	s_cbranch_scc0 .LBB0_1121
	s_and_b64 vcc, exec, s[18:19]
	s_cbranch_vccz .LBB0_1124
	s_barrier

; #define PG8_STAGE(bufoff, gbase, voff) do { _Pragma("unroll") for (int _i = 0; _i < 2; ++_i) \
;         __builtin_amdgcn_global_load_lds((const unsigned*)((const char*)(gbase) + (voff)[_i]), (LAS unsigned*)(lds + (bufoff) + ldsw + _i * 8192), 16, 0, 0); } while (0)
; #define PG8_LDA(dst, b, h) do { _Pragma("unroll") for (int m = 0; m < 4; ++m) _Pragma("unroll") for (int k = 0; k < 2; ++k) dst[m][k] = *(const LAS bf16x8*)(lds + PG8_SA(b, h) + aoff + m * 2048 + k * 1024); } while (0)
; #define PG8_LDB(dst, b, h) do { _Pragma("unroll") for (int n = 0; n < 2; ++n) _Pragma("unroll") for (int k = 0; k < 2; ++k) dst[n][k] = *(const LAS bf16x8*)(lds + PG8_SB(b, h) + boff + n * 2048 + k * 1024); } while (0)
; #define PG8_WAIT_V(n) asm volatile("s_waitcnt vmcnt(" #n ")" ::: "memory")
; #define PG8_WAIT_L(n) asm volatile("s_waitcnt lgkmcnt(" #n ")" ::: "memory")
; #define PG8_BAR __builtin_amdgcn_s_barrier()
; #define PG8_SCHED __builtin_amdgcn_sched_barrier(0)
; template <class Epi, bool FP8 = false>
; __device__ __forceinline__ void gemm_phase(LAS unsigned char* lds, const Gemm g, const StaticOrder& S_, const Epi& E, const int tid) {
;     ...
;         for (int t = 0; t < nt; t += 2) {
;             const bool last = (t == nt - 2);
;             const char* a1 = cA + (size_t)(t + 1) * kstep;
;             const char* a2 = last ? nA : cA + (size_t)(t + 2) * kstep; const char* b2 = last ? nB : cB + (size_t)(t + 2) * kstep;
;             const char* a3 = a2 + kstep; const char* b3 = b2 + kstep;
;             PG8_LDB(B0, 0, 0); PG8_LDB(B1, 0, 1); PG8_SCHED; PG8_LDA(At, 0, 0); PG8_STAGE(PG8_SA(1, 1), a1 + hstepA, voffA);
;             PG8_WAIT_V(8); PG8_WAIT_L(0); PG8_BAR; PG8_MMA(0, 0, At, B0); PG8_MMA(0, 1, At, B1); PG8_BAR; PG8_SCHED;
;             PG8_LDA(At, 0, 1); PG8_STAGE(PG8_SB(0, 0), b2, voffB); PG8_STAGE(PG8_SB(0, 1), b2 + hstepB, voffB); PG8_STAGE(PG8_SA(0, 0), a2, voffA);
;             PG8_WAIT_V(8); PG8_WAIT_L(0); PG8_BAR; PG8_MMA(1, 0, At, B0); PG8_MMA(1, 1, At, B1); PG8_BAR; PG8_SCHED;
.LBB0_1197:
	ds_read_b128 v[140:143], v152
	ds_read_b128 v[144:147], v152 offset:1024
	ds_read_b128 v[156:159], v152 offset:2048
	ds_read_b128 v[160:163], v152 offset:3072
	ds_read_b128 v[164:167], v153
	ds_read_b128 v[168:171], v153 offset:1024
	ds_read_b128 v[172:175], v153 offset:2048
	ds_read_b128 v[176:179], v153 offset:3072
	s_add_u32 s50, s48, 0xfff80080
	s_addc_u32 s51, s49, -1
	s_cmp_eq_u32 s70, 28
	s_cselect_b32 s53, s23, s51
	s_cselect_b32 s52, s43, s50
	s_cselect_b32 s51, s21, s69
	s_cselect_b32 s50, s66, s68
	v_lshl_add_u64 v[212:213], s[48:49], 0, v[132:133]
	s_add_i32 m0, s47, 0xc000
	ds_read_b128 v[180:183], v154
	ds_read_b128 v[184:187], v154 offset:1024
	ds_read_b128 v[188:191], v154 offset:2048
	ds_read_b128 v[192:195], v154 offset:3072
	ds_read_b128 v[196:199], v154 offset:4096
	ds_read_b128 v[200:203], v154 offset:5120
	ds_read_b128 v[204:207], v154 offset:6144
	ds_read_b128 v[208:211], v154 offset:7168
	global_load_lds_dwordx4 v[212:213], off
	v_lshl_add_u64 v[212:213], s[48:49], 0, v[134:135]
	s_add_i32 m0, s47, 0xe000
	s_nop 0
	global_load_lds_dwordx4 v[212:213], off
	s_waitcnt vmcnt(8)
	s_waitcnt lgkmcnt(0)
	s_setprio 1
	s_barrier
	v_mfma_f32_16x16x32_bf16 v[124:127], v[140:143], v[180:183], v[124:127]
	v_mfma_f32_16x16x32_bf16 v[120:123], v[156:159], v[180:183], v[120:123]
	v_mfma_f32_16x16x32_bf16 v[108:111], v[140:143], v[188:191], v[108:111]
	v_mfma_f32_16x16x32_bf16 v[104:107], v[156:159], v[188:191], v[104:107]
	v_mfma_f32_16x16x32_bf16 v[92:95], v[140:143], v[196:199], v[92:95]
	v_mfma_f32_16x16x32_bf16 v[88:91], v[156:159], v[196:199], v[88:91]
	v_mfma_f32_16x16x32_bf16 v[76:79], v[140:143], v[204:207], v[76:79]
	v_mfma_f32_16x16x32_bf16 v[72:75], v[156:159], v[204:207], v[72:75]
	v_mfma_f32_16x16x32_bf16 v[124:127], v[144:147], v[184:187], v[124:127]
	v_mfma_f32_16x16x32_bf16 v[120:123], v[160:163], v[184:187], v[120:123]
	v_mfma_f32_16x16x32_bf16 v[108:111], v[144:147], v[192:195], v[108:111]
	v_mfma_f32_16x16x32_bf16 v[104:107], v[160:163], v[192:195], v[104:107]
	v_mfma_f32_16x16x32_bf16 v[92:95], v[144:147], v[200:203], v[92:95]
	v_mfma_f32_16x16x32_bf16 v[88:91], v[160:163], v[200:203], v[88:91]
	v_mfma_f32_16x16x32_bf16 v[76:79], v[144:147], v[208:211], v[76:79]
	v_mfma_f32_16x16x32_bf16 v[72:75], v[160:163], v[208:211], v[72:75]
	v_mfma_f32_16x16x32_bf16 v[116:119], v[164:167], v[180:183], v[116:119]
	v_mfma_f32_16x16x32_bf16 v[112:115], v[172:175], v[180:183], v[112:115]
	v_mfma_f32_16x16x32_bf16 v[100:103], v[164:167], v[188:191], v[100:103]
	v_mfma_f32_16x16x32_bf16 v[96:99], v[172:175], v[188:191], v[96:99]
	v_mfma_f32_16x16x32_bf16 v[84:87], v[164:167], v[196:199], v[84:87]
	v_mfma_f32_16x16x32_bf16 v[80:83], v[172:175], v[196:199], v[80:83]
	v_mfma_f32_16x16x32_bf16 v[68:71], v[164:167], v[204:207], v[68:71]
	v_mfma_f32_16x16x32_bf16 v[64:67], v[172:175], v[204:207], v[64:67]
	v_mfma_f32_16x16x32_bf16 v[116:119], v[168:171], v[184:187], v[116:119]
	v_mfma_f32_16x16x32_bf16 v[112:115], v[176:179], v[184:187], v[112:115]
	v_mfma_f32_16x16x32_bf16 v[100:103], v[168:171], v[192:195], v[100:103]
	v_mfma_f32_16x16x32_bf16 v[96:99], v[176:179], v[192:195], v[96:99]
	v_mfma_f32_16x16x32_bf16 v[84:87], v[168:171], v[200:203], v[84:87]
	v_mfma_f32_16x16x32_bf16 v[80:83], v[176:179], v[200:203], v[80:83]
	v_mfma_f32_16x16x32_bf16 v[68:71], v[168:171], v[208:211], v[68:71]
	v_mfma_f32_16x16x32_bf16 v[64:67], v[176:179], v[208:211], v[64:67]
	s_setprio 0
	s_barrier
	s_add_i32 s71, s63, s56
	v_lshl_add_u64 v[212:213], s[50:51], 0, v[128:129]
	s_mov_b32 m0, s71
	ds_read_b128 v[180:183], v154 offset:16384
	ds_read_b128 v[184:187], v154 offset:17408
	ds_read_b128 v[188:191], v154 offset:18432
	ds_read_b128 v[192:195], v154 offset:19456
	ds_read_b128 v[196:199], v154 offset:20480
	ds_read_b128 v[200:203], v154 offset:21504
	ds_read_b128 v[204:207], v154 offset:22528
	ds_read_b128 v[208:211], v154 offset:23552
	global_load_lds_dwordx4 v[212:213], off
	s_add_i32 m0, s71, 0x2000
	s_add_u32 s72, s50, 0x80000
	v_lshl_add_u64 v[214:215], s[50:51], 0, v[130:131]
	s_addc_u32 s73, s51, 0
	s_add_i32 s71, s67, s56
	global_load_lds_dwordx4 v[214:215], off
	v_lshl_add_u64 v[216:217], s[72:73], 0, v[128:129]
	s_mov_b32 m0, s71
	v_lshl_add_u64 v[218:219], s[52:53], 0, v[130:131]
	global_load_lds_dwordx4 v[216:217], off
	v_lshl_add_u64 v[216:217], s[72:73], 0, v[130:131]
	s_add_i32 m0, s71, 0x2000
	s_nop 0
	global_load_lds_dwordx4 v[216:217], off
	v_lshl_add_u64 v[216:217], s[52:53], 0, v[128:129]
	s_mov_b32 m0, s47
	s_nop 0
	global_load_lds_dwordx4 v[216:217], off
	s_mov_b32 m0, s57
	s_nop 0
	global_load_lds_dwordx4 v[218:219], off
	s_waitcnt vmcnt(8)
	s_waitcnt lgkmcnt(0)
	s_setprio 1
	s_barrier
; #define PG8_STAGE(bufoff, gbase, voff) do { _Pragma("unroll") for (int _i = 0; _i < 2; ++_i) \
;         __builtin_amdgcn_global_load_lds((const unsigned*)((const char*)(gbase) + (voff)[_i]), (LAS unsigned*)(lds + (bufoff) + ldsw + _i * 8192), 16, 0, 0); } while (0)
; #define PG8_LDA(dst, b, h) do { _Pragma("unroll") for (int m = 0; m < 4; ++m) _Pragma("unroll") for (int k = 0; k < 2; ++k) dst[m][k] = *(const LAS bf16x8*)(lds + PG8_SA(b, h) + aoff + m * 2048 + k * 1024); } while (0)
; #define PG8_LDB(dst, b, h) do { _Pragma("unroll") for (int n = 0; n < 2; ++n) _Pragma("unroll") for (int k = 0; k < 2; ++k) dst[n][k] = *(const LAS bf16x8*)(lds + PG8_SB(b, h) + boff + n * 2048 + k * 1024); } while (0)
; #define PG8_WAIT_V(n) asm volatile("s_waitcnt vmcnt(" #n ")" ::: "memory")
; #define PG8_WAIT_L(n) asm volatile("s_waitcnt lgkmcnt(" #n ")" ::: "memory")
; #define PG8_BAR __builtin_amdgcn_s_barrier()
; #define PG8_SCHED __builtin_amdgcn_sched_barrier(0)
; template <class Epi, bool FP8 = false>
; __device__ __forceinline__ void gemm_phase(LAS unsigned char* lds, const Gemm g, const StaticOrder& S_, const Epi& E, const int tid) {
;     ...
;             PG8_WAIT_V(8); PG8_WAIT_L(0); PG8_BAR; PG8_MMA(1, 0, At, B0); PG8_MMA(1, 1, At, B1); PG8_BAR; PG8_SCHED;
;             PG8_LDB(B0, 1, 0); PG8_LDB(B1, 1, 1); PG8_SCHED; PG8_LDA(At, 1, 0); PG8_STAGE(PG8_SA(0, 1), a2 + hstepA, voffA);
;             PG8_WAIT_V(8); PG8_WAIT_L(0); PG8_BAR; PG8_MMA(0, 0, At, B0); PG8_MMA(0, 1, At, B1); PG8_BAR; PG8_SCHED;
;             PG8_LDA(At, 1, 1); PG8_STAGE(PG8_SB(1, 0), b3, voffB); PG8_STAGE(PG8_SB(1, 1), b3 + hstepB, voffB); PG8_STAGE(PG8_SA(1, 0), a3, voffA);
;             PG8_WAIT_V(8); PG8_WAIT_L(0); PG8_BAR; PG8_MMA(1, 0, At, B0); PG8_MMA(1, 1, At, B1); PG8_BAR; PG8_SCHED;
	v_mfma_f32_16x16x32_bf16 v[60:63], v[140:143], v[180:183], v[60:63]
	v_mfma_f32_16x16x32_bf16 v[56:59], v[156:159], v[180:183], v[56:59]
	v_mfma_f32_16x16x32_bf16 v[44:47], v[140:143], v[188:191], v[44:47]
	v_mfma_f32_16x16x32_bf16 v[40:43], v[156:159], v[188:191], v[40:43]
	v_mfma_f32_16x16x32_bf16 v[28:31], v[140:143], v[196:199], v[28:31]
	v_mfma_f32_16x16x32_bf16 v[24:27], v[156:159], v[196:199], v[24:27]
	v_mfma_f32_16x16x32_bf16 v[12:15], v[140:143], v[204:207], v[12:15]
	v_mfma_f32_16x16x32_bf16 v[8:11], v[156:159], v[204:207], v[8:11]
	v_mfma_f32_16x16x32_bf16 v[60:63], v[144:147], v[184:187], v[60:63]
	v_mfma_f32_16x16x32_bf16 v[56:59], v[160:163], v[184:187], v[56:59]
	v_mfma_f32_16x16x32_bf16 v[44:47], v[144:147], v[192:195], v[44:47]
	v_mfma_f32_16x16x32_bf16 v[40:43], v[160:163], v[192:195], v[40:43]
	v_mfma_f32_16x16x32_bf16 v[28:31], v[144:147], v[200:203], v[28:31]
	v_mfma_f32_16x16x32_bf16 v[24:27], v[160:163], v[200:203], v[24:27]
	v_mfma_f32_16x16x32_bf16 v[12:15], v[144:147], v[208:211], v[12:15]
	v_mfma_f32_16x16x32_bf16 v[8:11], v[160:163], v[208:211], v[8:11]
	v_mfma_f32_16x16x32_bf16 v[52:55], v[164:167], v[180:183], v[52:55]
	v_mfma_f32_16x16x32_bf16 v[48:51], v[172:175], v[180:183], v[48:51]
	v_mfma_f32_16x16x32_bf16 v[36:39], v[164:167], v[188:191], v[36:39]
	v_mfma_f32_16x16x32_bf16 v[32:35], v[172:175], v[188:191], v[32:35]
	v_mfma_f32_16x16x32_bf16 v[20:23], v[164:167], v[196:199], v[20:23]
	v_mfma_f32_16x16x32_bf16 v[16:19], v[172:175], v[196:199], v[16:19]
	v_mfma_f32_16x16x32_bf16 v[4:7], v[164:167], v[204:207], v[4:7]
	v_mfma_f32_16x16x32_bf16 v[0:3], v[172:175], v[204:207], v[0:3]
	v_mfma_f32_16x16x32_bf16 v[52:55], v[168:171], v[184:187], v[52:55]
	v_mfma_f32_16x16x32_bf16 v[48:51], v[176:179], v[184:187], v[48:51]
	v_mfma_f32_16x16x32_bf16 v[36:39], v[168:171], v[192:195], v[36:39]
	v_mfma_f32_16x16x32_bf16 v[32:35], v[176:179], v[192:195], v[32:35]
	v_mfma_f32_16x16x32_bf16 v[20:23], v[168:171], v[200:203], v[20:23]
	v_mfma_f32_16x16x32_bf16 v[16:19], v[176:179], v[200:203], v[16:19]
	v_mfma_f32_16x16x32_bf16 v[4:7], v[168:171], v[208:211], v[4:7]
	v_mfma_f32_16x16x32_bf16 v[0:3], v[176:179], v[208:211], v[0:3]
	s_setprio 0
	s_barrier
	s_add_i32 s71, 0, 0x18000
	v_add_u32_e32 v155, s71, v150
	s_add_i32 s72, 0, 0x1c000
	ds_read_b128 v[140:143], v155
	ds_read_b128 v[144:147], v155 offset:1024
	ds_read_b128 v[156:159], v155 offset:2048
	ds_read_b128 v[160:163], v155 offset:3072
	v_add_u32_e32 v155, s72, v150
	ds_read_b128 v[164:167], v155
	ds_read_b128 v[168:171], v155 offset:1024
	ds_read_b128 v[172:175], v155 offset:2048
	ds_read_b128 v[176:179], v155 offset:3072
	s_add_u32 s52, s52, 0x80000
	s_addc_u32 s53, s53, 0
	s_mov_b32 m0, s58
	v_lshl_add_u64 v[220:221], s[52:53], 0, v[128:129]
	ds_read_b128 v[180:183], v154 offset:32768
	ds_read_b128 v[184:187], v154 offset:33792
	ds_read_b128 v[188:191], v154 offset:34816
	ds_read_b128 v[192:195], v154 offset:35840
	ds_read_b128 v[196:199], v154 offset:36864
	ds_read_b128 v[200:203], v154 offset:37888
	ds_read_b128 v[204:207], v154 offset:38912
	ds_read_b128 v[208:211], v154 offset:39936
	global_load_lds_dwordx4 v[220:221], off
	v_lshl_add_u64 v[220:221], s[52:53], 0, v[130:131]
	s_mov_b32 m0, s59
	s_nop 0
	global_load_lds_dwordx4 v[220:221], off
	s_waitcnt vmcnt(8)
	s_waitcnt lgkmcnt(0)
	s_setprio 1
	s_barrier
	v_mfma_f32_16x16x32_bf16 v[124:127], v[140:143], v[180:183], v[124:127]
	v_mfma_f32_16x16x32_bf16 v[120:123], v[156:159], v[180:183], v[120:123]
	v_mfma_f32_16x16x32_bf16 v[108:111], v[140:143], v[188:191], v[108:111]
	v_mfma_f32_16x16x32_bf16 v[104:107], v[156:159], v[188:191], v[104:107]
	v_mfma_f32_16x16x32_bf16 v[92:95], v[140:143], v[196:199], v[92:95]
	v_mfma_f32_16x16x32_bf16 v[88:91], v[156:159], v[196:199], v[88:91]
	v_mfma_f32_16x16x32_bf16 v[76:79], v[140:143], v[204:207], v[76:79]
	v_mfma_f32_16x16x32_bf16 v[72:75], v[156:159], v[204:207], v[72:75]
	v_mfma_f32_16x16x32_bf16 v[124:127], v[144:147], v[184:187], v[124:127]
	v_mfma_f32_16x16x32_bf16 v[120:123], v[160:163], v[184:187], v[120:123]
	v_mfma_f32_16x16x32_bf16 v[108:111], v[144:147], v[192:195], v[108:111]
	v_mfma_f32_16x16x32_bf16 v[104:107], v[160:163], v[192:195], v[104:107]
	v_mfma_f32_16x16x32_bf16 v[92:95], v[144:147], v[200:203], v[92:95]
	v_mfma_f32_16x16x32_bf16 v[88:91], v[160:163], v[200:203], v[88:91]
	v_mfma_f32_16x16x32_bf16 v[76:79], v[144:147], v[208:211], v[76:79]
	v_mfma_f32_16x16x32_bf16 v[72:75], v[160:163], v[208:211], v[72:75]
	v_mfma_f32_16x16x32_bf16 v[116:119], v[164:167], v[180:183], v[116:119]
	v_mfma_f32_16x16x32_bf16 v[112:115], v[172:175], v[180:183], v[112:115]
	v_mfma_f32_16x16x32_bf16 v[100:103], v[164:167], v[188:191], v[100:103]
	v_mfma_f32_16x16x32_bf16 v[96:99], v[172:175], v[188:191], v[96:99]
	v_mfma_f32_16x16x32_bf16 v[84:87], v[164:167], v[196:199], v[84:87]
	v_mfma_f32_16x16x32_bf16 v[80:83], v[172:175], v[196:199], v[80:83]
	v_mfma_f32_16x16x32_bf16 v[68:71], v[164:167], v[204:207], v[68:71]
	v_mfma_f32_16x16x32_bf16 v[64:67], v[172:175], v[204:207], v[64:67]
	v_mfma_f32_16x16x32_bf16 v[116:119], v[168:171], v[184:187], v[116:119]
	v_mfma_f32_16x16x32_bf16 v[112:115], v[176:179], v[184:187], v[112:115]
	v_mfma_f32_16x16x32_bf16 v[100:103], v[168:171], v[192:195], v[100:103]
	v_mfma_f32_16x16x32_bf16 v[96:99], v[176:179], v[192:195], v[96:99]
	v_mfma_f32_16x16x32_bf16 v[84:87], v[168:171], v[200:203], v[84:87]
	v_mfma_f32_16x16x32_bf16 v[80:83], v[176:179], v[200:203], v[80:83]
	v_mfma_f32_16x16x32_bf16 v[68:71], v[168:171], v[208:211], v[68:71]
	v_mfma_f32_16x16x32_bf16 v[64:67], v[176:179], v[208:211], v[64:67]
	s_setprio 0
	s_barrier
; #define PG8_STAGE(bufoff, gbase, voff) do { _Pragma("unroll") for (int _i = 0; _i < 2; ++_i) \
;         __builtin_amdgcn_global_load_lds((const unsigned*)((const char*)(gbase) + (voff)[_i]), (LAS unsigned*)(lds + (bufoff) + ldsw + _i * 8192), 16, 0, 0); } while (0)
; #define PG8_LDA(dst, b, h) do { _Pragma("unroll") for (int m = 0; m < 4; ++m) _Pragma("unroll") for (int k = 0; k < 2; ++k) dst[m][k] = *(const LAS bf16x8*)(lds + PG8_SA(b, h) + aoff + m * 2048 + k * 1024); } while (0)
; #define PG8_WAIT_V(n) asm volatile("s_waitcnt vmcnt(" #n ")" ::: "memory")
; #define PG8_WAIT_L(n) asm volatile("s_waitcnt lgkmcnt(" #n ")" ::: "memory")
; #define PG8_BAR __builtin_amdgcn_s_barrier()
; #define PG8_SCHED __builtin_amdgcn_sched_barrier(0)
; template <class Epi, bool FP8 = false>
; __device__ __forceinline__ void gemm_phase(LAS unsigned char* lds, const Gemm g, const StaticOrder& S_, const Epi& E, const int tid) {
;     ...
;             PG8_LDA(At, 1, 1); PG8_STAGE(PG8_SB(1, 0), b3, voffB); PG8_STAGE(PG8_SB(1, 1), b3 + hstepB, voffB); PG8_STAGE(PG8_SA(1, 0), a3, voffA);
;             PG8_WAIT_V(8); PG8_WAIT_L(0); PG8_BAR; PG8_MMA(1, 0, At, B0); PG8_MMA(1, 1, At, B1); PG8_BAR; PG8_SCHED;
;         }
;         if (wr == 0) PG8_BAR;
	s_add_i32 s52, s71, s56
	v_lshl_add_u64 v[212:213], v[212:213], 0, s[14:15]
	s_mov_b32 m0, s52
	ds_read_b128 v[180:183], v154 offset:49152
	ds_read_b128 v[184:187], v154 offset:50176
	ds_read_b128 v[188:191], v154 offset:51200
	ds_read_b128 v[192:195], v154 offset:52224
	ds_read_b128 v[196:199], v154 offset:53248
	ds_read_b128 v[200:203], v154 offset:54272
	ds_read_b128 v[204:207], v154 offset:55296
	ds_read_b128 v[208:211], v154 offset:56320
	global_load_lds_dwordx4 v[212:213], off
	s_add_i32 m0, s52, 0x2000
	s_add_u32 s50, s50, 0x80080
	v_lshl_add_u64 v[212:213], v[214:215], 0, s[14:15]
	s_addc_u32 s51, s51, 0
	s_add_i32 s52, s72, s56
	global_load_lds_dwordx4 v[212:213], off
	v_lshl_add_u64 v[212:213], s[50:51], 0, v[128:129]
	s_mov_b32 m0, s52
	s_nop 0
	global_load_lds_dwordx4 v[212:213], off
	v_lshl_add_u64 v[212:213], s[50:51], 0, v[130:131]
	s_add_i32 m0, s52, 0x2000
	s_nop 0
	global_load_lds_dwordx4 v[212:213], off
	v_lshl_add_u64 v[212:213], v[216:217], 0, s[14:15]
	s_mov_b32 m0, s61
	s_nop 0
	global_load_lds_dwordx4 v[212:213], off
	v_lshl_add_u64 v[212:213], v[218:219], 0, s[14:15]
	s_mov_b32 m0, s62
	s_nop 0
	global_load_lds_dwordx4 v[212:213], off
	s_waitcnt vmcnt(8)
	s_waitcnt lgkmcnt(0)
	s_setprio 1
	s_barrier
	v_mfma_f32_16x16x32_bf16 v[60:63], v[140:143], v[180:183], v[60:63]
	v_mfma_f32_16x16x32_bf16 v[56:59], v[156:159], v[180:183], v[56:59]
	v_mfma_f32_16x16x32_bf16 v[44:47], v[140:143], v[188:191], v[44:47]
	v_mfma_f32_16x16x32_bf16 v[40:43], v[156:159], v[188:191], v[40:43]
	v_mfma_f32_16x16x32_bf16 v[28:31], v[140:143], v[196:199], v[28:31]
	v_mfma_f32_16x16x32_bf16 v[24:27], v[156:159], v[196:199], v[24:27]
	v_mfma_f32_16x16x32_bf16 v[12:15], v[140:143], v[204:207], v[12:15]
	v_mfma_f32_16x16x32_bf16 v[8:11], v[156:159], v[204:207], v[8:11]
	v_mfma_f32_16x16x32_bf16 v[60:63], v[144:147], v[184:187], v[60:63]
	v_mfma_f32_16x16x32_bf16 v[56:59], v[160:163], v[184:187], v[56:59]
	v_mfma_f32_16x16x32_bf16 v[44:47], v[144:147], v[192:195], v[44:47]
	v_mfma_f32_16x16x32_bf16 v[40:43], v[160:163], v[192:195], v[40:43]
	v_mfma_f32_16x16x32_bf16 v[28:31], v[144:147], v[200:203], v[28:31]
	v_mfma_f32_16x16x32_bf16 v[24:27], v[160:163], v[200:203], v[24:27]
	v_mfma_f32_16x16x32_bf16 v[12:15], v[144:147], v[208:211], v[12:15]
	v_mfma_f32_16x16x32_bf16 v[8:11], v[160:163], v[208:211], v[8:11]
	v_mfma_f32_16x16x32_bf16 v[52:55], v[164:167], v[180:183], v[52:55]
	v_mfma_f32_16x16x32_bf16 v[48:51], v[172:175], v[180:183], v[48:51]
	v_mfma_f32_16x16x32_bf16 v[36:39], v[164:167], v[188:191], v[36:39]
	v_mfma_f32_16x16x32_bf16 v[32:35], v[172:175], v[188:191], v[32:35]
	v_mfma_f32_16x16x32_bf16 v[20:23], v[164:167], v[196:199], v[20:23]
	v_mfma_f32_16x16x32_bf16 v[16:19], v[172:175], v[196:199], v[16:19]
	v_mfma_f32_16x16x32_bf16 v[4:7], v[164:167], v[204:207], v[4:7]
	v_mfma_f32_16x16x32_bf16 v[0:3], v[172:175], v[204:207], v[0:3]
	v_mfma_f32_16x16x32_bf16 v[52:55], v[168:171], v[184:187], v[52:55]
	v_mfma_f32_16x16x32_bf16 v[48:51], v[176:179], v[184:187], v[48:51]
	v_mfma_f32_16x16x32_bf16 v[36:39], v[168:171], v[192:195], v[36:39]
	v_mfma_f32_16x16x32_bf16 v[32:35], v[176:179], v[192:195], v[32:35]
	v_mfma_f32_16x16x32_bf16 v[20:23], v[168:171], v[200:203], v[20:23]
	v_mfma_f32_16x16x32_bf16 v[16:19], v[176:179], v[200:203], v[16:19]
	v_mfma_f32_16x16x32_bf16 v[4:7], v[168:171], v[208:211], v[4:7]
	v_mfma_f32_16x16x32_bf16 v[0:3], v[176:179], v[208:211], v[0:3]
	s_setprio 0
	s_barrier
	s_add_i32 s70, s70, 2
	s_add_u32 s48, s48, 0x100
	s_addc_u32 s49, s49, 0
	s_add_u32 s68, s68, 0x100
	s_addc_u32 s69, s69, 0
	s_cmp_gt_u32 s70, 29
	s_cbranch_scc0 .LBB0_1197
	s_and_b64 vcc, exec, s[16:17]
	s_cbranch_vccz .LBB0_1200
	s_barrier

; #define PG8_STAGE(bufoff, gbase, voff) do { _Pragma("unroll") for (int _i = 0; _i < 2; ++_i) \
;         __builtin_amdgcn_global_load_lds((const unsigned*)((const char*)(gbase) + (voff)[_i]), (LAS unsigned*)(lds + (bufoff) + ldsw + _i * 8192), 16, 0, 0); } while (0)
; #define PG8_LDA(dst, b, h) do { _Pragma("unroll") for (int m = 0; m < 4; ++m) _Pragma("unroll") for (int k = 0; k < 2; ++k) dst[m][k] = *(const LAS bf16x8*)(lds + PG8_SA(b, h) + aoff + m * 2048 + k * 1024); } while (0)
; #define PG8_LDB(dst, b, h) do { _Pragma("unroll") for (int n = 0; n < 2; ++n) _Pragma("unroll") for (int k = 0; k < 2; ++k) dst[n][k] = *(const LAS bf16x8*)(lds + PG8_SB(b, h) + boff + n * 2048 + k * 1024); } while (0)
; #define PG8_WAIT_V(n) asm volatile("s_waitcnt vmcnt(" #n ")" ::: "memory")
; #define PG8_WAIT_L(n) asm volatile("s_waitcnt lgkmcnt(" #n ")" ::: "memory")
; #define PG8_BAR __builtin_amdgcn_s_barrier()
; #define PG8_SCHED __builtin_amdgcn_sched_barrier(0)
; template <class Epi, bool FP8 = false>
; __device__ __forceinline__ void gemm_phase(LAS unsigned char* lds, const Gemm g, const StaticOrder& S_, const Epi& E, const int tid) {
;     ...
;             PG8_LDB(B0, 0, 0); PG8_LDB(B1, 0, 1); PG8_SCHED; PG8_LDA(At, 0, 0); PG8_STAGE(PG8_SA(1, 1), a1 + hstepA, voffA);
;             PG8_WAIT_V(8); PG8_WAIT_L(0); PG8_BAR; PG8_MMA(0, 0, At, B0); PG8_MMA(0, 1, At, B1); PG8_BAR; PG8_SCHED;
;             PG8_LDA(At, 0, 1); PG8_STAGE(PG8_SB(0, 0), b2, voffB); PG8_STAGE(PG8_SB(0, 1), b2 + hstepB, voffB); PG8_STAGE(PG8_SA(0, 0), a2, voffA);
;             PG8_WAIT_V(8); PG8_WAIT_L(0); PG8_BAR; PG8_MMA(1, 0, At, B0); PG8_MMA(1, 1, At, B1); PG8_BAR; PG8_SCHED;
.LBB0_1340:
	ds_read_b128 v[150:153], v147
	ds_read_b128 v[154:157], v147 offset:1024
	ds_read_b128 v[158:161], v147 offset:2048
	ds_read_b128 v[162:165], v147 offset:3072
	ds_read_b128 v[166:169], v148
	ds_read_b128 v[170:173], v148 offset:1024
	ds_read_b128 v[174:177], v148 offset:2048
	ds_read_b128 v[178:181], v148 offset:3072
	s_add_u32 s42, s30, 0xfff80080
	s_addc_u32 s43, s31, -1
	s_cmp_eq_u32 s69, 28
	s_cselect_b32 s47, s23, s43
	s_cselect_b32 s46, s63, s42
	s_cselect_b32 s43, s21, s68
	s_cselect_b32 s42, s66, s67
	v_lshl_add_u64 v[214:215], s[30:31], 0, v[136:137]
	s_add_i32 m0, s29, 0xc000
	ds_read_b128 v[182:185], v149
	ds_read_b128 v[186:189], v149 offset:1024
	ds_read_b128 v[190:193], v149 offset:2048
	ds_read_b128 v[194:197], v149 offset:3072
	ds_read_b128 v[198:201], v149 offset:4096
	ds_read_b128 v[202:205], v149 offset:5120
	ds_read_b128 v[206:209], v149 offset:6144
	ds_read_b128 v[210:213], v149 offset:7168
	global_load_lds_dwordx4 v[214:215], off
	v_lshl_add_u64 v[214:215], s[30:31], 0, v[138:139]
	s_add_i32 m0, s29, 0xe000
	s_nop 0
	global_load_lds_dwordx4 v[214:215], off
	s_waitcnt vmcnt(8)
	s_waitcnt lgkmcnt(0)
	s_setprio 1
	s_barrier
	v_mfma_f32_16x16x32_bf16 v[124:127], v[150:153], v[182:185], v[124:127]
	v_mfma_f32_16x16x32_bf16 v[120:123], v[158:161], v[182:185], v[120:123]
	v_mfma_f32_16x16x32_bf16 v[108:111], v[150:153], v[190:193], v[108:111]
	v_mfma_f32_16x16x32_bf16 v[104:107], v[158:161], v[190:193], v[104:107]
	v_mfma_f32_16x16x32_bf16 v[92:95], v[150:153], v[198:201], v[92:95]
	v_mfma_f32_16x16x32_bf16 v[88:91], v[158:161], v[198:201], v[88:91]
	v_mfma_f32_16x16x32_bf16 v[76:79], v[150:153], v[206:209], v[76:79]
	v_mfma_f32_16x16x32_bf16 v[72:75], v[158:161], v[206:209], v[72:75]
	v_mfma_f32_16x16x32_bf16 v[124:127], v[154:157], v[186:189], v[124:127]
	v_mfma_f32_16x16x32_bf16 v[120:123], v[162:165], v[186:189], v[120:123]
	v_mfma_f32_16x16x32_bf16 v[108:111], v[154:157], v[194:197], v[108:111]
	v_mfma_f32_16x16x32_bf16 v[104:107], v[162:165], v[194:197], v[104:107]
	v_mfma_f32_16x16x32_bf16 v[92:95], v[154:157], v[202:205], v[92:95]
	v_mfma_f32_16x16x32_bf16 v[88:91], v[162:165], v[202:205], v[88:91]
	v_mfma_f32_16x16x32_bf16 v[76:79], v[154:157], v[210:213], v[76:79]
	v_mfma_f32_16x16x32_bf16 v[72:75], v[162:165], v[210:213], v[72:75]
	v_mfma_f32_16x16x32_bf16 v[116:119], v[166:169], v[182:185], v[116:119]
	v_mfma_f32_16x16x32_bf16 v[112:115], v[174:177], v[182:185], v[112:115]
	v_mfma_f32_16x16x32_bf16 v[100:103], v[166:169], v[190:193], v[100:103]
	v_mfma_f32_16x16x32_bf16 v[96:99], v[174:177], v[190:193], v[96:99]
	v_mfma_f32_16x16x32_bf16 v[84:87], v[166:169], v[198:201], v[84:87]
	v_mfma_f32_16x16x32_bf16 v[80:83], v[174:177], v[198:201], v[80:83]
	v_mfma_f32_16x16x32_bf16 v[68:71], v[166:169], v[206:209], v[68:71]
	v_mfma_f32_16x16x32_bf16 v[64:67], v[174:177], v[206:209], v[64:67]
	v_mfma_f32_16x16x32_bf16 v[116:119], v[170:173], v[186:189], v[116:119]
	v_mfma_f32_16x16x32_bf16 v[112:115], v[178:181], v[186:189], v[112:115]
	v_mfma_f32_16x16x32_bf16 v[100:103], v[170:173], v[194:197], v[100:103]
	v_mfma_f32_16x16x32_bf16 v[96:99], v[178:181], v[194:197], v[96:99]
	v_mfma_f32_16x16x32_bf16 v[84:87], v[170:173], v[202:205], v[84:87]
	v_mfma_f32_16x16x32_bf16 v[80:83], v[178:181], v[202:205], v[80:83]
	v_mfma_f32_16x16x32_bf16 v[68:71], v[170:173], v[210:213], v[68:71]
	v_mfma_f32_16x16x32_bf16 v[64:67], v[178:181], v[210:213], v[64:67]
	s_setprio 0
	s_barrier
	s_add_i32 s70, s59, s50
	v_lshl_add_u64 v[214:215], s[42:43], 0, v[128:129]
	s_mov_b32 m0, s70
	ds_read_b128 v[182:185], v149 offset:16384
	ds_read_b128 v[186:189], v149 offset:17408
	ds_read_b128 v[190:193], v149 offset:18432
	ds_read_b128 v[194:197], v149 offset:19456
	ds_read_b128 v[198:201], v149 offset:20480
	ds_read_b128 v[202:205], v149 offset:21504
	ds_read_b128 v[206:209], v149 offset:22528
	ds_read_b128 v[210:213], v149 offset:23552
	global_load_lds_dwordx4 v[214:215], off
	s_add_i32 m0, s70, 0x2000
	s_add_u32 s70, s42, 0x80000
	v_lshl_add_u64 v[216:217], s[42:43], 0, v[130:131]
	s_addc_u32 s71, s43, 0
	s_add_i32 s72, s60, s50
	global_load_lds_dwordx4 v[216:217], off
	v_lshl_add_u64 v[218:219], s[70:71], 0, v[128:129]
	s_mov_b32 m0, s72
	v_lshl_add_u64 v[220:221], s[46:47], 0, v[132:133]
	global_load_lds_dwordx4 v[218:219], off
	v_lshl_add_u64 v[218:219], s[70:71], 0, v[130:131]
	s_add_i32 m0, s72, 0x2000
	s_nop 0
	global_load_lds_dwordx4 v[218:219], off
	v_lshl_add_u64 v[218:219], s[46:47], 0, v[134:135]
	s_mov_b32 m0, s29
	s_nop 0
	global_load_lds_dwordx4 v[218:219], off
	s_mov_b32 m0, s53
	s_nop 0
	global_load_lds_dwordx4 v[220:221], off
	s_waitcnt vmcnt(8)
	s_waitcnt lgkmcnt(0)
	s_setprio 1
	s_barrier
; #define PG8_STAGE(bufoff, gbase, voff) do { _Pragma("unroll") for (int _i = 0; _i < 2; ++_i) \
;         __builtin_amdgcn_global_load_lds((const unsigned*)((const char*)(gbase) + (voff)[_i]), (LAS unsigned*)(lds + (bufoff) + ldsw + _i * 8192), 16, 0, 0); } while (0)
; #define PG8_LDA(dst, b, h) do { _Pragma("unroll") for (int m = 0; m < 4; ++m) _Pragma("unroll") for (int k = 0; k < 2; ++k) dst[m][k] = *(const LAS bf16x8*)(lds + PG8_SA(b, h) + aoff + m * 2048 + k * 1024); } while (0)
; #define PG8_LDB(dst, b, h) do { _Pragma("unroll") for (int n = 0; n < 2; ++n) _Pragma("unroll") for (int k = 0; k < 2; ++k) dst[n][k] = *(const LAS bf16x8*)(lds + PG8_SB(b, h) + boff + n * 2048 + k * 1024); } while (0)
; #define PG8_WAIT_V(n) asm volatile("s_waitcnt vmcnt(" #n ")" ::: "memory")
; #define PG8_WAIT_L(n) asm volatile("s_waitcnt lgkmcnt(" #n ")" ::: "memory")
; #define PG8_BAR __builtin_amdgcn_s_barrier()
; #define PG8_SCHED __builtin_amdgcn_sched_barrier(0)
; template <class Epi, bool FP8 = false>
; __device__ __forceinline__ void gemm_phase(LAS unsigned char* lds, const Gemm g, const StaticOrder& S_, const Epi& E, const int tid) {
;     ...
;             PG8_WAIT_V(8); PG8_WAIT_L(0); PG8_BAR; PG8_MMA(1, 0, At, B0); PG8_MMA(1, 1, At, B1); PG8_BAR; PG8_SCHED;
;             PG8_LDB(B0, 1, 0); PG8_LDB(B1, 1, 1); PG8_SCHED; PG8_LDA(At, 1, 0); PG8_STAGE(PG8_SA(0, 1), a2 + hstepA, voffA);
;             PG8_WAIT_V(8); PG8_WAIT_L(0); PG8_BAR; PG8_MMA(0, 0, At, B0); PG8_MMA(0, 1, At, B1); PG8_BAR; PG8_SCHED;
	v_mfma_f32_16x16x32_bf16 v[60:63], v[150:153], v[182:185], v[60:63]
	v_mfma_f32_16x16x32_bf16 v[56:59], v[158:161], v[182:185], v[56:59]
	v_mfma_f32_16x16x32_bf16 v[44:47], v[150:153], v[190:193], v[44:47]
	v_mfma_f32_16x16x32_bf16 v[40:43], v[158:161], v[190:193], v[40:43]
	v_mfma_f32_16x16x32_bf16 v[28:31], v[150:153], v[198:201], v[28:31]
	v_mfma_f32_16x16x32_bf16 v[24:27], v[158:161], v[198:201], v[24:27]
	v_mfma_f32_16x16x32_bf16 v[12:15], v[150:153], v[206:209], v[12:15]
	v_mfma_f32_16x16x32_bf16 v[8:11], v[158:161], v[206:209], v[8:11]
	v_mfma_f32_16x16x32_bf16 v[60:63], v[154:157], v[186:189], v[60:63]
	v_mfma_f32_16x16x32_bf16 v[56:59], v[162:165], v[186:189], v[56:59]
	v_mfma_f32_16x16x32_bf16 v[44:47], v[154:157], v[194:197], v[44:47]
	v_mfma_f32_16x16x32_bf16 v[40:43], v[162:165], v[194:197], v[40:43]
	v_mfma_f32_16x16x32_bf16 v[28:31], v[154:157], v[202:205], v[28:31]
	v_mfma_f32_16x16x32_bf16 v[24:27], v[162:165], v[202:205], v[24:27]
	v_mfma_f32_16x16x32_bf16 v[12:15], v[154:157], v[210:213], v[12:15]
	v_mfma_f32_16x16x32_bf16 v[8:11], v[162:165], v[210:213], v[8:11]
	v_mfma_f32_16x16x32_bf16 v[52:55], v[166:169], v[182:185], v[52:55]
	v_mfma_f32_16x16x32_bf16 v[48:51], v[174:177], v[182:185], v[48:51]
	v_mfma_f32_16x16x32_bf16 v[36:39], v[166:169], v[190:193], v[36:39]
	v_mfma_f32_16x16x32_bf16 v[32:35], v[174:177], v[190:193], v[32:35]
	v_mfma_f32_16x16x32_bf16 v[20:23], v[166:169], v[198:201], v[20:23]
	v_mfma_f32_16x16x32_bf16 v[16:19], v[174:177], v[198:201], v[16:19]
	v_mfma_f32_16x16x32_bf16 v[4:7], v[166:169], v[206:209], v[4:7]
	v_mfma_f32_16x16x32_bf16 v[0:3], v[174:177], v[206:209], v[0:3]
	v_mfma_f32_16x16x32_bf16 v[52:55], v[170:173], v[186:189], v[52:55]
	v_mfma_f32_16x16x32_bf16 v[48:51], v[178:181], v[186:189], v[48:51]
	v_mfma_f32_16x16x32_bf16 v[36:39], v[170:173], v[194:197], v[36:39]
	v_mfma_f32_16x16x32_bf16 v[32:35], v[178:181], v[194:197], v[32:35]
	v_mfma_f32_16x16x32_bf16 v[20:23], v[170:173], v[202:205], v[20:23]
	v_mfma_f32_16x16x32_bf16 v[16:19], v[178:181], v[202:205], v[16:19]
	v_mfma_f32_16x16x32_bf16 v[4:7], v[170:173], v[210:213], v[4:7]
	v_mfma_f32_16x16x32_bf16 v[0:3], v[178:181], v[210:213], v[0:3]
	s_setprio 0
	s_barrier
	s_add_i32 s70, 0, 0x18000
	s_add_i32 s71, 0, 0x1c000
	v_add_u32_e32 v162, s70, v145
	v_add_u32_e32 v178, s71, v145
	ds_read_b128 v[150:153], v162
	ds_read_b128 v[154:157], v162 offset:1024
	ds_read_b128 v[158:161], v162 offset:2048
	ds_read_b128 v[162:165], v162 offset:3072
	ds_read_b128 v[166:169], v178
	ds_read_b128 v[170:173], v178 offset:1024
	ds_read_b128 v[174:177], v178 offset:2048
	ds_read_b128 v[178:181], v178 offset:3072
	s_add_u32 s46, s46, 0x80000
	s_addc_u32 s47, s47, 0
	s_mov_b32 m0, s54
	v_lshl_add_u64 v[222:223], s[46:47], 0, v[134:135]
	ds_read_b128 v[182:185], v149 offset:32768
	ds_read_b128 v[186:189], v149 offset:33792
	ds_read_b128 v[190:193], v149 offset:34816
	ds_read_b128 v[194:197], v149 offset:35840
	ds_read_b128 v[198:201], v149 offset:36864
	ds_read_b128 v[202:205], v149 offset:37888
	ds_read_b128 v[206:209], v149 offset:38912
	ds_read_b128 v[210:213], v149 offset:39936
	global_load_lds_dwordx4 v[222:223], off
	v_lshl_add_u64 v[222:223], s[46:47], 0, v[132:133]
	s_mov_b32 m0, s55
	s_nop 0
	global_load_lds_dwordx4 v[222:223], off
	s_waitcnt vmcnt(8)
	s_waitcnt lgkmcnt(0)
	s_setprio 1
	s_barrier
	v_mfma_f32_16x16x32_bf16 v[124:127], v[150:153], v[182:185], v[124:127]
	v_mfma_f32_16x16x32_bf16 v[120:123], v[158:161], v[182:185], v[120:123]
	v_mfma_f32_16x16x32_bf16 v[108:111], v[150:153], v[190:193], v[108:111]
	v_mfma_f32_16x16x32_bf16 v[104:107], v[158:161], v[190:193], v[104:107]
	v_mfma_f32_16x16x32_bf16 v[92:95], v[150:153], v[198:201], v[92:95]
	v_mfma_f32_16x16x32_bf16 v[88:91], v[158:161], v[198:201], v[88:91]
	v_mfma_f32_16x16x32_bf16 v[76:79], v[150:153], v[206:209], v[76:79]
	v_mfma_f32_16x16x32_bf16 v[72:75], v[158:161], v[206:209], v[72:75]
	v_mfma_f32_16x16x32_bf16 v[124:127], v[154:157], v[186:189], v[124:127]
	v_mfma_f32_16x16x32_bf16 v[120:123], v[162:165], v[186:189], v[120:123]
	v_mfma_f32_16x16x32_bf16 v[108:111], v[154:157], v[194:197], v[108:111]
	v_mfma_f32_16x16x32_bf16 v[104:107], v[162:165], v[194:197], v[104:107]
	v_mfma_f32_16x16x32_bf16 v[92:95], v[154:157], v[202:205], v[92:95]
	v_mfma_f32_16x16x32_bf16 v[88:91], v[162:165], v[202:205], v[88:91]
	v_mfma_f32_16x16x32_bf16 v[76:79], v[154:157], v[210:213], v[76:79]
	v_mfma_f32_16x16x32_bf16 v[72:75], v[162:165], v[210:213], v[72:75]
	v_mfma_f32_16x16x32_bf16 v[116:119], v[166:169], v[182:185], v[116:119]
	v_mfma_f32_16x16x32_bf16 v[112:115], v[174:177], v[182:185], v[112:115]
	v_mfma_f32_16x16x32_bf16 v[100:103], v[166:169], v[190:193], v[100:103]
	v_mfma_f32_16x16x32_bf16 v[96:99], v[174:177], v[190:193], v[96:99]
	v_mfma_f32_16x16x32_bf16 v[84:87], v[166:169], v[198:201], v[84:87]
	v_mfma_f32_16x16x32_bf16 v[80:83], v[174:177], v[198:201], v[80:83]
	v_mfma_f32_16x16x32_bf16 v[68:71], v[166:169], v[206:209], v[68:71]
	v_mfma_f32_16x16x32_bf16 v[64:67], v[174:177], v[206:209], v[64:67]
	v_mfma_f32_16x16x32_bf16 v[116:119], v[170:173], v[186:189], v[116:119]
	v_mfma_f32_16x16x32_bf16 v[112:115], v[178:181], v[186:189], v[112:115]
	v_mfma_f32_16x16x32_bf16 v[100:103], v[170:173], v[194:197], v[100:103]
	v_mfma_f32_16x16x32_bf16 v[96:99], v[178:181], v[194:197], v[96:99]
	v_mfma_f32_16x16x32_bf16 v[84:87], v[170:173], v[202:205], v[84:87]
	v_mfma_f32_16x16x32_bf16 v[80:83], v[178:181], v[202:205], v[80:83]
	v_mfma_f32_16x16x32_bf16 v[68:71], v[170:173], v[210:213], v[68:71]
	v_mfma_f32_16x16x32_bf16 v[64:67], v[178:181], v[210:213], v[64:67]
	s_setprio 0
	s_barrier
; #define PG8_STAGE(bufoff, gbase, voff) do { _Pragma("unroll") for (int _i = 0; _i < 2; ++_i) \
;         __builtin_amdgcn_global_load_lds((const unsigned*)((const char*)(gbase) + (voff)[_i]), (LAS unsigned*)(lds + (bufoff) + ldsw + _i * 8192), 16, 0, 0); } while (0)
; #define PG8_LDA(dst, b, h) do { _Pragma("unroll") for (int m = 0; m < 4; ++m) _Pragma("unroll") for (int k = 0; k < 2; ++k) dst[m][k] = *(const LAS bf16x8*)(lds + PG8_SA(b, h) + aoff + m * 2048 + k * 1024); } while (0)
; #define PG8_WAIT_V(n) asm volatile("s_waitcnt vmcnt(" #n ")" ::: "memory")
; #define PG8_WAIT_L(n) asm volatile("s_waitcnt lgkmcnt(" #n ")" ::: "memory")
; #define PG8_BAR __builtin_amdgcn_s_barrier()
; #define PG8_SCHED __builtin_amdgcn_sched_barrier(0)
; template <class Epi, bool FP8 = false>
; __device__ __forceinline__ void gemm_phase(LAS unsigned char* lds, const Gemm g, const StaticOrder& S_, const Epi& E, const int tid) {
;     ...
;             PG8_LDA(At, 1, 1); PG8_STAGE(PG8_SB(1, 0), b3, voffB); PG8_STAGE(PG8_SB(1, 1), b3 + hstepB, voffB); PG8_STAGE(PG8_SA(1, 0), a3, voffA);
;             PG8_WAIT_V(8); PG8_WAIT_L(0); PG8_BAR; PG8_MMA(1, 0, At, B0); PG8_MMA(1, 1, At, B1); PG8_BAR; PG8_SCHED;
;         }
;         if (wr == 0) PG8_BAR;
	s_add_i32 s46, s70, s50
	v_lshl_add_u64 v[214:215], v[214:215], 0, s[16:17]
	s_mov_b32 m0, s46
	ds_read_b128 v[182:185], v149 offset:49152
	ds_read_b128 v[186:189], v149 offset:50176
	ds_read_b128 v[190:193], v149 offset:51200
	ds_read_b128 v[194:197], v149 offset:52224
	ds_read_b128 v[198:201], v149 offset:53248
	ds_read_b128 v[202:205], v149 offset:54272
	ds_read_b128 v[206:209], v149 offset:55296
	ds_read_b128 v[210:213], v149 offset:56320
	global_load_lds_dwordx4 v[214:215], off
	s_add_i32 m0, s46, 0x2000
	s_add_u32 s42, s42, 0x80080
	v_lshl_add_u64 v[214:215], v[216:217], 0, s[16:17]
	s_addc_u32 s43, s43, 0
	s_add_i32 s46, s71, s50
	global_load_lds_dwordx4 v[214:215], off
	v_lshl_add_u64 v[214:215], s[42:43], 0, v[128:129]
	s_mov_b32 m0, s46
	s_nop 0
	global_load_lds_dwordx4 v[214:215], off
	v_lshl_add_u64 v[214:215], s[42:43], 0, v[130:131]
	s_add_i32 m0, s46, 0x2000
	s_nop 0
	global_load_lds_dwordx4 v[214:215], off
	v_lshl_add_u64 v[214:215], v[218:219], 0, s[16:17]
	s_mov_b32 m0, s57
	s_nop 0
	global_load_lds_dwordx4 v[214:215], off
	v_lshl_add_u64 v[214:215], v[220:221], 0, s[16:17]
	s_mov_b32 m0, s58
	s_nop 0
	global_load_lds_dwordx4 v[214:215], off
	s_waitcnt vmcnt(8)
	s_waitcnt lgkmcnt(0)
	s_setprio 1
	s_barrier
	v_mfma_f32_16x16x32_bf16 v[60:63], v[150:153], v[182:185], v[60:63]
	v_mfma_f32_16x16x32_bf16 v[56:59], v[158:161], v[182:185], v[56:59]
	v_mfma_f32_16x16x32_bf16 v[44:47], v[150:153], v[190:193], v[44:47]
	v_mfma_f32_16x16x32_bf16 v[40:43], v[158:161], v[190:193], v[40:43]
	v_mfma_f32_16x16x32_bf16 v[28:31], v[150:153], v[198:201], v[28:31]
	v_mfma_f32_16x16x32_bf16 v[24:27], v[158:161], v[198:201], v[24:27]
	v_mfma_f32_16x16x32_bf16 v[12:15], v[150:153], v[206:209], v[12:15]
	v_mfma_f32_16x16x32_bf16 v[8:11], v[158:161], v[206:209], v[8:11]
	v_mfma_f32_16x16x32_bf16 v[60:63], v[154:157], v[186:189], v[60:63]
	v_mfma_f32_16x16x32_bf16 v[56:59], v[162:165], v[186:189], v[56:59]
	v_mfma_f32_16x16x32_bf16 v[44:47], v[154:157], v[194:197], v[44:47]
	v_mfma_f32_16x16x32_bf16 v[40:43], v[162:165], v[194:197], v[40:43]
	v_mfma_f32_16x16x32_bf16 v[28:31], v[154:157], v[202:205], v[28:31]
	v_mfma_f32_16x16x32_bf16 v[24:27], v[162:165], v[202:205], v[24:27]
	v_mfma_f32_16x16x32_bf16 v[12:15], v[154:157], v[210:213], v[12:15]
	v_mfma_f32_16x16x32_bf16 v[8:11], v[162:165], v[210:213], v[8:11]
	v_mfma_f32_16x16x32_bf16 v[52:55], v[166:169], v[182:185], v[52:55]
	v_mfma_f32_16x16x32_bf16 v[48:51], v[174:177], v[182:185], v[48:51]
	v_mfma_f32_16x16x32_bf16 v[36:39], v[166:169], v[190:193], v[36:39]
	v_mfma_f32_16x16x32_bf16 v[32:35], v[174:177], v[190:193], v[32:35]
	v_mfma_f32_16x16x32_bf16 v[20:23], v[166:169], v[198:201], v[20:23]
	v_mfma_f32_16x16x32_bf16 v[16:19], v[174:177], v[198:201], v[16:19]
	v_mfma_f32_16x16x32_bf16 v[4:7], v[166:169], v[206:209], v[4:7]
	v_mfma_f32_16x16x32_bf16 v[0:3], v[174:177], v[206:209], v[0:3]
	v_mfma_f32_16x16x32_bf16 v[52:55], v[170:173], v[186:189], v[52:55]
	v_mfma_f32_16x16x32_bf16 v[48:51], v[178:181], v[186:189], v[48:51]
	v_mfma_f32_16x16x32_bf16 v[36:39], v[170:173], v[194:197], v[36:39]
	v_mfma_f32_16x16x32_bf16 v[32:35], v[178:181], v[194:197], v[32:35]
	v_mfma_f32_16x16x32_bf16 v[20:23], v[170:173], v[202:205], v[20:23]
	v_mfma_f32_16x16x32_bf16 v[16:19], v[178:181], v[202:205], v[16:19]
	v_mfma_f32_16x16x32_bf16 v[4:7], v[170:173], v[210:213], v[4:7]
	v_mfma_f32_16x16x32_bf16 v[0:3], v[178:181], v[210:213], v[0:3]
	s_setprio 0
	s_barrier
	s_add_i32 s69, s69, 2
	s_add_u32 s30, s30, 0x100
	s_addc_u32 s31, s31, 0
	s_add_u32 s67, s67, 0x100
	s_addc_u32 s68, s68, 0
	s_cmp_gt_u32 s69, 29
	s_cbranch_scc0 .LBB0_1340
	s_and_b64 vcc, exec, s[18:19]
	s_cbranch_vccz .LBB0_1343
	s_barrier

; #define PG8_STAGE(bufoff, gbase, voff) do { _Pragma("unroll") for (int _i = 0; _i < 2; ++_i) \
;         __builtin_amdgcn_global_load_lds((const unsigned*)((const char*)(gbase) + (voff)[_i]), (LAS unsigned*)(lds + (bufoff) + ldsw + _i * 8192), 16, 0, 0); } while (0)
; #define PG8_LDA(dst, b, h) do { _Pragma("unroll") for (int m = 0; m < 4; ++m) _Pragma("unroll") for (int k = 0; k < 2; ++k) dst[m][k] = *(const LAS bf16x8*)(lds + PG8_SA(b, h) + aoff + m * 2048 + k * 1024); } while (0)
; #define PG8_LDB(dst, b, h) do { _Pragma("unroll") for (int n = 0; n < 2; ++n) _Pragma("unroll") for (int k = 0; k < 2; ++k) dst[n][k] = *(const LAS bf16x8*)(lds + PG8_SB(b, h) + boff + n * 2048 + k * 1024); } while (0)
; #define PG8_WAIT_V(n) asm volatile("s_waitcnt vmcnt(" #n ")" ::: "memory")
; #define PG8_WAIT_L(n) asm volatile("s_waitcnt lgkmcnt(" #n ")" ::: "memory")
; #define PG8_BAR __builtin_amdgcn_s_barrier()
; #define PG8_SCHED __builtin_amdgcn_sched_barrier(0)
; template <class Epi, bool FP8 = false>
; __device__ __forceinline__ void gemm_phase(LAS unsigned char* lds, const Gemm g, const StaticOrder& S_, const Epi& E, const int tid) {
;     ...
;             PG8_LDB(B0, 0, 0); PG8_LDB(B1, 0, 1); PG8_SCHED; PG8_LDA(At, 0, 0); PG8_STAGE(PG8_SA(1, 1), a1 + hstepA, voffA);
;             PG8_WAIT_V(8); PG8_WAIT_L(0); PG8_BAR; PG8_MMA(0, 0, At, B0); PG8_MMA(0, 1, At, B1); PG8_BAR; PG8_SCHED;
;             PG8_LDA(At, 0, 1); PG8_STAGE(PG8_SB(0, 0), b2, voffB); PG8_STAGE(PG8_SB(0, 1), b2 + hstepB, voffB); PG8_STAGE(PG8_SA(0, 0), a2, voffA);
;             PG8_WAIT_V(8); PG8_WAIT_L(0); PG8_BAR; PG8_MMA(1, 0, At, B0); PG8_MMA(1, 1, At, B1); PG8_BAR; PG8_SCHED;
.LBB0_1420:
	ds_read_b128 v[140:143], v152
	ds_read_b128 v[144:147], v152 offset:1024
	ds_read_b128 v[156:159], v152 offset:2048
	ds_read_b128 v[160:163], v152 offset:3072
	ds_read_b128 v[164:167], v153
	ds_read_b128 v[168:171], v153 offset:1024
	ds_read_b128 v[172:175], v153 offset:2048
	ds_read_b128 v[176:179], v153 offset:3072
	s_add_u32 s28, s26, 0x100
	s_addc_u32 s29, s27, 0
	s_cmpk_eq_i32 s66, 0x54
	s_cselect_b32 s43, s7, s29
	s_cselect_b32 s42, s6, s28
	s_cselect_b32 s31, s25, s63
	s_cselect_b32 s30, s24, s62
	v_lshl_add_u64 v[212:213], s[26:27], 0, v[132:133]
	s_add_i32 m0, s49, 0xc000
	ds_read_b128 v[180:183], v154
	ds_read_b128 v[184:187], v154 offset:1024
	ds_read_b128 v[188:191], v154 offset:2048
	ds_read_b128 v[192:195], v154 offset:3072
	ds_read_b128 v[196:199], v154 offset:4096
	ds_read_b128 v[200:203], v154 offset:5120
	ds_read_b128 v[204:207], v154 offset:6144
	ds_read_b128 v[208:211], v154 offset:7168
	global_load_lds_dwordx4 v[212:213], off
	v_lshl_add_u64 v[212:213], s[26:27], 0, v[134:135]
	s_add_i32 m0, s49, 0xe000
	s_nop 0
	global_load_lds_dwordx4 v[212:213], off
	s_waitcnt vmcnt(8)
	s_waitcnt lgkmcnt(0)
	s_setprio 1
	s_barrier
	v_mfma_f32_16x16x32_bf16 v[124:127], v[140:143], v[180:183], v[124:127]
	v_mfma_f32_16x16x32_bf16 v[120:123], v[156:159], v[180:183], v[120:123]
	v_mfma_f32_16x16x32_bf16 v[108:111], v[140:143], v[188:191], v[108:111]
	v_mfma_f32_16x16x32_bf16 v[104:107], v[156:159], v[188:191], v[104:107]
	v_mfma_f32_16x16x32_bf16 v[92:95], v[140:143], v[196:199], v[92:95]
	v_mfma_f32_16x16x32_bf16 v[88:91], v[156:159], v[196:199], v[88:91]
	v_mfma_f32_16x16x32_bf16 v[76:79], v[140:143], v[204:207], v[76:79]
	v_mfma_f32_16x16x32_bf16 v[72:75], v[156:159], v[204:207], v[72:75]
	v_mfma_f32_16x16x32_bf16 v[124:127], v[144:147], v[184:187], v[124:127]
	v_mfma_f32_16x16x32_bf16 v[120:123], v[160:163], v[184:187], v[120:123]
	v_mfma_f32_16x16x32_bf16 v[108:111], v[144:147], v[192:195], v[108:111]
	v_mfma_f32_16x16x32_bf16 v[104:107], v[160:163], v[192:195], v[104:107]
	v_mfma_f32_16x16x32_bf16 v[92:95], v[144:147], v[200:203], v[92:95]
	v_mfma_f32_16x16x32_bf16 v[88:91], v[160:163], v[200:203], v[88:91]
	v_mfma_f32_16x16x32_bf16 v[76:79], v[144:147], v[208:211], v[76:79]
	v_mfma_f32_16x16x32_bf16 v[72:75], v[160:163], v[208:211], v[72:75]
	v_mfma_f32_16x16x32_bf16 v[116:119], v[164:167], v[180:183], v[116:119]
	v_mfma_f32_16x16x32_bf16 v[112:115], v[172:175], v[180:183], v[112:115]
	v_mfma_f32_16x16x32_bf16 v[100:103], v[164:167], v[188:191], v[100:103]
	v_mfma_f32_16x16x32_bf16 v[96:99], v[172:175], v[188:191], v[96:99]
	v_mfma_f32_16x16x32_bf16 v[84:87], v[164:167], v[196:199], v[84:87]
	v_mfma_f32_16x16x32_bf16 v[80:83], v[172:175], v[196:199], v[80:83]
	v_mfma_f32_16x16x32_bf16 v[68:71], v[164:167], v[204:207], v[68:71]
	v_mfma_f32_16x16x32_bf16 v[64:67], v[172:175], v[204:207], v[64:67]
	v_mfma_f32_16x16x32_bf16 v[116:119], v[168:171], v[184:187], v[116:119]
	v_mfma_f32_16x16x32_bf16 v[112:115], v[176:179], v[184:187], v[112:115]
	v_mfma_f32_16x16x32_bf16 v[100:103], v[168:171], v[192:195], v[100:103]
	v_mfma_f32_16x16x32_bf16 v[96:99], v[176:179], v[192:195], v[96:99]
	v_mfma_f32_16x16x32_bf16 v[84:87], v[168:171], v[200:203], v[84:87]
	v_mfma_f32_16x16x32_bf16 v[80:83], v[176:179], v[200:203], v[80:83]
	v_mfma_f32_16x16x32_bf16 v[68:71], v[168:171], v[208:211], v[68:71]
	v_mfma_f32_16x16x32_bf16 v[64:67], v[176:179], v[208:211], v[64:67]
	s_setprio 0
	s_barrier
	s_add_i32 s26, s56, s48
	v_lshl_add_u64 v[212:213], s[30:31], 0, v[128:129]
	s_mov_b32 m0, s26
	ds_read_b128 v[180:183], v154 offset:16384
	ds_read_b128 v[184:187], v154 offset:17408
	ds_read_b128 v[188:191], v154 offset:18432
	ds_read_b128 v[192:195], v154 offset:19456
	ds_read_b128 v[196:199], v154 offset:20480
	ds_read_b128 v[200:203], v154 offset:21504
	ds_read_b128 v[204:207], v154 offset:22528
	ds_read_b128 v[208:211], v154 offset:23552
	global_load_lds_dwordx4 v[212:213], off
	s_add_i32 m0, s26, 0x2000
	s_add_u32 s26, s30, 0x160000
	v_lshl_add_u64 v[214:215], s[30:31], 0, v[130:131]
	s_addc_u32 s27, s31, 0
	s_add_i32 s67, s57, s48
	global_load_lds_dwordx4 v[214:215], off
	v_lshl_add_u64 v[216:217], s[26:27], 0, v[128:129]
	s_mov_b32 m0, s67
	v_lshl_add_u64 v[218:219], s[42:43], 0, v[130:131]
	global_load_lds_dwordx4 v[216:217], off
	v_lshl_add_u64 v[216:217], s[26:27], 0, v[130:131]
	s_add_i32 m0, s67, 0x2000
	s_nop 0
	global_load_lds_dwordx4 v[216:217], off
	v_lshl_add_u64 v[216:217], s[42:43], 0, v[128:129]
	s_mov_b32 m0, s49
	s_nop 0
	global_load_lds_dwordx4 v[216:217], off
	s_mov_b32 m0, s50
	s_nop 0
	global_load_lds_dwordx4 v[218:219], off
	s_waitcnt vmcnt(8)
	s_waitcnt lgkmcnt(0)
	s_setprio 1
	s_barrier
; #define PG8_STAGE(bufoff, gbase, voff) do { _Pragma("unroll") for (int _i = 0; _i < 2; ++_i) \
;         __builtin_amdgcn_global_load_lds((const unsigned*)((const char*)(gbase) + (voff)[_i]), (LAS unsigned*)(lds + (bufoff) + ldsw + _i * 8192), 16, 0, 0); } while (0)
; #define PG8_LDA(dst, b, h) do { _Pragma("unroll") for (int m = 0; m < 4; ++m) _Pragma("unroll") for (int k = 0; k < 2; ++k) dst[m][k] = *(const LAS bf16x8*)(lds + PG8_SA(b, h) + aoff + m * 2048 + k * 1024); } while (0)
; #define PG8_LDB(dst, b, h) do { _Pragma("unroll") for (int n = 0; n < 2; ++n) _Pragma("unroll") for (int k = 0; k < 2; ++k) dst[n][k] = *(const LAS bf16x8*)(lds + PG8_SB(b, h) + boff + n * 2048 + k * 1024); } while (0)
; #define PG8_WAIT_V(n) asm volatile("s_waitcnt vmcnt(" #n ")" ::: "memory")
; #define PG8_WAIT_L(n) asm volatile("s_waitcnt lgkmcnt(" #n ")" ::: "memory")
; #define PG8_BAR __builtin_amdgcn_s_barrier()
; #define PG8_SCHED __builtin_amdgcn_sched_barrier(0)
; template <class Epi, bool FP8 = false>
; __device__ __forceinline__ void gemm_phase(LAS unsigned char* lds, const Gemm g, const StaticOrder& S_, const Epi& E, const int tid) {
;     ...
;             PG8_WAIT_V(8); PG8_WAIT_L(0); PG8_BAR; PG8_MMA(1, 0, At, B0); PG8_MMA(1, 1, At, B1); PG8_BAR; PG8_SCHED;
;             PG8_LDB(B0, 1, 0); PG8_LDB(B1, 1, 1); PG8_SCHED; PG8_LDA(At, 1, 0); PG8_STAGE(PG8_SA(0, 1), a2 + hstepA, voffA);
;             PG8_WAIT_V(8); PG8_WAIT_L(0); PG8_BAR; PG8_MMA(0, 0, At, B0); PG8_MMA(0, 1, At, B1); PG8_BAR; PG8_SCHED;
	v_mfma_f32_16x16x32_bf16 v[60:63], v[140:143], v[180:183], v[60:63]
	v_mfma_f32_16x16x32_bf16 v[56:59], v[156:159], v[180:183], v[56:59]
	v_mfma_f32_16x16x32_bf16 v[44:47], v[140:143], v[188:191], v[44:47]
	v_mfma_f32_16x16x32_bf16 v[40:43], v[156:159], v[188:191], v[40:43]
	v_mfma_f32_16x16x32_bf16 v[28:31], v[140:143], v[196:199], v[28:31]
	v_mfma_f32_16x16x32_bf16 v[24:27], v[156:159], v[196:199], v[24:27]
	v_mfma_f32_16x16x32_bf16 v[12:15], v[140:143], v[204:207], v[12:15]
	v_mfma_f32_16x16x32_bf16 v[8:11], v[156:159], v[204:207], v[8:11]
	v_mfma_f32_16x16x32_bf16 v[60:63], v[144:147], v[184:187], v[60:63]
	v_mfma_f32_16x16x32_bf16 v[56:59], v[160:163], v[184:187], v[56:59]
	v_mfma_f32_16x16x32_bf16 v[44:47], v[144:147], v[192:195], v[44:47]
	v_mfma_f32_16x16x32_bf16 v[40:43], v[160:163], v[192:195], v[40:43]
	v_mfma_f32_16x16x32_bf16 v[28:31], v[144:147], v[200:203], v[28:31]
	v_mfma_f32_16x16x32_bf16 v[24:27], v[160:163], v[200:203], v[24:27]
	v_mfma_f32_16x16x32_bf16 v[12:15], v[144:147], v[208:211], v[12:15]
	v_mfma_f32_16x16x32_bf16 v[8:11], v[160:163], v[208:211], v[8:11]
	v_mfma_f32_16x16x32_bf16 v[52:55], v[164:167], v[180:183], v[52:55]
	v_mfma_f32_16x16x32_bf16 v[48:51], v[172:175], v[180:183], v[48:51]
	v_mfma_f32_16x16x32_bf16 v[36:39], v[164:167], v[188:191], v[36:39]
	v_mfma_f32_16x16x32_bf16 v[32:35], v[172:175], v[188:191], v[32:35]
	v_mfma_f32_16x16x32_bf16 v[20:23], v[164:167], v[196:199], v[20:23]
	v_mfma_f32_16x16x32_bf16 v[16:19], v[172:175], v[196:199], v[16:19]
	v_mfma_f32_16x16x32_bf16 v[4:7], v[164:167], v[204:207], v[4:7]
	v_mfma_f32_16x16x32_bf16 v[0:3], v[172:175], v[204:207], v[0:3]
	v_mfma_f32_16x16x32_bf16 v[52:55], v[168:171], v[184:187], v[52:55]
	v_mfma_f32_16x16x32_bf16 v[48:51], v[176:179], v[184:187], v[48:51]
	v_mfma_f32_16x16x32_bf16 v[36:39], v[168:171], v[192:195], v[36:39]
	v_mfma_f32_16x16x32_bf16 v[32:35], v[176:179], v[192:195], v[32:35]
	v_mfma_f32_16x16x32_bf16 v[20:23], v[168:171], v[200:203], v[20:23]
	v_mfma_f32_16x16x32_bf16 v[16:19], v[176:179], v[200:203], v[16:19]
	v_mfma_f32_16x16x32_bf16 v[4:7], v[168:171], v[208:211], v[4:7]
	v_mfma_f32_16x16x32_bf16 v[0:3], v[176:179], v[208:211], v[0:3]
	s_setprio 0
	s_barrier
	s_add_i32 s67, 0, 0x18000
	v_add_u32_e32 v155, s67, v150
	s_add_i32 s68, 0, 0x1c000
	ds_read_b128 v[140:143], v155
	ds_read_b128 v[144:147], v155 offset:1024
	ds_read_b128 v[156:159], v155 offset:2048
	ds_read_b128 v[160:163], v155 offset:3072
	v_add_u32_e32 v155, s68, v150
	ds_read_b128 v[164:167], v155
	ds_read_b128 v[168:171], v155 offset:1024
	ds_read_b128 v[172:175], v155 offset:2048
	ds_read_b128 v[176:179], v155 offset:3072
	s_add_u32 s26, s42, 0x160000
	s_addc_u32 s27, s43, 0
	s_mov_b32 m0, s51
	v_lshl_add_u64 v[220:221], s[26:27], 0, v[128:129]
	ds_read_b128 v[180:183], v154 offset:32768
	ds_read_b128 v[184:187], v154 offset:33792
	ds_read_b128 v[188:191], v154 offset:34816
	ds_read_b128 v[192:195], v154 offset:35840
	ds_read_b128 v[196:199], v154 offset:36864
	ds_read_b128 v[200:203], v154 offset:37888
	ds_read_b128 v[204:207], v154 offset:38912
	ds_read_b128 v[208:211], v154 offset:39936
	global_load_lds_dwordx4 v[220:221], off
	v_lshl_add_u64 v[220:221], s[26:27], 0, v[130:131]
	s_mov_b32 m0, s52
	s_nop 0
	global_load_lds_dwordx4 v[220:221], off
	s_waitcnt vmcnt(8)
	s_waitcnt lgkmcnt(0)
	s_setprio 1
	s_barrier
	v_mfma_f32_16x16x32_bf16 v[124:127], v[140:143], v[180:183], v[124:127]
	v_mfma_f32_16x16x32_bf16 v[120:123], v[156:159], v[180:183], v[120:123]
	v_mfma_f32_16x16x32_bf16 v[108:111], v[140:143], v[188:191], v[108:111]
	v_mfma_f32_16x16x32_bf16 v[104:107], v[156:159], v[188:191], v[104:107]
	v_mfma_f32_16x16x32_bf16 v[92:95], v[140:143], v[196:199], v[92:95]
	v_mfma_f32_16x16x32_bf16 v[88:91], v[156:159], v[196:199], v[88:91]
	v_mfma_f32_16x16x32_bf16 v[76:79], v[140:143], v[204:207], v[76:79]
	v_mfma_f32_16x16x32_bf16 v[72:75], v[156:159], v[204:207], v[72:75]
	v_mfma_f32_16x16x32_bf16 v[124:127], v[144:147], v[184:187], v[124:127]
	v_mfma_f32_16x16x32_bf16 v[120:123], v[160:163], v[184:187], v[120:123]
	v_mfma_f32_16x16x32_bf16 v[108:111], v[144:147], v[192:195], v[108:111]
	v_mfma_f32_16x16x32_bf16 v[104:107], v[160:163], v[192:195], v[104:107]
	v_mfma_f32_16x16x32_bf16 v[92:95], v[144:147], v[200:203], v[92:95]
	v_mfma_f32_16x16x32_bf16 v[88:91], v[160:163], v[200:203], v[88:91]
	v_mfma_f32_16x16x32_bf16 v[76:79], v[144:147], v[208:211], v[76:79]
	v_mfma_f32_16x16x32_bf16 v[72:75], v[160:163], v[208:211], v[72:75]
	v_mfma_f32_16x16x32_bf16 v[116:119], v[164:167], v[180:183], v[116:119]
	v_mfma_f32_16x16x32_bf16 v[112:115], v[172:175], v[180:183], v[112:115]
	v_mfma_f32_16x16x32_bf16 v[100:103], v[164:167], v[188:191], v[100:103]
	v_mfma_f32_16x16x32_bf16 v[96:99], v[172:175], v[188:191], v[96:99]
	v_mfma_f32_16x16x32_bf16 v[84:87], v[164:167], v[196:199], v[84:87]
	v_mfma_f32_16x16x32_bf16 v[80:83], v[172:175], v[196:199], v[80:83]
	v_mfma_f32_16x16x32_bf16 v[68:71], v[164:167], v[204:207], v[68:71]
	v_mfma_f32_16x16x32_bf16 v[64:67], v[172:175], v[204:207], v[64:67]
	v_mfma_f32_16x16x32_bf16 v[116:119], v[168:171], v[184:187], v[116:119]
	v_mfma_f32_16x16x32_bf16 v[112:115], v[176:179], v[184:187], v[112:115]
	v_mfma_f32_16x16x32_bf16 v[100:103], v[168:171], v[192:195], v[100:103]
	v_mfma_f32_16x16x32_bf16 v[96:99], v[176:179], v[192:195], v[96:99]
	v_mfma_f32_16x16x32_bf16 v[84:87], v[168:171], v[200:203], v[84:87]
	v_mfma_f32_16x16x32_bf16 v[80:83], v[176:179], v[200:203], v[80:83]
	v_mfma_f32_16x16x32_bf16 v[68:71], v[168:171], v[208:211], v[68:71]
	v_mfma_f32_16x16x32_bf16 v[64:67], v[176:179], v[208:211], v[64:67]
	s_setprio 0
	s_barrier
; #define PG8_STAGE(bufoff, gbase, voff) do { _Pragma("unroll") for (int _i = 0; _i < 2; ++_i) \
;         __builtin_amdgcn_global_load_lds((const unsigned*)((const char*)(gbase) + (voff)[_i]), (LAS unsigned*)(lds + (bufoff) + ldsw + _i * 8192), 16, 0, 0); } while (0)
; #define PG8_LDA(dst, b, h) do { _Pragma("unroll") for (int m = 0; m < 4; ++m) _Pragma("unroll") for (int k = 0; k < 2; ++k) dst[m][k] = *(const LAS bf16x8*)(lds + PG8_SA(b, h) + aoff + m * 2048 + k * 1024); } while (0)
; #define PG8_WAIT_V(n) asm volatile("s_waitcnt vmcnt(" #n ")" ::: "memory")
; #define PG8_WAIT_L(n) asm volatile("s_waitcnt lgkmcnt(" #n ")" ::: "memory")
; #define PG8_BAR __builtin_amdgcn_s_barrier()
; #define PG8_SCHED __builtin_amdgcn_sched_barrier(0)
; template <class Epi, bool FP8 = false>
; __device__ __forceinline__ void gemm_phase(LAS unsigned char* lds, const Gemm g, const StaticOrder& S_, const Epi& E, const int tid) {
;     ...
;             PG8_LDA(At, 1, 1); PG8_STAGE(PG8_SB(1, 0), b3, voffB); PG8_STAGE(PG8_SB(1, 1), b3 + hstepB, voffB); PG8_STAGE(PG8_SA(1, 0), a3, voffA);
;             PG8_WAIT_V(8); PG8_WAIT_L(0); PG8_BAR; PG8_MMA(1, 0, At, B0); PG8_MMA(1, 1, At, B1); PG8_BAR; PG8_SCHED;
;         }
;         if (wr == 0) PG8_BAR;
	s_add_i32 s26, s67, s48
	v_lshl_add_u64 v[212:213], v[212:213], 0, s[18:19]
	s_mov_b32 m0, s26
	ds_read_b128 v[180:183], v154 offset:49152
	ds_read_b128 v[184:187], v154 offset:50176
	ds_read_b128 v[188:191], v154 offset:51200
	ds_read_b128 v[192:195], v154 offset:52224
	ds_read_b128 v[196:199], v154 offset:53248
	ds_read_b128 v[200:203], v154 offset:54272
	ds_read_b128 v[204:207], v154 offset:55296
	ds_read_b128 v[208:211], v154 offset:56320
	global_load_lds_dwordx4 v[212:213], off
	s_add_i32 m0, s26, 0x2000
	s_add_u32 s26, s30, 0x160080
	v_lshl_add_u64 v[212:213], v[214:215], 0, s[18:19]
	s_addc_u32 s27, s31, 0
	s_add_i32 s30, s68, s48
	global_load_lds_dwordx4 v[212:213], off
	v_lshl_add_u64 v[212:213], s[26:27], 0, v[128:129]
	s_mov_b32 m0, s30
	s_nop 0
	global_load_lds_dwordx4 v[212:213], off
	v_lshl_add_u64 v[212:213], s[26:27], 0, v[130:131]
	s_add_i32 m0, s30, 0x2000
	s_nop 0
	global_load_lds_dwordx4 v[212:213], off
	v_lshl_add_u64 v[212:213], v[216:217], 0, s[18:19]
	s_mov_b32 m0, s54
	s_nop 0
	global_load_lds_dwordx4 v[212:213], off
	v_lshl_add_u64 v[212:213], v[218:219], 0, s[18:19]
	s_mov_b32 m0, s55
	s_nop 0
	global_load_lds_dwordx4 v[212:213], off
	s_waitcnt vmcnt(8)
	s_waitcnt lgkmcnt(0)
	s_setprio 1
	s_barrier
	v_mfma_f32_16x16x32_bf16 v[60:63], v[140:143], v[180:183], v[60:63]
	v_mfma_f32_16x16x32_bf16 v[56:59], v[156:159], v[180:183], v[56:59]
	v_mfma_f32_16x16x32_bf16 v[44:47], v[140:143], v[188:191], v[44:47]
	v_mfma_f32_16x16x32_bf16 v[40:43], v[156:159], v[188:191], v[40:43]
	v_mfma_f32_16x16x32_bf16 v[28:31], v[140:143], v[196:199], v[28:31]
	v_mfma_f32_16x16x32_bf16 v[24:27], v[156:159], v[196:199], v[24:27]
	v_mfma_f32_16x16x32_bf16 v[12:15], v[140:143], v[204:207], v[12:15]
	v_mfma_f32_16x16x32_bf16 v[8:11], v[156:159], v[204:207], v[8:11]
	v_mfma_f32_16x16x32_bf16 v[60:63], v[144:147], v[184:187], v[60:63]
	v_mfma_f32_16x16x32_bf16 v[56:59], v[160:163], v[184:187], v[56:59]
	v_mfma_f32_16x16x32_bf16 v[44:47], v[144:147], v[192:195], v[44:47]
	v_mfma_f32_16x16x32_bf16 v[40:43], v[160:163], v[192:195], v[40:43]
	v_mfma_f32_16x16x32_bf16 v[28:31], v[144:147], v[200:203], v[28:31]
	v_mfma_f32_16x16x32_bf16 v[24:27], v[160:163], v[200:203], v[24:27]
	v_mfma_f32_16x16x32_bf16 v[12:15], v[144:147], v[208:211], v[12:15]
	v_mfma_f32_16x16x32_bf16 v[8:11], v[160:163], v[208:211], v[8:11]
	v_mfma_f32_16x16x32_bf16 v[52:55], v[164:167], v[180:183], v[52:55]
	v_mfma_f32_16x16x32_bf16 v[48:51], v[172:175], v[180:183], v[48:51]
	v_mfma_f32_16x16x32_bf16 v[36:39], v[164:167], v[188:191], v[36:39]
	v_mfma_f32_16x16x32_bf16 v[32:35], v[172:175], v[188:191], v[32:35]
	v_mfma_f32_16x16x32_bf16 v[20:23], v[164:167], v[196:199], v[20:23]
	v_mfma_f32_16x16x32_bf16 v[16:19], v[172:175], v[196:199], v[16:19]
	v_mfma_f32_16x16x32_bf16 v[4:7], v[164:167], v[204:207], v[4:7]
	v_mfma_f32_16x16x32_bf16 v[0:3], v[172:175], v[204:207], v[0:3]
	v_mfma_f32_16x16x32_bf16 v[52:55], v[168:171], v[184:187], v[52:55]
	v_mfma_f32_16x16x32_bf16 v[48:51], v[176:179], v[184:187], v[48:51]
	v_mfma_f32_16x16x32_bf16 v[36:39], v[168:171], v[192:195], v[36:39]
	v_mfma_f32_16x16x32_bf16 v[32:35], v[176:179], v[192:195], v[32:35]
	v_mfma_f32_16x16x32_bf16 v[20:23], v[168:171], v[200:203], v[20:23]
	v_mfma_f32_16x16x32_bf16 v[16:19], v[176:179], v[200:203], v[16:19]
	v_mfma_f32_16x16x32_bf16 v[4:7], v[168:171], v[208:211], v[4:7]
	v_mfma_f32_16x16x32_bf16 v[0:3], v[176:179], v[208:211], v[0:3]
	s_setprio 0
	s_barrier
	s_add_i32 s66, s66, 2
	s_add_u32 s62, s62, 0x100
	s_addc_u32 s63, s63, 0
	s_cmpk_gt_u32 s66, 0x55
	s_mov_b64 s[26:27], s[28:29]
	s_cbranch_scc0 .LBB0_1420
	s_and_b64 vcc, exec, s[20:21]
	s_cbranch_vccz .LBB0_1423
	s_barrier
